# gatenorm phase re-partitioned: sample-out GEMM units as 128 quadrant workgroups that first take 2 gatenorm rows per wave; other 128 workgroups take 6 rows per wave
# speedup vs baseline: 1.1234x; 1.0187x over previous
.LBB0_1137:
	s_andn2_b64 vcc, exec, s[0:1]
	s_cbranch_vccnz .LBB0_1205
	v_readlane_b32 s3, v246, 0
	s_cmp_gt_i32 s3, 31
	s_mov_b64 s[0:1], -1
	v_mov_b32_e32 v1, v180
	s_lshl_b32 s0, s3, 3
	s_movk_i32 s69, 0x3ff
	s_cmp_gt_u32 s3, 127
	s_cselect_b32 s64, 0x400, 0
	s_cselect_b32 s65, 0, 0xfffffc00
	s_cselect_b32 s69, 0x1bff, s69
	s_add_i32 s1, s0, s64
	v_ashrrev_i32_e32 v2, 6, v1
	v_add_u32_e32 v0, s1, v2
	v_cmp_gt_i32_e32 vcc, s87, v0
	s_and_saveexec_b64 s[8:9], vcc
	s_mov_b32 s15, 0xe900000
	s_mov_b32 s20, 0x10d03000
	s_mov_b32 s34, 0x358637bd
	s_mov_b32 s36, 0x3b800000
	s_brev_b32 s40, 60
	s_cbranch_execz .LBB0_1142
	v_and_b32_e32 v4, 64, v182
	v_xor_b32_e32 v3, 1, v182
	v_add_u32_e32 v4, 64, v4
	v_cmp_lt_i32_e32 vcc, v3, v4
	s_lshl_b64 s[6:7], s[24:25], 2
	s_add_u32 s6, s2, s6
	v_cndmask_b32_e32 v3, v182, v3, vcc
	v_lshlrev_b32_e32 v88, 2, v3
	v_xor_b32_e32 v3, 2, v182
	v_cmp_lt_i32_e32 vcc, v3, v4
	s_addc_u32 s7, s4, s7
	v_add_u32_e32 v2, s0, v2
	v_cndmask_b32_e32 v3, v182, v3, vcc
	v_lshlrev_b32_e32 v89, 2, v3
	v_xor_b32_e32 v3, 4, v182
	v_cmp_lt_i32_e32 vcc, v3, v4
	v_add_u32_e32 v93, s65, v2
	s_mov_b64 s[12:13], 0
	v_cndmask_b32_e32 v3, v182, v3, vcc
	v_lshlrev_b32_e32 v90, 2, v3
	v_xor_b32_e32 v3, 8, v182
	v_cmp_lt_i32_e32 vcc, v3, v4
	s_nop 1
	v_cndmask_b32_e32 v3, v182, v3, vcc
	v_lshlrev_b32_e32 v91, 2, v3
	v_xor_b32_e32 v3, 16, v182
	v_cmp_lt_i32_e32 vcc, v3, v4
	s_nop 1
	v_cndmask_b32_e32 v3, v182, v3, vcc
	v_lshlrev_b32_e32 v92, 2, v3
	v_lshlrev_b32_e32 v3, 5, v1
	v_and_b32_e32 v144, 0x1e0, v3
	v_lshl_add_u64 v[8:9], s[6:7], 0, v[144:145]
	s_lshl_b64 s[6:7], s[38:39], 2
	s_add_u32 s4, s5, s6
	s_addc_u32 s5, s14, s7
	v_and_b32_e32 v144, 0x3e0, v3
	v_and_b32_e32 v1, 63, v1
	v_lshl_add_u64 v[10:11], s[4:5], 0, v[144:145]
	v_lshlrev_b32_e32 v144, 4, v1
	v_ashrrev_i32_e32 v1, 31, v0
	v_mov_b64_e32 v[2:3], s[26:27]
	v_mad_i64_i32 v[12:13], s[0:1], v0, s86, v[2:3]
	v_lshlrev_b64 v[0:1], 12, v[0:1]
	v_lshl_add_u64 v[14:15], s[26:27], 0, v[0:1]
.LBB0_1141:
	v_lshl_add_u64 v[20:21], v[14:15], 0, v[144:145]
	v_add_co_u32_e32 v16, vcc, 0xc500000, v20
	v_lshl_add_u64 v[18:19], v[12:13], 0, v[144:145]
	s_nop 0
	v_addc_co_u32_e32 v17, vcc, 0, v21, vcc
	flat_load_dwordx4 v[38:41], v[16:17]
	v_add_co_u32_e32 v24, vcc, 0x10d01000, v18
	v_add_u32_e32 v93, 0x400, v93
	s_nop 0
	v_addc_co_u32_e32 v25, vcc, 0, v19, vcc
	flat_load_dwordx4 v[42:45], v[24:25] offset:2080
	flat_load_dwordx4 v[4:7], v[8:9]
	flat_load_dwordx4 v[0:3], v[8:9] offset:16
	flat_load_dwordx4 v[82:85], v[16:17] offset:1024
	flat_load_dwordx4 v[94:97], v[24:25] offset:3104
	s_waitcnt vmcnt(0) lgkmcnt(0)
	v_and_b32_e32 v23, 0xffff0000, v41
	v_lshlrev_b32_e32 v27, 16, v41
	v_mov_b32_e32 v28, v23
	v_mov_b32_e32 v29, v27
	v_lshlrev_b32_e32 v26, 16, v45
	v_pk_mul_f32 v[86:87], v[28:29], v[28:29]
	v_mul_f32_e32 v28, 0xbfb8aa3b, v26
	v_exp_f32_e32 v28, v28
	v_and_b32_e32 v32, 0xffff0000, v44
	v_and_b32_e32 v33, 0xffff0000, v40
	v_lshlrev_b32_e32 v41, 16, v40
	v_add_f32_e32 v28, 1.0, v28
	v_rcp_f32_e32 v30, v28
	v_mul_f32_e32 v28, 0xbfb8aa3b, v32
	v_exp_f32_e32 v28, v28
	v_lshlrev_b32_e32 v40, 16, v44
	v_mov_b32_e32 v29, v41
	v_and_b32_e32 v48, 0xffff0000, v43
	v_add_f32_e32 v28, 1.0, v28
	v_rcp_f32_e32 v36, v28
	v_mov_b32_e32 v28, v33
	v_pk_mul_f32 v[98:99], v[28:29], v[28:29]
	v_mul_f32_e32 v28, 0xbfb8aa3b, v40
	v_exp_f32_e32 v28, v28
	v_and_b32_e32 v49, 0xffff0000, v39
	v_lshlrev_b32_e32 v57, 16, v39
	v_lshlrev_b32_e32 v56, 16, v43
	v_add_f32_e32 v28, 1.0, v28
	v_rcp_f32_e32 v46, v28
	v_mul_f32_e32 v28, 0xbfb8aa3b, v48
	v_exp_f32_e32 v28, v28
	v_mov_b32_e32 v29, v57
	v_and_b32_e32 v70, 0xffff0000, v42
	v_lshlrev_b32_e32 v78, 16, v42
	v_add_f32_e32 v28, 1.0, v28
	v_rcp_f32_e32 v52, v28
	v_mov_b32_e32 v28, v49
	v_pk_mul_f32 v[100:101], v[28:29], v[28:29]
	v_mul_f32_e32 v28, 0xbfb8aa3b, v56
	v_exp_f32_e32 v28, v28
	v_and_b32_e32 v22, 0xffff0000, v45
	v_and_b32_e32 v25, 0xffff0000, v85
	v_lshlrev_b32_e32 v29, 16, v85
	v_add_f32_e32 v28, 1.0, v28
	v_rcp_f32_e32 v68, v28
	v_mul_f32_e32 v28, 0xbfb8aa3b, v70
	v_exp_f32_e32 v28, v28
	v_and_b32_e32 v71, 0xffff0000, v38
	v_lshlrev_b32_e32 v79, 16, v38
	v_mov_b32_e32 v34, v25
	v_add_f32_e32 v28, 1.0, v28
	v_rcp_f32_e32 v74, v28
	v_mul_f32_e32 v28, 0xbfb8aa3b, v78
	v_exp_f32_e32 v28, v28
	v_mov_b32_e32 v35, v29
	v_and_b32_e32 v38, 0xffff0000, v96
	v_pk_mul_f32 v[102:103], v[34:35], v[34:35]
	v_add_f32_e32 v28, 1.0, v28
	v_rcp_f32_e32 v60, v28
	v_mul_f32_e32 v28, 0xbfb8aa3b, v22
	v_exp_f32_e32 v28, v28
	v_and_b32_e32 v55, 0xffff0000, v83
	v_lshlrev_b32_e32 v67, 16, v83
	v_and_b32_e32 v77, 0xffff0000, v82
	v_add_f32_e32 v28, 1.0, v28
	v_rcp_f32_e32 v64, v28
	v_lshlrev_b32_e32 v28, 16, v97
	v_mul_f32_e32 v31, 0xbfb8aa3b, v28
	v_exp_f32_e32 v31, v31
	v_and_b32_e32 v54, 0xffff0000, v95
	v_lshlrev_b32_e32 v66, 16, v95
	v_mov_b32_e32 v62, v55
	v_add_f32_e32 v31, 1.0, v31
	v_rcp_f32_e32 v34, v31
	v_mul_f32_e32 v31, 0xbfb8aa3b, v38
	v_exp_f32_e32 v31, v31
	v_mov_b32_e32 v63, v67
	v_and_b32_e32 v76, 0xffff0000, v94
	v_lshlrev_b32_e32 v83, 16, v82
	v_lshlrev_b32_e32 v82, 16, v94
	v_mov_b32_e32 v94, v77
	v_mov_b32_e32 v95, v71
	v_and_b32_e32 v24, 0xffff0000, v97
	v_and_b32_e32 v39, 0xffff0000, v84
	v_lshlrev_b32_e32 v45, 16, v84
	v_lshlrev_b32_e32 v44, 16, v96
	v_pk_mul_f32 v[96:97], v[62:63], v[62:63]
	v_pk_mul_f32 v[94:95], v[94:95], v[94:95]
	v_mov_b32_e32 v104, v83
	v_mov_b32_e32 v105, v79
	v_mov_b32_e32 v50, v39
	v_mov_b32_e32 v51, v45
	v_pk_fma_f32 v[94:95], v[104:105], v[104:105], v[94:95]
	v_mov_b32_e32 v104, v97
	v_mov_b32_e32 v105, v101
	v_add_f32_e32 v31, 1.0, v31
	v_pk_mul_f32 v[84:85], v[50:51], v[50:51]
	v_pk_add_f32 v[94:95], v[104:105], v[94:95]
	v_mov_b32_e32 v97, v100
	v_rcp_f32_e32 v42, v31
	v_mul_f32_e32 v31, 0xbfb8aa3b, v44
	v_pk_add_f32 v[94:95], v[96:97], v[94:95]
	v_mov_b32_e32 v96, v85
	v_mov_b32_e32 v97, v99
	v_exp_f32_e32 v31, v31
	v_pk_add_f32 v[94:95], v[96:97], v[94:95]
	v_mov_b32_e32 v85, v98
	v_pk_add_f32 v[84:85], v[84:85], v[94:95]
	v_mov_b32_e32 v94, v103
	v_mov_b32_e32 v95, v87
	v_pk_add_f32 v[84:85], v[94:95], v[84:85]
	v_mov_b32_e32 v103, v86
	v_pk_add_f32 v[84:85], v[102:103], v[84:85]
	v_add_f32_e32 v31, 1.0, v31
	ds_bpermute_b32 v87, v88, v85
	ds_bpermute_b32 v86, v88, v84
	v_rcp_f32_e32 v50, v31
	v_mul_f32_e32 v31, 0xbfb8aa3b, v54
	v_exp_f32_e32 v31, v31
	s_waitcnt lgkmcnt(0)
	v_pk_add_f32 v[84:85], v[84:85], v[86:87]
	ds_bpermute_b32 v87, v89, v85
	v_add_f32_e32 v31, 1.0, v31
	ds_bpermute_b32 v86, v89, v84
	v_rcp_f32_e32 v58, v31
	v_mul_f32_e32 v31, 0xbfb8aa3b, v66
	v_exp_f32_e32 v31, v31
	s_waitcnt lgkmcnt(0)
	v_pk_add_f32 v[84:85], v[84:85], v[86:87]
	ds_bpermute_b32 v87, v90, v85
	v_add_f32_e32 v31, 1.0, v31
	ds_bpermute_b32 v86, v90, v84
	v_rcp_f32_e32 v72, v31
	v_mul_f32_e32 v31, 0xbfb8aa3b, v76
	v_exp_f32_e32 v31, v31
	s_waitcnt lgkmcnt(0)
	v_pk_add_f32 v[84:85], v[84:85], v[86:87]
	ds_bpermute_b32 v87, v91, v85
	v_add_f32_e32 v31, 1.0, v31
	ds_bpermute_b32 v86, v91, v84
	v_rcp_f32_e32 v80, v31
	v_mul_f32_e32 v31, 0xbfb8aa3b, v82
	v_exp_f32_e32 v31, v31
	s_waitcnt lgkmcnt(0)
	v_pk_add_f32 v[84:85], v[84:85], v[86:87]
	v_mov_b64_e32 v[86:87], s[34:35]
	v_add_f32_e32 v31, 1.0, v31
	v_pk_fma_f32 v[84:85], v[84:85], s[40:41], v[86:87] op_sel_hi:[1,0,0]
	v_rcp_f32_e32 v62, v31
	v_mul_f32_e32 v31, 0x4b800000, v85
	v_cmp_gt_f32_e64 s[0:1], s80, v85
	v_cmp_gt_f32_e32 vcc, s80, v84
	s_nop 0
	v_cndmask_b32_e64 v31, v85, v31, s[0:1]
	v_rsq_f32_e32 v31, v31
	s_nop 0
	v_mul_f32_e32 v35, 0x45800000, v31
	v_cndmask_b32_e64 v61, v31, v35, s[0:1]
	v_pk_mul_f32 v[78:79], v[60:61], v[78:79]
	v_mov_b32_e32 v75, v61
	v_mul_f32_e32 v4, v4, v79
	v_pk_mul_f32 v[70:71], v[74:75], v[70:71]
	v_mul_f32_e32 v35, v78, v4
	v_mul_f32_e32 v4, v5, v71
	v_mov_b32_e32 v69, v61
	v_mul_f32_e32 v43, v70, v4
	v_pk_mul_f32 v[4:5], v[68:69], v[56:57]
	v_mov_b32_e32 v53, v61
	v_mul_f32_e32 v5, v6, v5
	v_mul_f32_e32 v6, v4, v5
	v_pk_mul_f32 v[4:5], v[52:53], v[48:49]
	v_mov_b32_e32 v47, v61
	v_mul_f32_e32 v5, v7, v5
	v_mul_f32_e32 v7, v4, v5
	v_pk_mul_f32 v[4:5], v[46:47], v[40:41]
	v_mov_b32_e32 v37, v61
	v_mul_f32_e32 v0, v0, v5
	v_mul_f32_e32 v40, v4, v0
	v_pk_mul_f32 v[4:5], v[36:37], v[32:33]
	v_mov_b32_e32 v31, v61
	v_mul_f32_e32 v0, v1, v5
	v_mul_f32_e32 v4, v4, v0
	v_pk_mul_f32 v[0:1], v[30:31], v[26:27]
	v_mov_b32_e32 v65, v61
	v_mul_f32_e32 v1, v2, v1
	v_mul_f32_e32 v5, v0, v1
	v_pk_mul_f32 v[0:1], v[64:65], v[22:23]
	v_add_u32_e32 v2, 0x8000, v35
	v_mul_f32_e32 v1, v3, v1
	v_mul_f32_e32 v0, v0, v1
	v_add_u32_e32 v1, 0x8000, v43
	v_perm_b32 v2, v1, v2, s81
	v_add_u32_e32 v1, 0x8000, v7
	v_add_u32_e32 v3, 0x8000, v6
	v_perm_b32 v3, v1, v3, s81
	v_add_u32_e32 v1, 0x8000, v4
	v_add_u32_e32 v4, 0x8000, v40
	v_perm_b32 v4, v1, v4, s81
	v_add_u32_e32 v0, 0x8000, v0
	v_add_u32_e32 v1, 0x8000, v5
	v_perm_b32 v5, v0, v1, s81
	v_add_co_u32_e64 v0, s[0:1], s15, v20
	v_mul_f32_e32 v6, 0x4b800000, v84
	s_nop 0
	v_addc_co_u32_e64 v1, s[0:1], 0, v21, s[0:1]
	flat_store_dwordx4 v[0:1], v[2:5]
	flat_load_dwordx4 v[2:5], v[8:9] offset:16
	s_nop 0
	flat_load_dwordx4 v[20:23], v[8:9]
	v_cndmask_b32_e32 v6, v84, v6, vcc
	v_rsq_f32_e32 v6, v6
	s_nop 0
	v_mul_f32_e32 v7, 0x45800000, v6
	v_cndmask_b32_e32 v63, v6, v7, vcc
	v_pk_mul_f32 v[6:7], v[62:63], v[82:83]
	v_mov_b32_e32 v81, v63
	v_mov_b32_e32 v73, v63
	v_mov_b32_e32 v59, v63
	v_mov_b32_e32 v51, v63
	v_mov_b32_e32 v43, v63
	v_mov_b32_e32 v35, v63
	s_waitcnt vmcnt(0) lgkmcnt(0)
	v_mul_f32_e32 v7, v20, v7
	v_mul_f32_e32 v20, v6, v7
	v_pk_mul_f32 v[6:7], v[80:81], v[76:77]
	s_nop 0
	v_mul_f32_e32 v7, v21, v7
	v_mul_f32_e32 v21, v6, v7
	v_pk_mul_f32 v[6:7], v[72:73], v[66:67]
	s_nop 0
	v_mul_f32_e32 v7, v22, v7
	v_mul_f32_e32 v22, v6, v7
	v_pk_mul_f32 v[6:7], v[58:59], v[54:55]
	s_nop 0
	v_mul_f32_e32 v7, v23, v7
	v_mul_f32_e32 v23, v6, v7
	v_pk_mul_f32 v[6:7], v[50:51], v[44:45]
	s_nop 0
	v_mul_f32_e32 v2, v2, v7
	v_mul_f32_e32 v26, v6, v2
	v_pk_mul_f32 v[6:7], v[42:43], v[38:39]
	s_nop 0
	v_mul_f32_e32 v2, v3, v7
	v_mul_f32_e32 v6, v6, v2
	v_pk_mul_f32 v[2:3], v[34:35], v[28:29]
	s_nop 0
	v_mul_f32_e32 v3, v4, v3
	v_mul_f32_e32 v7, v2, v3
	v_mul_f32_e32 v2, 0xbfb8aa3b, v24
	v_exp_f32_e32 v2, v2
	v_add_u32_e32 v4, 0x8000, v22
	v_add_f32_e32 v2, 1.0, v2
	v_rcp_f32_e32 v62, v2
	s_nop 0
	v_pk_mul_f32 v[2:3], v[62:63], v[24:25]
	s_nop 0
	v_mul_f32_e32 v3, v5, v3
	v_mul_f32_e32 v5, v2, v3
	v_add_u32_e32 v2, 0x8000, v21
	v_add_u32_e32 v3, 0x8000, v20
	v_perm_b32 v2, v2, v3, s81
	v_add_u32_e32 v3, 0x8000, v23
	v_perm_b32 v3, v3, v4, s81
	v_add_u32_e32 v4, 0x8000, v6
	v_add_u32_e32 v6, 0x8000, v26
	v_perm_b32 v4, v4, v6, s81
	v_add_u32_e32 v5, 0x8000, v5
	v_add_u32_e32 v6, 0x8000, v7
	v_perm_b32 v5, v5, v6, s81
	v_add_co_u32_e32 v6, vcc, s20, v18
	flat_store_dwordx4 v[0:1], v[2:5] offset:1024
	flat_load_dwordx4 v[2:5], v[16:17] offset:2048
	v_addc_co_u32_e32 v7, vcc, 0, v19, vcc
	flat_load_dwordx4 v[18:21], v[6:7] offset:64
	flat_load_dwordx4 v[22:25], v[10:11]
	flat_load_dwordx4 v[26:29], v[10:11] offset:16
	s_waitcnt vmcnt(0) lgkmcnt(0)
	v_and_b32_e32 v31, 0xffff0000, v5
	v_lshlrev_b32_e32 v32, 16, v21
	v_lshlrev_b32_e32 v33, 16, v5
	v_mul_f32_e32 v5, 0xbfb8aa3b, v32
	v_exp_f32_e32 v5, v5
	v_and_b32_e32 v38, 0xffff0000, v20
	v_and_b32_e32 v30, 0xffff0000, v21
	v_and_b32_e32 v39, 0xffff0000, v4
	v_add_f32_e32 v5, 1.0, v5
	v_rcp_f32_e32 v36, v5
	v_mul_f32_e32 v5, 0xbfb8aa3b, v38
	v_exp_f32_e32 v5, v5
	v_lshlrev_b32_e32 v21, 16, v4
	v_lshlrev_b32_e32 v20, 16, v20
	v_mov_b32_e32 v4, v39
	v_add_f32_e32 v5, 1.0, v5
	v_rcp_f32_e32 v40, v5
	v_mov_b32_e32 v5, v21
	v_pk_mul_f32 v[42:43], v[4:5], v[4:5]
	v_mul_f32_e32 v4, 0xbfb8aa3b, v20
	v_lshlrev_b32_e32 v50, 16, v19
	v_lshlrev_b32_e32 v60, 16, v18
	v_exp_f32_e32 v4, v4
	v_and_b32_e32 v47, 0xffff0000, v3
	v_lshlrev_b32_e32 v51, 16, v3
	v_mul_f32_e32 v3, 0xbfb8aa3b, v50
	v_and_b32_e32 v57, 0xffff0000, v2
	v_lshlrev_b32_e32 v61, 16, v2
	v_mul_f32_e32 v2, 0xbfb8aa3b, v60
	v_exp_f32_e32 v3, v3
	v_exp_f32_e32 v2, v2
	v_add_f32_e32 v4, 1.0, v4
	v_and_b32_e32 v46, 0xffff0000, v19
	v_rcp_f32_e32 v44, v4
	v_mul_f32_e32 v4, 0xbfb8aa3b, v46
	v_add_f32_e32 v3, 1.0, v3
	v_and_b32_e32 v56, 0xffff0000, v18
	v_add_f32_e32 v2, 1.0, v2
	v_exp_f32_e32 v4, v4
	v_rcp_f32_e32 v54, v3
	v_mul_f32_e32 v3, 0xbfb8aa3b, v56
	v_rcp_f32_e32 v62, v2
	v_mul_f32_e32 v2, 0xbfb8aa3b, v30
	v_exp_f32_e32 v3, v3
	v_exp_f32_e32 v2, v2
	v_add_f32_e32 v4, 1.0, v4
	v_rcp_f32_e32 v48, v4
	v_mov_b32_e32 v4, v47
	v_mov_b32_e32 v5, v51
	v_add_f32_e32 v3, 1.0, v3
	v_add_f32_e32 v2, 1.0, v2
	v_pk_mul_f32 v[52:53], v[4:5], v[4:5]
	v_rcp_f32_e32 v58, v3
	v_rcp_f32_e32 v64, v2
	flat_load_dwordx4 v[2:5], v[16:17] offset:3072
	s_nop 0
	flat_load_dwordx4 v[16:19], v[6:7] offset:1088
	v_mov_b32_e32 v34, v31
	v_mov_b32_e32 v35, v33
	v_pk_mul_f32 v[34:35], v[34:35], v[34:35]
	s_waitcnt vmcnt(0) lgkmcnt(0)
	v_and_b32_e32 v81, 0xffff0000, v3
	v_lshlrev_b32_e32 v76, 16, v18
	v_lshlrev_b32_e32 v84, 16, v17
	v_and_b32_e32 v72, 0xffff0000, v18
	v_mul_f32_e32 v18, 0xbfb8aa3b, v76
	v_lshlrev_b32_e32 v85, 16, v3
	v_mul_f32_e32 v3, 0xbfb8aa3b, v84
	v_lshlrev_b32_e32 v66, 16, v19
	v_exp_f32_e32 v18, v18
	v_exp_f32_e32 v3, v3
	v_and_b32_e32 v7, 0xffff0000, v5
	v_lshlrev_b32_e32 v67, 16, v5
	v_mul_f32_e32 v5, 0xbfb8aa3b, v66
	v_exp_f32_e32 v5, v5
	v_add_f32_e32 v18, 1.0, v18
	v_and_b32_e32 v80, 0xffff0000, v17
	v_add_f32_e32 v3, 1.0, v3
	v_and_b32_e32 v96, 0xffff0000, v16
	v_lshlrev_b32_e32 v100, 16, v16
	v_rcp_f32_e32 v78, v18
	v_mul_f32_e32 v18, 0xbfb8aa3b, v80
	v_rcp_f32_e32 v94, v3
	v_and_b32_e32 v97, 0xffff0000, v2
	v_mul_f32_e32 v3, 0xbfb8aa3b, v96
	v_lshlrev_b32_e32 v101, 16, v2
	v_mul_f32_e32 v2, 0xbfb8aa3b, v100
	v_add_f32_e32 v5, 1.0, v5
	v_exp_f32_e32 v18, v18
	v_exp_f32_e32 v3, v3
	v_exp_f32_e32 v2, v2
	v_rcp_f32_e32 v70, v5
	v_mul_f32_e32 v5, 0xbfb8aa3b, v72
	v_exp_f32_e32 v5, v5
	v_add_f32_e32 v18, 1.0, v18
	v_add_f32_e32 v3, 1.0, v3
	v_add_f32_e32 v2, 1.0, v2
	v_and_b32_e32 v6, 0xffff0000, v19
	v_rcp_f32_e32 v82, v18
	v_mov_b32_e32 v18, v81
	v_mov_b32_e32 v19, v85
	v_rcp_f32_e32 v98, v3
	v_rcp_f32_e32 v102, v2
	v_mov_b32_e32 v2, v97
	v_mov_b32_e32 v3, v57
	v_and_b32_e32 v73, 0xffff0000, v4
	v_add_f32_e32 v5, 1.0, v5
	v_lshlrev_b32_e32 v77, 16, v4
	v_pk_mul_f32 v[18:19], v[18:19], v[18:19]
	v_pk_mul_f32 v[2:3], v[2:3], v[2:3]
	v_mov_b32_e32 v16, v101
	v_mov_b32_e32 v17, v61
	v_rcp_f32_e32 v74, v5
	v_mov_b32_e32 v4, v73
	v_mov_b32_e32 v5, v77
	v_pk_fma_f32 v[2:3], v[16:17], v[16:17], v[2:3]
	v_mov_b32_e32 v16, v19
	v_mov_b32_e32 v17, v53
	v_pk_mul_f32 v[4:5], v[4:5], v[4:5]
	v_pk_add_f32 v[2:3], v[16:17], v[2:3]
	v_mov_b32_e32 v19, v52
	v_mov_b32_e32 v68, v7
	v_mov_b32_e32 v69, v67
	v_pk_add_f32 v[2:3], v[18:19], v[2:3]
	v_mov_b32_e32 v16, v5
	v_mov_b32_e32 v17, v43
	v_pk_mul_f32 v[68:69], v[68:69], v[68:69]
	v_pk_add_f32 v[2:3], v[16:17], v[2:3]
	v_mov_b32_e32 v5, v42
	v_pk_add_f32 v[2:3], v[4:5], v[2:3]
	v_mov_b32_e32 v4, v69
	v_mov_b32_e32 v5, v35
	v_pk_add_f32 v[2:3], v[4:5], v[2:3]
	v_mov_b32_e32 v69, v34
	v_pk_add_f32 v[2:3], v[68:69], v[2:3]
	ds_bpermute_b32 v5, v88, v3
	ds_bpermute_b32 v4, v88, v2
	s_waitcnt lgkmcnt(0)
	v_pk_add_f32 v[2:3], v[2:3], v[4:5]
	ds_bpermute_b32 v5, v89, v3
	ds_bpermute_b32 v4, v89, v2
	s_waitcnt lgkmcnt(0)
	v_pk_add_f32 v[2:3], v[2:3], v[4:5]
	ds_bpermute_b32 v5, v90, v3
	ds_bpermute_b32 v4, v90, v2
	s_waitcnt lgkmcnt(0)
	v_pk_add_f32 v[2:3], v[2:3], v[4:5]
	ds_bpermute_b32 v5, v91, v3
	ds_bpermute_b32 v4, v91, v2
	s_waitcnt lgkmcnt(0)
	v_pk_add_f32 v[2:3], v[2:3], v[4:5]
	ds_bpermute_b32 v5, v92, v3
	ds_bpermute_b32 v4, v92, v2
	s_waitcnt lgkmcnt(0)
	v_pk_add_f32 v[2:3], v[2:3], v[4:5]
	s_nop 0
	v_pk_fma_f32 v[34:35], v[2:3], s[36:37], v[86:87] op_sel_hi:[1,0,0]
	s_nop 0
	v_mul_f32_e32 v2, 0x4b800000, v35
	v_cmp_gt_f32_e64 s[0:1], s80, v35
	v_cmp_gt_f32_e32 vcc, s80, v34
	s_nop 0
	v_cndmask_b32_e64 v2, v35, v2, s[0:1]
	v_rsq_f32_e32 v2, v2
	s_nop 0
	v_mul_f32_e32 v3, 0x45800000, v2
	v_cndmask_b32_e64 v63, v2, v3, s[0:1]
	v_pk_mul_f32 v[2:3], v[62:63], v[60:61]
	v_mov_b32_e32 v59, v63
	v_mul_f32_e32 v3, v22, v3
	v_mul_f32_e32 v4, v2, v3
	v_pk_mul_f32 v[2:3], v[58:59], v[56:57]
	v_mov_b32_e32 v55, v63
	v_mul_f32_e32 v3, v23, v3
	v_mul_f32_e32 v5, v2, v3
	v_pk_mul_f32 v[2:3], v[54:55], v[50:51]
	v_mov_b32_e32 v49, v63
	v_mul_f32_e32 v3, v24, v3
	v_mul_f32_e32 v16, v2, v3
	v_pk_mul_f32 v[2:3], v[48:49], v[46:47]
	v_mov_b32_e32 v45, v63
	v_mul_f32_e32 v3, v25, v3
	v_mul_f32_e32 v17, v2, v3
	v_pk_mul_f32 v[2:3], v[44:45], v[20:21]
	v_mov_b32_e32 v41, v63
	v_mul_f32_e32 v3, v26, v3
	v_mul_f32_e32 v18, v2, v3
	v_pk_mul_f32 v[2:3], v[40:41], v[38:39]
	v_mov_b32_e32 v37, v63
	v_mul_f32_e32 v3, v27, v3
	v_mul_f32_e32 v19, v2, v3
	v_pk_mul_f32 v[2:3], v[36:37], v[32:33]
	v_mov_b32_e32 v65, v63
	v_mul_f32_e32 v3, v28, v3
	v_mul_f32_e32 v20, v2, v3
	v_pk_mul_f32 v[2:3], v[64:65], v[30:31]
	s_mov_b64 s[0:1], 0xe80000
	v_mul_f32_e32 v3, v29, v3
	v_mul_f32_e32 v21, v2, v3
	v_add_u32_e32 v2, 0x8000, v5
	v_add_u32_e32 v3, 0x8000, v4
	v_perm_b32 v2, v2, v3, s81
	v_add_u32_e32 v3, 0x8000, v17
	v_add_u32_e32 v4, 0x8000, v16
	v_perm_b32 v3, v3, v4, s81
	v_add_u32_e32 v4, 0x8000, v19
	v_add_u32_e32 v5, 0x8000, v18
	v_perm_b32 v4, v4, v5, s81
	v_add_u32_e32 v5, 0x8000, v21
	v_add_u32_e32 v16, 0x8000, v20
	v_perm_b32 v5, v5, v16, s81
	flat_store_dwordx4 v[0:1], v[2:5] offset:2048
	flat_load_dwordx4 v[2:5], v[10:11]
	s_nop 0
	flat_load_dwordx4 v[16:19], v[10:11] offset:16
	v_mul_f32_e32 v20, 0x4b800000, v34
	v_cndmask_b32_e32 v20, v34, v20, vcc
	v_rsq_f32_e32 v20, v20
	v_lshl_add_u64 v[12:13], v[12:13], 0, s[0:1]
	s_mov_b64 s[0:1], 0x400000
	v_lshl_add_u64 v[14:15], v[14:15], 0, s[0:1]
	v_mul_f32_e32 v21, 0x45800000, v20
	v_cndmask_b32_e32 v103, v20, v21, vcc
	v_pk_mul_f32 v[20:21], v[102:103], v[100:101]
	v_mov_b32_e32 v99, v103
	v_mov_b32_e32 v95, v103
	v_mov_b32_e32 v83, v103
	v_mov_b32_e32 v79, v103
	v_mov_b32_e32 v75, v103
	v_mov_b32_e32 v71, v103
	s_mov_b32 s0, s69
	v_cmp_lt_i32_e32 vcc, s0, v93
	s_or_b64 s[12:13], vcc, s[12:13]
	s_waitcnt vmcnt(0) lgkmcnt(0)
	v_mul_f32_e32 v2, v2, v21
	v_mul_f32_e32 v22, v20, v2
	v_pk_mul_f32 v[20:21], v[98:99], v[96:97]
	s_nop 0
	v_mul_f32_e32 v2, v3, v21
	v_mul_f32_e32 v20, v20, v2
	v_pk_mul_f32 v[2:3], v[94:95], v[84:85]
	s_nop 0
	v_mul_f32_e32 v3, v4, v3
	v_mul_f32_e32 v4, v2, v3
	v_pk_mul_f32 v[2:3], v[82:83], v[80:81]
	v_add_u32_e32 v4, 0x8000, v4
	v_mul_f32_e32 v3, v5, v3
	v_mul_f32_e32 v5, v2, v3
	v_pk_mul_f32 v[2:3], v[78:79], v[76:77]
	s_nop 0
	v_mul_f32_e32 v3, v16, v3
	v_mul_f32_e32 v16, v2, v3
	v_pk_mul_f32 v[2:3], v[74:75], v[72:73]
	s_nop 0
	v_mul_f32_e32 v3, v17, v3
	v_mul_f32_e32 v17, v2, v3
	v_pk_mul_f32 v[2:3], v[70:71], v[66:67]
	s_nop 0
	v_mul_f32_e32 v3, v18, v3
	v_mul_f32_e32 v18, v2, v3
	v_mul_f32_e32 v2, 0xbfb8aa3b, v6
	v_exp_f32_e32 v2, v2
	s_nop 0
	v_add_f32_e32 v2, 1.0, v2
	v_rcp_f32_e32 v102, v2
	s_nop 0
	v_pk_mul_f32 v[2:3], v[102:103], v[6:7]
	s_nop 0
	v_mul_f32_e32 v3, v19, v3
	v_mul_f32_e32 v6, v2, v3
	v_add_u32_e32 v2, 0x8000, v20
	v_add_u32_e32 v3, 0x8000, v22
	v_perm_b32 v2, v2, v3, s81
	v_add_u32_e32 v3, 0x8000, v5
	v_perm_b32 v3, v3, v4, s81
	v_add_u32_e32 v4, 0x8000, v17
	v_add_u32_e32 v5, 0x8000, v16
	v_perm_b32 v4, v4, v5, s81
	v_add_u32_e32 v5, 0x8000, v6
	v_add_u32_e32 v6, 0x8000, v18
	v_perm_b32 v5, v5, v6, s81
	flat_store_dwordx4 v[0:1], v[2:5] offset:3072
	s_andn2_b64 exec, exec, s[12:13]
	s_cbranch_execnz .LBB0_1141

.LBB0_1148:
	v_readlane_b32 s0, v246, 0
	s_nop 1
	s_cmp_lt_u32 s0, 0x80
	s_cselect_b64 s[0:1], -1, 0
.LBB0_1149:
	s_and_b64 vcc, exec, s[0:1]
	s_cbranch_vccz .LBB0_1205
	s_waitcnt vmcnt(0) lgkmcnt(0)
	s_barrier
	v_readlane_b32 s3, v246, 0
	s_nop 1
	s_lshr_b32 s51, s3, 5
	s_lshl_b32 s51, 1, s51
	s_and_b32 s3, s3, 31
	v_mov_b32_e32 v14, v180
	s_lshl_b32 s0, s30, 1
	v_ashrrev_i32_e32 v1, 31, v14
	v_lshrrev_b32_e32 v1, 26, v1
	v_add_u32_e32 v1, v14, v1
	v_ashrrev_i32_e32 v8, 6, v1
	v_bfe_i32 v1, v14, 27, 1
	v_lshlrev_b32_e32 v0, 4, v14
	v_lshrrev_b32_e32 v1, 22, v1
	v_add_u32_e32 v1, v0, v1
	v_and_b32_e32 v1, 0xfffffc00, v1
	v_sub_u32_e32 v1, v0, v1
	v_lshrrev_b32_e32 v2, 4, v1
	v_bitop3_b32 v1, v2, v1, 32 bitop3:0x6c
	v_ashrrev_i32_e32 v3, 31, v1
	v_lshrrev_b32_e32 v3, 26, v3
	v_add_u32_e32 v3, v1, v3
	v_ashrrev_i32_e32 v9, 6, v3
	v_and_b32_e32 v3, 0xc0, v3
	v_sub_u32_e32 v1, v1, v3
	v_lshlrev_b32_e32 v2, 3, v8
	v_lshlrev_b32_e32 v4, 5, v8
	v_ashrrev_i16_sdwa v1, v147, sext(v1) dst_sel:DWORD dst_unused:UNUSED_PAD src0_sel:DWORD src1_sel:BYTE_0
	v_and_b32_e32 v2, 0xffff0, v2
	v_and_b32_e32 v4, 32, v4
	v_bfe_i32 v10, v1, 0, 16
	v_add_u32_e32 v1, v4, v10
	v_add_lshl_u32 v2, v9, v2, 12
	v_add_u32_e32 v0, 0x2000, v0
	v_lshl_add_u32 v144, v1, 1, v2
	v_ashrrev_i32_e32 v1, 31, v0
	v_lshrrev_b32_e32 v1, 22, v1
	v_add_u32_e32 v1, v0, v1
	v_ashrrev_i32_e32 v11, 10, v1
	v_mul_i32_i24_e32 v1, 0x400, v11
	s_add_u32 s4, s26, s0
	v_sub_u32_e32 v0, v0, v1
	s_addc_u32 s5, s27, 0
	s_ashr_i32 s2, s3, 3
	v_lshrrev_b32_e32 v1, 4, v0
	s_add_i32 s0, s2, 32
	v_readfirstlane_b32 s7, v14
	v_bitop3_b32 v0, v1, v0, 32 bitop3:0x6c
	s_and_b32 s6, s3, 7
	v_ashrrev_i32_e32 v2, 31, v0
	s_ashr_i32 s14, s7, 6
	s_ashr_i32 s1, s0, 31
	s_ashr_i32 s3, s7, 8
	v_lshrrev_b32_e32 v2, 26, v2
	s_lshl_b32 s20, s14, 10
	s_lshl_b64 s[8:9], s[0:1], 20
	s_lshl_b32 s12, s6, 20
	v_add_u32_e32 v2, v0, v2
	s_add_u32 s13, s4, s12
	v_ashrrev_i32_e32 v12, 6, v2
	v_and_b32_e32 v2, 0xc0, v2
	s_addc_u32 s15, s5, 0
	v_sub_u32_e32 v0, v0, v2
	s_add_u32 s4, s13, 0x3b00000
	v_lshlrev_b32_e32 v1, 3, v11
	v_lshlrev_b32_e32 v3, 5, v11
	v_ashrrev_i16_sdwa v0, v147, sext(v0) dst_sel:DWORD dst_unused:UNUSED_PAD src0_sel:DWORD src1_sel:BYTE_0
	s_addc_u32 s5, s15, 0
	s_add_i32 s1, s20, 0
	v_and_b32_e32 v1, 0xffff0, v1
	v_and_b32_e32 v3, 32, v3
	v_bfe_i32 v13, v0, 0, 16
	s_add_i32 m0, s1, 0x10000
	v_add_u32_e32 v0, v3, v13
	v_add_lshl_u32 v1, v12, v1, 12
	global_load_lds_dwordx4 v144, s[4:5]
	s_add_i32 m0, s1, 0x12000
	v_lshl_add_u32 v28, v0, 1, v1
	s_add_u32 s24, s13, 0x3b80000
	global_load_lds_dwordx4 v28, s[4:5]
	s_addc_u32 s25, s15, 0
	s_add_i32 m0, s1, 0x14000
	v_mov_b32_e32 v29, v145
	global_load_lds_dwordx4 v144, s[24:25]
	s_add_i32 m0, s1, 0x16000
	s_add_u32 s13, s26, s8
	s_addc_u32 s15, s27, s9
	s_add_u32 s8, s13, 0xe900000
	s_addc_u32 s9, s15, 0
	s_add_i32 s21, s1, 0x2000
	global_load_lds_dwordx4 v28, s[24:25]
	s_mov_b32 m0, s1
	s_add_u32 s28, s13, 0xe980000
	global_load_lds_dwordx4 v144, s[8:9]
	s_mov_b32 m0, s21
	s_addc_u32 s29, s15, 0
	s_add_i32 s24, s1, 0x4000
	global_load_lds_dwordx4 v28, s[8:9]
	s_mov_b32 m0, s24
	s_add_i32 s25, s1, 0x6000
	global_load_lds_dwordx4 v144, s[28:29]
	s_mov_b32 m0, s25
	s_mov_b32 s13, s67
	global_load_lds_dwordx4 v28, s[28:29]
	v_lshl_add_u64 v[6:7], s[4:5], 0, v[144:145]
	v_lshl_add_u64 v[4:5], s[4:5], 0, v[28:29]
	v_lshl_add_u64 v[2:3], s[8:9], 0, v[144:145]
	s_cmp_lg_u32 s3, 1
	v_lshl_add_u64 v[0:1], s[8:9], 0, v[28:29]
	s_cbranch_scc1 .LBB0_1152
	s_barrier
.LBB0_1152:
	v_bfe_u32 v146, v14, 4, 2
	s_lshl_b32 s14, s14, 5
	v_and_b32_e32 v15, 15, v14
	v_lshlrev_b32_e32 v16, 4, v146
	v_lshlrev_b32_e32 v14, 2, v14
	s_and_b32 s28, s14, 0x60
	v_lshl_or_b32 v160, s3, 6, v15
	v_lshl_or_b32 v15, v15, 6, v16
	v_and_b32_e32 v14, 32, v14
	s_lshl_b32 s14, s28, 7
	v_bitop3_b32 v38, v15, s14, v14 bitop3:0xde
	s_lshl_b64 s[14:15], s[90:91], 22
	s_add_i32 m0, s1, 0x18000
	v_lshl_add_u64 v[6:7], v[6:7], 0, s[94:95]
	s_lshl_b32 s3, s3, 13
	s_and_b32 s14, s14, 0xff800000
	s_waitcnt vmcnt(2)
	s_barrier
	global_load_lds_dwordx4 v[6:7], off
	v_lshl_add_u64 v[4:5], v[4:5], 0, s[94:95]
	s_add_i32 m0, s1, 0x1a000
	s_add_i32 s29, s1, 0x8000
	s_add_i32 s31, s1, 0xa000
	global_load_lds_dwordx4 v[4:5], off
	v_lshl_add_u64 v[2:3], v[2:3], 0, s[94:95]
	s_mov_b32 m0, s29
	s_add_u32 s34, s4, 0x80080
	global_load_lds_dwordx4 v[2:3], off
	v_lshl_add_u64 v[0:1], v[0:1], 0, s[94:95]
	s_mov_b32 m0, s31
	s_addc_u32 s35, s5, 0
	global_load_lds_dwordx4 v[0:1], off
	s_add_i32 m0, s1, 0x1c000
	v_lshl_add_u64 v[0:1], s[34:35], 0, v[144:145]
	global_load_lds_dwordx4 v[0:1], off
	v_lshl_add_u64 v[0:1], s[34:35], 0, v[28:29]
	s_add_i32 m0, s1, 0x1e000
	s_or_b64 s[12:13], s[14:15], s[12:13]
	global_load_lds_dwordx4 v[0:1], off
	v_bitop3_b32 v14, v15, s3, v14 bitop3:0xde
	s_add_u32 s3, s26, s12
	s_addc_u32 s12, s27, s13
	s_add_u32 s33, s3, 0x3b00100
	s_addc_u32 s34, s12, 0
	s_ashr_i32 s3, s2, 31
	s_lshl_b64 s[2:3], s[2:3], 20
	v_lshlrev_b32_e32 v0, 15, v11
	v_and_b32_e32 v0, 0xffff0000, v0
	s_add_u32 s35, s26, s2
	v_lshl_add_u32 v0, v12, 12, v0
	v_and_b32_e32 v1, 1, v11
	s_addc_u32 s36, s27, s3
	v_lshl_or_b32 v0, v1, 6, v0
	s_add_u32 s2, s35, 0x10980080
	v_lshl_add_u32 v0, v13, 1, v0
	v_mov_b32_e32 v1, v145
	s_addc_u32 s3, s36, 0
	v_lshl_add_u64 v[30:31], s[2:3], 0, v[0:1]
	v_lshlrev_b32_e32 v0, 15, v8
	v_and_b32_e32 v0, 0xffff0000, v0
	v_lshl_add_u32 v0, v9, 12, v0
	v_and_b32_e32 v1, 1, v8
	v_lshl_or_b32 v0, v1, 6, v0
	s_waitcnt vmcnt(6)
	v_lshl_add_u32 v0, v10, 1, v0
	v_mov_b32_e32 v1, v145
	v_lshl_add_u64 v[36:37], s[2:3], 0, v[0:1]
	v_mov_b32_e32 v0, 0
	s_mov_b32 s37, -2
	s_mov_b64 s[12:13], 0
	v_add_u32_e32 v39, 0, v14
	v_lshrrev_b32_e32 v178, 8, v180
	v_and_b32_e32 v178, 1, v178
	v_lshlrev_b32_e32 v178, 6, v178
	v_and_b32_e32 v179, 15, v180
	v_or_b32_e32 v178, v178, v179
	v_lshlrev_b32_e32 v178, 13, v178
	v_lshrrev_b32_e32 v179, 6, v180
	v_and_b32_e32 v179, 3, v179
	v_lshl_or_b32 v178, v179, 7, v178
	v_lshrrev_b32_e32 v179, 4, v180
	v_and_b32_e32 v179, 3, v179
	v_lshl_or_b32 v178, v179, 4, v178
	v_readlane_b32 s32, v246, 0
	s_nop 1
	s_and_b32 s32, s32, 31
	s_lshr_b32 s100, s32, 3
	s_and_b32 s32, s32, 7
	s_lshl_b32 s32, s32, 10
	s_lshl_b32 s100, s100, 21
	s_add_u32 s32, s32, s100
	s_cmp_eq_u32 s90, 0
	s_cbranch_scc1 .Lpre_smp_in1
	s_add_u32 s100, s44, 0xbd00000
	s_addc_u32 s101, s45, 0
	s_branch .Lpre_smp_go
.Lpre_smp_in1:
	v_mov_b32_e32 v179, 0x23008
	ds_read_b64 v[140:141], v179
	s_waitcnt lgkmcnt(0)
	v_readfirstlane_b32 s100, v140
	v_readfirstlane_b32 s101, v141
.Lpre_smp_go:
	s_add_u32 s100, s100, s32
	s_addc_u32 s101, s101, 0
	s_cmp_eq_u32 s51, 15
	s_cbranch_scc1 .Lqp_smp_full
	v_mov_b32_e32 v0, 0
	v_mov_b32_e32 v1, 0
	v_mov_b32_e32 v2, 0
	v_mov_b32_e32 v3, 0
	v_mov_b32_e32 v4, 0
	v_mov_b32_e32 v5, 0
	v_mov_b32_e32 v6, 0
	v_mov_b32_e32 v7, 0
	v_mov_b32_e32 v8, 0
	v_mov_b32_e32 v9, 0
	v_mov_b32_e32 v10, 0
	v_mov_b32_e32 v11, 0
	v_mov_b32_e32 v12, 0
	v_mov_b32_e32 v13, 0
	v_mov_b32_e32 v14, 0
	v_mov_b32_e32 v15, 0
	v_mov_b32_e32 v16, 0
	v_mov_b32_e32 v17, 0
	v_mov_b32_e32 v18, 0
	v_mov_b32_e32 v19, 0
	v_mov_b32_e32 v20, 0
	v_mov_b32_e32 v21, 0
	v_mov_b32_e32 v22, 0
	v_mov_b32_e32 v23, 0
	v_mov_b32_e32 v24, 0
	v_mov_b32_e32 v25, 0
	v_mov_b32_e32 v26, 0
	v_mov_b32_e32 v27, 0
	v_mov_b32_e32 v32, 0
	v_mov_b32_e32 v33, 0
	v_mov_b32_e32 v34, 0
	v_mov_b32_e32 v35, 0
	v_mov_b32_e32 v44, 0
	v_mov_b32_e32 v45, 0
	v_mov_b32_e32 v46, 0
	v_mov_b32_e32 v47, 0
	v_mov_b32_e32 v52, 0
	v_mov_b32_e32 v53, 0
	v_mov_b32_e32 v54, 0
	v_mov_b32_e32 v55, 0
	v_mov_b32_e32 v56, 0
	v_mov_b32_e32 v57, 0
	v_mov_b32_e32 v58, 0
	v_mov_b32_e32 v59, 0
	v_mov_b32_e32 v60, 0
	v_mov_b32_e32 v61, 0
	v_mov_b32_e32 v62, 0
	v_mov_b32_e32 v63, 0
	v_mov_b32_e32 v64, 0
	v_mov_b32_e32 v65, 0
	v_mov_b32_e32 v66, 0
	v_mov_b32_e32 v67, 0
	v_mov_b32_e32 v68, 0
	v_mov_b32_e32 v69, 0
	v_mov_b32_e32 v70, 0
	v_mov_b32_e32 v71, 0
	v_mov_b32_e32 v72, 0
	v_mov_b32_e32 v73, 0
	v_mov_b32_e32 v74, 0
	v_mov_b32_e32 v75, 0
	v_mov_b32_e32 v76, 0
	v_mov_b32_e32 v77, 0
	v_mov_b32_e32 v78, 0
	v_mov_b32_e32 v79, 0
	v_mov_b32_e32 v80, 0
	v_mov_b32_e32 v81, 0
	v_mov_b32_e32 v82, 0
	v_mov_b32_e32 v83, 0
	v_mov_b32_e32 v84, 0
	v_mov_b32_e32 v85, 0
	v_mov_b32_e32 v86, 0
	v_mov_b32_e32 v87, 0
	v_mov_b32_e32 v88, 0
	v_mov_b32_e32 v89, 0
	v_mov_b32_e32 v90, 0
	v_mov_b32_e32 v91, 0
	v_mov_b32_e32 v92, 0
	v_mov_b32_e32 v93, 0
	v_mov_b32_e32 v94, 0
	v_mov_b32_e32 v95, 0
	v_mov_b32_e32 v96, 0
	v_mov_b32_e32 v97, 0
	v_mov_b32_e32 v98, 0
	v_mov_b32_e32 v99, 0
	v_mov_b32_e32 v100, 0
	v_mov_b32_e32 v101, 0
	v_mov_b32_e32 v102, 0
	v_mov_b32_e32 v103, 0
	v_mov_b32_e32 v104, 0
	v_mov_b32_e32 v105, 0
	v_mov_b32_e32 v106, 0
	v_mov_b32_e32 v107, 0
	v_mov_b32_e32 v108, 0
	v_mov_b32_e32 v109, 0
	v_mov_b32_e32 v110, 0
	v_mov_b32_e32 v111, 0
	v_mov_b32_e32 v112, 0
	v_mov_b32_e32 v113, 0
	v_mov_b32_e32 v114, 0
	v_mov_b32_e32 v115, 0
	v_mov_b32_e32 v116, 0
	v_mov_b32_e32 v117, 0
	v_mov_b32_e32 v118, 0
	v_mov_b32_e32 v119, 0
	v_mov_b32_e32 v120, 0
	v_mov_b32_e32 v121, 0
	v_mov_b32_e32 v122, 0
	v_mov_b32_e32 v123, 0
	v_mov_b32_e32 v124, 0
	v_mov_b32_e32 v125, 0
	v_mov_b32_e32 v126, 0
	v_mov_b32_e32 v127, 0
	v_mov_b32_e32 v128, 0
	v_mov_b32_e32 v129, 0
	v_mov_b32_e32 v130, 0
	v_mov_b32_e32 v131, 0
	v_mov_b32_e32 v132, 0
	v_mov_b32_e32 v133, 0
	v_mov_b32_e32 v134, 0
	v_mov_b32_e32 v135, 0
	v_mov_b32_e32 v136, 0
	v_mov_b32_e32 v137, 0
	v_mov_b32_e32 v138, 0
	v_mov_b32_e32 v139, 0
	v_mov_b32_e32 v140, 0
	v_mov_b32_e32 v141, 0
	v_mov_b32_e32 v142, 0
	v_mov_b32_e32 v143, 0
.Lqp_smp_full:
	s_bitcmp1_b32 s51, 0
	s_cbranch_scc0 .Lqp_smp_0
	global_load_dwordx4 v[140:143], v178, s[100:101]
.Lqp_smp_0:
	s_bitcmp1_b32 s51, 0
	s_cbranch_scc0 .Lqp_smp_1
	global_load_dwordx4 v[136:139], v178, s[100:101] offset:64
.Lqp_smp_1:
	s_bitcmp1_b32 s51, 1
	s_cbranch_scc0 .Lqp_smp_2
	global_load_dwordx4 v[132:135], v178, s[100:101] offset:512
.Lqp_smp_2:
	s_bitcmp1_b32 s51, 1
	s_cbranch_scc0 .Lqp_smp_3
	global_load_dwordx4 v[128:131], v178, s[100:101] offset:576
.Lqp_smp_3:
	s_add_u32 s100, s100, 0x20000
	s_addc_u32 s101, s101, 0
	s_bitcmp1_b32 s51, 0
	s_cbranch_scc0 .Lqp_smp_4
	global_load_dwordx4 v[124:127], v178, s[100:101]
.Lqp_smp_4:
	s_bitcmp1_b32 s51, 0
	s_cbranch_scc0 .Lqp_smp_5
	global_load_dwordx4 v[120:123], v178, s[100:101] offset:64
.Lqp_smp_5:
	s_bitcmp1_b32 s51, 1
	s_cbranch_scc0 .Lqp_smp_6
	global_load_dwordx4 v[116:119], v178, s[100:101] offset:512
.Lqp_smp_6:
	s_bitcmp1_b32 s51, 1
	s_cbranch_scc0 .Lqp_smp_7
	global_load_dwordx4 v[112:115], v178, s[100:101] offset:576
.Lqp_smp_7:
	s_add_u32 s100, s100, 0x20000
	s_addc_u32 s101, s101, 0
	s_bitcmp1_b32 s51, 0
	s_cbranch_scc0 .Lqp_smp_8
	global_load_dwordx4 v[108:111], v178, s[100:101]
.Lqp_smp_8:
	s_bitcmp1_b32 s51, 0
	s_cbranch_scc0 .Lqp_smp_9
	global_load_dwordx4 v[104:107], v178, s[100:101] offset:64
.Lqp_smp_9:
	s_bitcmp1_b32 s51, 1
	s_cbranch_scc0 .Lqp_smp_10
	global_load_dwordx4 v[100:103], v178, s[100:101] offset:512
.Lqp_smp_10:
	s_bitcmp1_b32 s51, 1
	s_cbranch_scc0 .Lqp_smp_11
	global_load_dwordx4 v[96:99], v178, s[100:101] offset:576
.Lqp_smp_11:
	s_add_u32 s100, s100, 0x20000
	s_addc_u32 s101, s101, 0
	s_bitcmp1_b32 s51, 0
	s_cbranch_scc0 .Lqp_smp_12
	global_load_dwordx4 v[92:95], v178, s[100:101]
.Lqp_smp_12:
	s_bitcmp1_b32 s51, 0
	s_cbranch_scc0 .Lqp_smp_13
	global_load_dwordx4 v[88:91], v178, s[100:101] offset:64
.Lqp_smp_13:
	s_bitcmp1_b32 s51, 1
	s_cbranch_scc0 .Lqp_smp_14
	global_load_dwordx4 v[84:87], v178, s[100:101] offset:512
.Lqp_smp_14:
	s_bitcmp1_b32 s51, 1
	s_cbranch_scc0 .Lqp_smp_15
	global_load_dwordx4 v[80:83], v178, s[100:101] offset:576
.Lqp_smp_15:
	s_add_u32 s100, s100, 0xa0000
	s_addc_u32 s101, s101, 0
	s_bitcmp1_b32 s51, 2
	s_cbranch_scc0 .Lqp_smp_16
	global_load_dwordx4 v[76:79], v178, s[100:101]
.Lqp_smp_16:
	s_bitcmp1_b32 s51, 2
	s_cbranch_scc0 .Lqp_smp_17
	global_load_dwordx4 v[72:75], v178, s[100:101] offset:64
.Lqp_smp_17:
	s_bitcmp1_b32 s51, 3
	s_cbranch_scc0 .Lqp_smp_18
	global_load_dwordx4 v[68:71], v178, s[100:101] offset:512
.Lqp_smp_18:
	s_bitcmp1_b32 s51, 3
	s_cbranch_scc0 .Lqp_smp_19
	global_load_dwordx4 v[64:67], v178, s[100:101] offset:576
.Lqp_smp_19:
	s_add_u32 s100, s100, 0x20000
	s_addc_u32 s101, s101, 0
	s_bitcmp1_b32 s51, 2
	s_cbranch_scc0 .Lqp_smp_20
	global_load_dwordx4 v[60:63], v178, s[100:101]
.Lqp_smp_20:
	s_bitcmp1_b32 s51, 2
	s_cbranch_scc0 .Lqp_smp_21
	global_load_dwordx4 v[56:59], v178, s[100:101] offset:64
.Lqp_smp_21:
	s_bitcmp1_b32 s51, 3
	s_cbranch_scc0 .Lqp_smp_22
	global_load_dwordx4 v[52:55], v178, s[100:101] offset:512
.Lqp_smp_22:
	s_bitcmp1_b32 s51, 3
	s_cbranch_scc0 .Lqp_smp_23
	global_load_dwordx4 v[44:47], v178, s[100:101] offset:576
.Lqp_smp_23:
	s_add_u32 s100, s100, 0x20000
	s_addc_u32 s101, s101, 0
	s_bitcmp1_b32 s51, 2
	s_cbranch_scc0 .Lqp_smp_24
	global_load_dwordx4 v[32:35], v178, s[100:101]
.Lqp_smp_24:
	s_bitcmp1_b32 s51, 2
	s_cbranch_scc0 .Lqp_smp_25
	global_load_dwordx4 v[24:27], v178, s[100:101] offset:64
.Lqp_smp_25:
	s_bitcmp1_b32 s51, 3
	s_cbranch_scc0 .Lqp_smp_26
	global_load_dwordx4 v[20:23], v178, s[100:101] offset:512
.Lqp_smp_26:
	s_bitcmp1_b32 s51, 3
	s_cbranch_scc0 .Lqp_smp_27
	global_load_dwordx4 v[16:19], v178, s[100:101] offset:576
.Lqp_smp_27:
	s_add_u32 s100, s100, 0x20000
	s_addc_u32 s101, s101, 0
	s_bitcmp1_b32 s51, 2
	s_cbranch_scc0 .Lqp_smp_28
	global_load_dwordx4 v[12:15], v178, s[100:101]
.Lqp_smp_28:
	s_bitcmp1_b32 s51, 2
	s_cbranch_scc0 .Lqp_smp_29
	global_load_dwordx4 v[8:11], v178, s[100:101] offset:64
.Lqp_smp_29:
	s_bitcmp1_b32 s51, 3
	s_cbranch_scc0 .Lqp_smp_30
	global_load_dwordx4 v[4:7], v178, s[100:101] offset:512
.Lqp_smp_30:
	s_bitcmp1_b32 s51, 3
	s_cbranch_scc0 .Lqp_smp_31
	global_load_dwordx4 v[0:3], v178, s[100:101] offset:576
.Lqp_smp_31:
	s_waitcnt vmcnt(0)
	s_barrier
	s_cmp_eq_u32 s51, 15
	s_cbranch_scc0 .Lq_smp_disp
.LBB0_1153:
	s_add_u32 s2, s35, s12
	s_addc_u32 s3, s36, s13
	s_add_u32 s2, s2, 0x10900100
	s_addc_u32 s3, s3, 0
	s_add_u32 s38, s33, s12
	s_addc_u32 s39, s34, s13
	s_add_i32 s40, 0, 0x10000
	s_cmpk_eq_i32 s12, 0xf00
	s_cselect_b32 s15, s9, s3
	s_cselect_b32 s14, s8, s2
	v_add_u32_e32 v161, s40, v38
	s_cselect_b32 s3, s5, s39
	s_cselect_b32 s2, s4, s38
	s_add_i32 s41, 0, 0x14000
	ds_read_b128 v[40:43], v161
	ds_read_b128 v[48:51], v161 offset:1024
	ds_read_b128 v[162:165], v161 offset:2048
	ds_read_b128 v[166:169], v161 offset:3072
	v_add_u32_e32 v161, s41, v38
	ds_read_b128 v[170:173], v161
	ds_read_b128 v[174:177], v161 offset:1024
	ds_read_b128 v[190:193], v161 offset:2048
	ds_read_b128 v[194:197], v161 offset:3072
	v_lshl_add_u64 v[178:179], v[36:37], 0, s[12:13]
	s_add_i32 m0, s1, 0xc000
	ds_read_b128 v[198:201], v39
	ds_read_b128 v[202:205], v39 offset:1024
	ds_read_b128 v[206:209], v39 offset:2048
	ds_read_b128 v[210:213], v39 offset:3072
	ds_read_b128 v[214:217], v39 offset:4096
	ds_read_b128 v[218:221], v39 offset:5120
	ds_read_b128 v[222:225], v39 offset:6144
	ds_read_b128 v[226:229], v39 offset:7168
	global_load_lds_dwordx4 v[178:179], off
	v_lshl_add_u64 v[178:179], v[30:31], 0, s[12:13]
	s_add_i32 m0, s1, 0xe000
	s_nop 0
	global_load_lds_dwordx4 v[178:179], off
	s_waitcnt vmcnt(8)
	s_waitcnt lgkmcnt(0)
	s_barrier
	s_setprio 1
	s_waitcnt lgkmcnt(0)
	v_mfma_f32_16x16x32_bf16 v[140:143], v[40:43], v[198:201], v[140:143]
	v_mfma_f32_16x16x32_bf16 v[136:139], v[162:165], v[198:201], v[136:139]
	v_mfma_f32_16x16x32_bf16 v[124:127], v[40:43], v[206:209], v[124:127]
	v_mfma_f32_16x16x32_bf16 v[120:123], v[162:165], v[206:209], v[120:123]
	v_mfma_f32_16x16x32_bf16 v[108:111], v[40:43], v[214:217], v[108:111]
	v_mfma_f32_16x16x32_bf16 v[104:107], v[162:165], v[214:217], v[104:107]
	v_mfma_f32_16x16x32_bf16 v[92:95], v[40:43], v[222:225], v[92:95]
	v_mfma_f32_16x16x32_bf16 v[88:91], v[162:165], v[222:225], v[88:91]
	v_mfma_f32_16x16x32_bf16 v[140:143], v[48:51], v[202:205], v[140:143]
	v_mfma_f32_16x16x32_bf16 v[136:139], v[166:169], v[202:205], v[136:139]
	v_mfma_f32_16x16x32_bf16 v[124:127], v[48:51], v[210:213], v[124:127]
	v_mfma_f32_16x16x32_bf16 v[120:123], v[166:169], v[210:213], v[120:123]
	v_mfma_f32_16x16x32_bf16 v[108:111], v[48:51], v[218:221], v[108:111]
	v_mfma_f32_16x16x32_bf16 v[104:107], v[166:169], v[218:221], v[104:107]
	v_mfma_f32_16x16x32_bf16 v[92:95], v[48:51], v[226:229], v[92:95]
	v_mfma_f32_16x16x32_bf16 v[88:91], v[166:169], v[226:229], v[88:91]
	s_setprio 0
	s_setprio 1
	v_mfma_f32_16x16x32_bf16 v[132:135], v[170:173], v[198:201], v[132:135]
	v_mfma_f32_16x16x32_bf16 v[128:131], v[190:193], v[198:201], v[128:131]
	v_mfma_f32_16x16x32_bf16 v[116:119], v[170:173], v[206:209], v[116:119]
	v_mfma_f32_16x16x32_bf16 v[112:115], v[190:193], v[206:209], v[112:115]
	v_mfma_f32_16x16x32_bf16 v[100:103], v[170:173], v[214:217], v[100:103]
	v_mfma_f32_16x16x32_bf16 v[96:99], v[190:193], v[214:217], v[96:99]
	v_mfma_f32_16x16x32_bf16 v[84:87], v[170:173], v[222:225], v[84:87]
	v_mfma_f32_16x16x32_bf16 v[80:83], v[190:193], v[222:225], v[80:83]
	v_mfma_f32_16x16x32_bf16 v[132:135], v[174:177], v[202:205], v[132:135]
	v_mfma_f32_16x16x32_bf16 v[128:131], v[194:197], v[202:205], v[128:131]
	v_mfma_f32_16x16x32_bf16 v[116:119], v[174:177], v[210:213], v[116:119]
	v_mfma_f32_16x16x32_bf16 v[112:115], v[194:197], v[210:213], v[112:115]
	v_mfma_f32_16x16x32_bf16 v[100:103], v[174:177], v[218:221], v[100:103]
	v_mfma_f32_16x16x32_bf16 v[96:99], v[194:197], v[218:221], v[96:99]
	v_mfma_f32_16x16x32_bf16 v[84:87], v[174:177], v[226:229], v[84:87]
	v_mfma_f32_16x16x32_bf16 v[80:83], v[194:197], v[226:229], v[80:83]
	s_setprio 0
	s_barrier
	s_add_i32 s38, s40, s20
	v_lshl_add_u64 v[178:179], s[2:3], 0, v[144:145]
	s_mov_b32 m0, s38
	ds_read_b128 v[198:201], v39 offset:16384
	ds_read_b128 v[202:205], v39 offset:17408
	ds_read_b128 v[206:209], v39 offset:18432
	ds_read_b128 v[210:213], v39 offset:19456
	ds_read_b128 v[214:217], v39 offset:20480
	ds_read_b128 v[218:221], v39 offset:21504
	ds_read_b128 v[222:225], v39 offset:22528
	ds_read_b128 v[226:229], v39 offset:23552
	global_load_lds_dwordx4 v[178:179], off
	s_add_i32 m0, s38, 0x2000
	s_add_u32 s38, s2, 0x80000
	v_lshl_add_u64 v[230:231], s[2:3], 0, v[28:29]
	s_addc_u32 s39, s3, 0
	s_add_i32 s40, s41, s20
	global_load_lds_dwordx4 v[230:231], off
	v_lshl_add_u64 v[232:233], s[38:39], 0, v[144:145]
	s_mov_b32 m0, s40
	v_lshl_add_u64 v[234:235], s[14:15], 0, v[28:29]
	global_load_lds_dwordx4 v[232:233], off
	v_lshl_add_u64 v[232:233], s[38:39], 0, v[28:29]
	s_add_i32 m0, s40, 0x2000
	s_nop 0
	global_load_lds_dwordx4 v[232:233], off
	v_lshl_add_u64 v[232:233], s[14:15], 0, v[144:145]
	s_mov_b32 m0, s1
	s_nop 0
	global_load_lds_dwordx4 v[232:233], off
	s_mov_b32 m0, s21
	s_nop 0
	global_load_lds_dwordx4 v[234:235], off
	s_waitcnt vmcnt(8)
	s_waitcnt lgkmcnt(0)
	s_barrier
	s_setprio 1
	s_waitcnt lgkmcnt(0)
	v_mfma_f32_16x16x32_bf16 v[76:79], v[40:43], v[198:201], v[76:79]
	v_mfma_f32_16x16x32_bf16 v[72:75], v[162:165], v[198:201], v[72:75]
	v_mfma_f32_16x16x32_bf16 v[60:63], v[40:43], v[206:209], v[60:63]
	v_mfma_f32_16x16x32_bf16 v[56:59], v[162:165], v[206:209], v[56:59]
	v_mfma_f32_16x16x32_bf16 v[32:35], v[40:43], v[214:217], v[32:35]
	v_mfma_f32_16x16x32_bf16 v[24:27], v[162:165], v[214:217], v[24:27]
	v_mfma_f32_16x16x32_bf16 v[12:15], v[40:43], v[222:225], v[12:15]
	v_mfma_f32_16x16x32_bf16 v[8:11], v[162:165], v[222:225], v[8:11]
	v_mfma_f32_16x16x32_bf16 v[76:79], v[48:51], v[202:205], v[76:79]
	v_mfma_f32_16x16x32_bf16 v[72:75], v[166:169], v[202:205], v[72:75]
	v_mfma_f32_16x16x32_bf16 v[60:63], v[48:51], v[210:213], v[60:63]
	v_mfma_f32_16x16x32_bf16 v[56:59], v[166:169], v[210:213], v[56:59]
	v_mfma_f32_16x16x32_bf16 v[32:35], v[48:51], v[218:221], v[32:35]
	v_mfma_f32_16x16x32_bf16 v[24:27], v[166:169], v[218:221], v[24:27]
	v_mfma_f32_16x16x32_bf16 v[12:15], v[48:51], v[226:229], v[12:15]
	v_mfma_f32_16x16x32_bf16 v[8:11], v[166:169], v[226:229], v[8:11]
	s_setprio 0
	s_setprio 1
	v_mfma_f32_16x16x32_bf16 v[52:55], v[170:173], v[206:209], v[52:55]
	v_mfma_f32_16x16x32_bf16 v[44:47], v[190:193], v[206:209], v[44:47]
	v_mfma_f32_16x16x32_bf16 v[20:23], v[170:173], v[214:217], v[20:23]
	v_mfma_f32_16x16x32_bf16 v[16:19], v[190:193], v[214:217], v[16:19]
	v_mfma_f32_16x16x32_bf16 v[4:7], v[170:173], v[222:225], v[4:7]
	v_mfma_f32_16x16x32_bf16 v[0:3], v[190:193], v[222:225], v[0:3]
	v_mfma_f32_16x16x32_bf16 v[40:43], v[170:173], v[198:201], v[68:71]
	v_mfma_f32_16x16x32_bf16 v[48:51], v[190:193], v[198:201], v[64:67]
	v_mfma_f32_16x16x32_bf16 v[52:55], v[174:177], v[210:213], v[52:55]
	v_mfma_f32_16x16x32_bf16 v[44:47], v[194:197], v[210:213], v[44:47]
	v_mfma_f32_16x16x32_bf16 v[20:23], v[174:177], v[218:221], v[20:23]
	v_mfma_f32_16x16x32_bf16 v[16:19], v[194:197], v[218:221], v[16:19]
	v_mfma_f32_16x16x32_bf16 v[4:7], v[174:177], v[226:229], v[4:7]
	v_mfma_f32_16x16x32_bf16 v[0:3], v[194:197], v[226:229], v[0:3]
	v_mfma_f32_16x16x32_bf16 v[40:43], v[174:177], v[202:205], v[40:43]
	v_mfma_f32_16x16x32_bf16 v[48:51], v[194:197], v[202:205], v[48:51]
	s_setprio 0
	s_barrier
	s_add_i32 s38, 0, 0x18000
	v_add_u32_e32 v161, s38, v38
	s_add_i32 s39, 0, 0x1c000
	ds_read_b128 v[64:67], v161
	ds_read_b128 v[68:71], v161 offset:1024
	ds_read_b128 v[162:165], v161 offset:2048
	ds_read_b128 v[166:169], v161 offset:3072
	v_add_u32_e32 v161, s39, v38
	ds_read_b128 v[170:173], v161
	ds_read_b128 v[174:177], v161 offset:1024
	ds_read_b128 v[190:193], v161 offset:2048
	ds_read_b128 v[194:197], v161 offset:3072
	s_add_u32 s14, s14, 0x80000
	s_addc_u32 s15, s15, 0
	s_mov_b32 m0, s24
	v_lshl_add_u64 v[236:237], s[14:15], 0, v[144:145]
	ds_read_b128 v[198:201], v39 offset:32768
	ds_read_b128 v[202:205], v39 offset:33792
	ds_read_b128 v[206:209], v39 offset:34816
	ds_read_b128 v[210:213], v39 offset:35840
	ds_read_b128 v[214:217], v39 offset:36864
	ds_read_b128 v[218:221], v39 offset:37888
	ds_read_b128 v[222:225], v39 offset:38912
	ds_read_b128 v[226:229], v39 offset:39936
	global_load_lds_dwordx4 v[236:237], off
	v_lshl_add_u64 v[236:237], s[14:15], 0, v[28:29]
	s_mov_b32 m0, s25
	s_nop 0
	global_load_lds_dwordx4 v[236:237], off
	s_waitcnt vmcnt(8)
	s_waitcnt lgkmcnt(0)
	s_barrier
	s_setprio 1
	s_waitcnt lgkmcnt(0)
	v_mfma_f32_16x16x32_bf16 v[140:143], v[64:67], v[198:201], v[140:143]
	v_mfma_f32_16x16x32_bf16 v[136:139], v[162:165], v[198:201], v[136:139]
	v_mfma_f32_16x16x32_bf16 v[124:127], v[64:67], v[206:209], v[124:127]
	v_mfma_f32_16x16x32_bf16 v[120:123], v[162:165], v[206:209], v[120:123]
	v_mfma_f32_16x16x32_bf16 v[108:111], v[64:67], v[214:217], v[108:111]
	v_mfma_f32_16x16x32_bf16 v[104:107], v[162:165], v[214:217], v[104:107]
	v_mfma_f32_16x16x32_bf16 v[92:95], v[64:67], v[222:225], v[92:95]
	v_mfma_f32_16x16x32_bf16 v[88:91], v[162:165], v[222:225], v[88:91]
	v_mfma_f32_16x16x32_bf16 v[140:143], v[68:71], v[202:205], v[140:143]
	v_mfma_f32_16x16x32_bf16 v[136:139], v[166:169], v[202:205], v[136:139]
	v_mfma_f32_16x16x32_bf16 v[124:127], v[68:71], v[210:213], v[124:127]
	v_mfma_f32_16x16x32_bf16 v[120:123], v[166:169], v[210:213], v[120:123]
	v_mfma_f32_16x16x32_bf16 v[108:111], v[68:71], v[218:221], v[108:111]
	v_mfma_f32_16x16x32_bf16 v[104:107], v[166:169], v[218:221], v[104:107]
	v_mfma_f32_16x16x32_bf16 v[92:95], v[68:71], v[226:229], v[92:95]
	v_mfma_f32_16x16x32_bf16 v[88:91], v[166:169], v[226:229], v[88:91]
	s_setprio 0
	s_setprio 1
	v_mfma_f32_16x16x32_bf16 v[132:135], v[170:173], v[198:201], v[132:135]
	v_mfma_f32_16x16x32_bf16 v[128:131], v[190:193], v[198:201], v[128:131]
	v_mfma_f32_16x16x32_bf16 v[116:119], v[170:173], v[206:209], v[116:119]
	v_mfma_f32_16x16x32_bf16 v[112:115], v[190:193], v[206:209], v[112:115]
	v_mfma_f32_16x16x32_bf16 v[100:103], v[170:173], v[214:217], v[100:103]
	v_mfma_f32_16x16x32_bf16 v[96:99], v[190:193], v[214:217], v[96:99]
	v_mfma_f32_16x16x32_bf16 v[84:87], v[170:173], v[222:225], v[84:87]
	v_mfma_f32_16x16x32_bf16 v[80:83], v[190:193], v[222:225], v[80:83]
	v_mfma_f32_16x16x32_bf16 v[132:135], v[174:177], v[202:205], v[132:135]
	v_mfma_f32_16x16x32_bf16 v[128:131], v[194:197], v[202:205], v[128:131]
	v_mfma_f32_16x16x32_bf16 v[116:119], v[174:177], v[210:213], v[116:119]
	v_mfma_f32_16x16x32_bf16 v[112:115], v[194:197], v[210:213], v[112:115]
	v_mfma_f32_16x16x32_bf16 v[100:103], v[174:177], v[218:221], v[100:103]
	v_mfma_f32_16x16x32_bf16 v[96:99], v[194:197], v[218:221], v[96:99]
	v_mfma_f32_16x16x32_bf16 v[84:87], v[174:177], v[226:229], v[84:87]
	v_mfma_f32_16x16x32_bf16 v[80:83], v[194:197], v[226:229], v[80:83]
	s_setprio 0
	s_barrier
	s_add_i32 s14, s38, s20
	v_lshl_add_u64 v[178:179], v[178:179], 0, s[94:95]
	s_mov_b32 m0, s14
	ds_read_b128 v[198:201], v39 offset:49152
	ds_read_b128 v[202:205], v39 offset:50176
	ds_read_b128 v[206:209], v39 offset:51200
	ds_read_b128 v[210:213], v39 offset:52224
	ds_read_b128 v[214:217], v39 offset:53248
	ds_read_b128 v[218:221], v39 offset:54272
	ds_read_b128 v[222:225], v39 offset:55296
	ds_read_b128 v[226:229], v39 offset:56320
	global_load_lds_dwordx4 v[178:179], off
	s_add_i32 m0, s14, 0x2000
	s_add_u32 s2, s2, 0x80080
	v_lshl_add_u64 v[178:179], v[230:231], 0, s[94:95]
	s_addc_u32 s3, s3, 0
	s_add_i32 s14, s39, s20
	global_load_lds_dwordx4 v[178:179], off
	v_lshl_add_u64 v[178:179], s[2:3], 0, v[144:145]
	s_mov_b32 m0, s14
	s_nop 0
	global_load_lds_dwordx4 v[178:179], off
	v_lshl_add_u64 v[178:179], s[2:3], 0, v[28:29]
	s_add_i32 m0, s14, 0x2000
	s_nop 0
	global_load_lds_dwordx4 v[178:179], off
	v_lshl_add_u64 v[178:179], v[232:233], 0, s[94:95]
	s_mov_b32 m0, s29
	s_nop 0
	global_load_lds_dwordx4 v[178:179], off
	v_lshl_add_u64 v[178:179], v[234:235], 0, s[94:95]
	s_mov_b32 m0, s31
	s_nop 0
	global_load_lds_dwordx4 v[178:179], off
	s_waitcnt vmcnt(8)
	s_waitcnt lgkmcnt(0)
	s_barrier
	s_setprio 1
	s_waitcnt lgkmcnt(0)
	v_mfma_f32_16x16x32_bf16 v[76:79], v[64:67], v[198:201], v[76:79]
	v_mfma_f32_16x16x32_bf16 v[72:75], v[162:165], v[198:201], v[72:75]
	v_mfma_f32_16x16x32_bf16 v[60:63], v[64:67], v[206:209], v[60:63]
	v_mfma_f32_16x16x32_bf16 v[56:59], v[162:165], v[206:209], v[56:59]
	v_mfma_f32_16x16x32_bf16 v[32:35], v[64:67], v[214:217], v[32:35]
	v_mfma_f32_16x16x32_bf16 v[24:27], v[162:165], v[214:217], v[24:27]
	v_mfma_f32_16x16x32_bf16 v[12:15], v[64:67], v[222:225], v[12:15]
	v_mfma_f32_16x16x32_bf16 v[8:11], v[162:165], v[222:225], v[8:11]
	v_mfma_f32_16x16x32_bf16 v[76:79], v[68:71], v[202:205], v[76:79]
	v_mfma_f32_16x16x32_bf16 v[72:75], v[166:169], v[202:205], v[72:75]
	v_mfma_f32_16x16x32_bf16 v[60:63], v[68:71], v[210:213], v[60:63]
	v_mfma_f32_16x16x32_bf16 v[56:59], v[166:169], v[210:213], v[56:59]
	v_mfma_f32_16x16x32_bf16 v[32:35], v[68:71], v[218:221], v[32:35]
	v_mfma_f32_16x16x32_bf16 v[24:27], v[166:169], v[218:221], v[24:27]
	v_mfma_f32_16x16x32_bf16 v[12:15], v[68:71], v[226:229], v[12:15]
	v_mfma_f32_16x16x32_bf16 v[8:11], v[166:169], v[226:229], v[8:11]
	s_setprio 0
	s_setprio 1
	v_mfma_f32_16x16x32_bf16 v[40:43], v[170:173], v[198:201], v[40:43]
	v_mfma_f32_16x16x32_bf16 v[68:71], v[174:177], v[202:205], v[40:43]
	v_mfma_f32_16x16x32_bf16 v[40:43], v[190:193], v[198:201], v[48:51]
	v_mfma_f32_16x16x32_bf16 v[64:67], v[194:197], v[202:205], v[40:43]
	v_mfma_f32_16x16x32_bf16 v[40:43], v[170:173], v[206:209], v[52:55]
	v_mfma_f32_16x16x32_bf16 v[52:55], v[174:177], v[210:213], v[40:43]
	v_mfma_f32_16x16x32_bf16 v[40:43], v[190:193], v[206:209], v[44:47]
	v_mfma_f32_16x16x32_bf16 v[20:23], v[170:173], v[214:217], v[20:23]
	v_mfma_f32_16x16x32_bf16 v[16:19], v[190:193], v[214:217], v[16:19]
	v_mfma_f32_16x16x32_bf16 v[4:7], v[170:173], v[222:225], v[4:7]
	v_mfma_f32_16x16x32_bf16 v[0:3], v[190:193], v[222:225], v[0:3]
	v_mfma_f32_16x16x32_bf16 v[44:47], v[194:197], v[210:213], v[40:43]
	v_mfma_f32_16x16x32_bf16 v[20:23], v[174:177], v[218:221], v[20:23]
	v_mfma_f32_16x16x32_bf16 v[16:19], v[194:197], v[218:221], v[16:19]
	v_mfma_f32_16x16x32_bf16 v[4:7], v[174:177], v[226:229], v[4:7]
	v_mfma_f32_16x16x32_bf16 v[0:3], v[194:197], v[226:229], v[0:3]
	s_setprio 0
	s_barrier
	s_add_i32 s37, s37, 2
	s_add_u32 s12, s12, 0x100
	s_addc_u32 s13, s13, 0
	s_cmp_gt_u32 s37, 29
	s_cbranch_scc0 .LBB0_1153
	s_branch .Lq_smp_exit
.Lq_smp_disp:
	s_cmp_eq_u32 s51, 1
	s_cbranch_scc1 .Lq_smp_0_loop
	s_cmp_eq_u32 s51, 2
	s_cbranch_scc1 .Lq_smp_1_loop
	s_cmp_eq_u32 s51, 4
	s_cbranch_scc1 .Lq_smp_2_loop
	s_branch .Lq_smp_3_loop
.Lq_smp_0_loop:
	s_add_u32 s14, s8, 0x100
	s_addc_u32 s15, s9, 0
	s_add_u32 s2, s4, 0x100
	s_addc_u32 s3, s5, 0
	s_waitcnt vmcnt(0)
	s_barrier
	s_barrier
	v_lshl_add_u64 v[178:179], s[14:15], 0, v[144:145]
	s_add_i32 m0, s1, 0x4000
	v_lshl_add_u64 v[230:231], s[14:15], 0, v[28:29]
	global_load_lds_dwordx4 v[178:179], off
	s_add_i32 m0, s1, 0x6000
	v_lshl_add_u64 v[232:233], s[2:3], 0, v[144:145]
	global_load_lds_dwordx4 v[230:231], off
	s_add_i32 m0, s1, 0x14000
	v_lshl_add_u64 v[234:235], s[2:3], 0, v[28:29]
	global_load_lds_dwordx4 v[232:233], off
	s_add_i32 m0, s1, 0x16000
	s_add_u32 s14, s14, 0x80
	s_addc_u32 s15, s15, 0
	global_load_lds_dwordx4 v[234:235], off
	s_add_u32 s2, s2, 0x80
	s_addc_u32 s3, s3, 0
	s_mov_b32 s55, 0
.Lq_smp_0_k:
	v_lshl_add_u64 v[178:179], s[14:15], 0, v[144:145]
	s_add_i32 m0, s1, 0xc000
	v_lshl_add_u64 v[230:231], s[14:15], 0, v[28:29]
	global_load_lds_dwordx4 v[178:179], off
	s_add_i32 m0, s1, 0xe000
	v_lshl_add_u64 v[232:233], s[2:3], 0, v[144:145]
	global_load_lds_dwordx4 v[230:231], off
	s_add_i32 m0, s1, 0x1c000
	v_lshl_add_u64 v[234:235], s[2:3], 0, v[28:29]
	global_load_lds_dwordx4 v[232:233], off
	s_add_i32 m0, s1, 0x1e000
	s_add_u32 s14, s14, 0x80
	s_addc_u32 s15, s15, 0
	global_load_lds_dwordx4 v[234:235], off
	s_add_u32 s2, s2, 0x80
	s_addc_u32 s3, s3, 0
	v_add_u32_e32 v161, 0x10000, v38
	ds_read_b128 v[198:201], v39 offset:0
	ds_read_b128 v[202:205], v39 offset:1024
	ds_read_b128 v[206:209], v39 offset:2048
	ds_read_b128 v[210:213], v39 offset:3072
	ds_read_b128 v[214:217], v39 offset:4096
	ds_read_b128 v[218:221], v39 offset:5120
	ds_read_b128 v[222:225], v39 offset:6144
	ds_read_b128 v[226:229], v39 offset:7168
	ds_read_b128 v[40:43], v161
	ds_read_b128 v[48:51], v161 offset:1024
	ds_read_b128 v[162:165], v161 offset:2048
	ds_read_b128 v[166:169], v161 offset:3072
	s_waitcnt vmcnt(8)
	s_waitcnt lgkmcnt(0)
	s_barrier
	s_setprio 1
	v_mfma_f32_16x16x32_bf16 v[140:143], v[40:43], v[198:201], v[140:143]
	v_mfma_f32_16x16x32_bf16 v[136:139], v[162:165], v[198:201], v[136:139]
	v_mfma_f32_16x16x32_bf16 v[124:127], v[40:43], v[206:209], v[124:127]
	v_mfma_f32_16x16x32_bf16 v[120:123], v[162:165], v[206:209], v[120:123]
	v_mfma_f32_16x16x32_bf16 v[108:111], v[40:43], v[214:217], v[108:111]
	v_mfma_f32_16x16x32_bf16 v[104:107], v[162:165], v[214:217], v[104:107]
	v_mfma_f32_16x16x32_bf16 v[92:95], v[40:43], v[222:225], v[92:95]
	v_mfma_f32_16x16x32_bf16 v[88:91], v[162:165], v[222:225], v[88:91]
	v_mfma_f32_16x16x32_bf16 v[140:143], v[48:51], v[202:205], v[140:143]
	v_mfma_f32_16x16x32_bf16 v[136:139], v[166:169], v[202:205], v[136:139]
	v_mfma_f32_16x16x32_bf16 v[124:127], v[48:51], v[210:213], v[124:127]
	v_mfma_f32_16x16x32_bf16 v[120:123], v[166:169], v[210:213], v[120:123]
	v_mfma_f32_16x16x32_bf16 v[108:111], v[48:51], v[218:221], v[108:111]
	v_mfma_f32_16x16x32_bf16 v[104:107], v[166:169], v[218:221], v[104:107]
	v_mfma_f32_16x16x32_bf16 v[92:95], v[48:51], v[226:229], v[92:95]
	v_mfma_f32_16x16x32_bf16 v[88:91], v[166:169], v[226:229], v[88:91]
	s_setprio 0
	s_barrier
	v_lshl_add_u64 v[178:179], s[14:15], 0, v[144:145]
	s_add_i32 m0, s1, 0x0
	v_lshl_add_u64 v[230:231], s[14:15], 0, v[28:29]
	global_load_lds_dwordx4 v[178:179], off
	s_add_i32 m0, s1, 0x2000
	v_lshl_add_u64 v[232:233], s[2:3], 0, v[144:145]
	global_load_lds_dwordx4 v[230:231], off
	s_add_i32 m0, s1, 0x10000
	v_lshl_add_u64 v[234:235], s[2:3], 0, v[28:29]
	global_load_lds_dwordx4 v[232:233], off
	s_add_i32 m0, s1, 0x12000
	s_add_u32 s14, s14, 0x80
	s_addc_u32 s15, s15, 0
	global_load_lds_dwordx4 v[234:235], off
	s_add_u32 s2, s2, 0x80
	s_addc_u32 s3, s3, 0
	v_add_u32_e32 v161, 0x18000, v38
	ds_read_b128 v[198:201], v39 offset:32768
	ds_read_b128 v[202:205], v39 offset:33792
	ds_read_b128 v[206:209], v39 offset:34816
	ds_read_b128 v[210:213], v39 offset:35840
	ds_read_b128 v[214:217], v39 offset:36864
	ds_read_b128 v[218:221], v39 offset:37888
	ds_read_b128 v[222:225], v39 offset:38912
	ds_read_b128 v[226:229], v39 offset:39936
	ds_read_b128 v[40:43], v161
	ds_read_b128 v[48:51], v161 offset:1024
	ds_read_b128 v[162:165], v161 offset:2048
	ds_read_b128 v[166:169], v161 offset:3072
	s_waitcnt vmcnt(8)
	s_waitcnt lgkmcnt(0)
	s_barrier
	s_setprio 1
	v_mfma_f32_16x16x32_bf16 v[140:143], v[40:43], v[198:201], v[140:143]
	v_mfma_f32_16x16x32_bf16 v[136:139], v[162:165], v[198:201], v[136:139]
	v_mfma_f32_16x16x32_bf16 v[124:127], v[40:43], v[206:209], v[124:127]
	v_mfma_f32_16x16x32_bf16 v[120:123], v[162:165], v[206:209], v[120:123]
	v_mfma_f32_16x16x32_bf16 v[108:111], v[40:43], v[214:217], v[108:111]
	v_mfma_f32_16x16x32_bf16 v[104:107], v[162:165], v[214:217], v[104:107]
	v_mfma_f32_16x16x32_bf16 v[92:95], v[40:43], v[222:225], v[92:95]
	v_mfma_f32_16x16x32_bf16 v[88:91], v[162:165], v[222:225], v[88:91]
	v_mfma_f32_16x16x32_bf16 v[140:143], v[48:51], v[202:205], v[140:143]
	v_mfma_f32_16x16x32_bf16 v[136:139], v[166:169], v[202:205], v[136:139]
	v_mfma_f32_16x16x32_bf16 v[124:127], v[48:51], v[210:213], v[124:127]
	v_mfma_f32_16x16x32_bf16 v[120:123], v[166:169], v[210:213], v[120:123]
	v_mfma_f32_16x16x32_bf16 v[108:111], v[48:51], v[218:221], v[108:111]
	v_mfma_f32_16x16x32_bf16 v[104:107], v[166:169], v[218:221], v[104:107]
	v_mfma_f32_16x16x32_bf16 v[92:95], v[48:51], v[226:229], v[92:95]
	v_mfma_f32_16x16x32_bf16 v[88:91], v[166:169], v[226:229], v[88:91]
	s_setprio 0
	s_barrier
	v_lshl_add_u64 v[178:179], s[14:15], 0, v[144:145]
	s_add_i32 m0, s1, 0x8000
	v_lshl_add_u64 v[230:231], s[14:15], 0, v[28:29]
	global_load_lds_dwordx4 v[178:179], off
	s_add_i32 m0, s1, 0xa000
	v_lshl_add_u64 v[232:233], s[2:3], 0, v[144:145]
	global_load_lds_dwordx4 v[230:231], off
	s_add_i32 m0, s1, 0x18000
	v_lshl_add_u64 v[234:235], s[2:3], 0, v[28:29]
	global_load_lds_dwordx4 v[232:233], off
	s_add_i32 m0, s1, 0x1a000
	s_add_u32 s14, s14, 0x80
	s_addc_u32 s15, s15, 0
	global_load_lds_dwordx4 v[234:235], off
	s_add_u32 s2, s2, 0x80
	s_addc_u32 s3, s3, 0
	v_add_u32_e32 v161, 0x14000, v38
	ds_read_b128 v[198:201], v39 offset:16384
	ds_read_b128 v[202:205], v39 offset:17408
	ds_read_b128 v[206:209], v39 offset:18432
	ds_read_b128 v[210:213], v39 offset:19456
	ds_read_b128 v[214:217], v39 offset:20480
	ds_read_b128 v[218:221], v39 offset:21504
	ds_read_b128 v[222:225], v39 offset:22528
	ds_read_b128 v[226:229], v39 offset:23552
	ds_read_b128 v[40:43], v161
	ds_read_b128 v[48:51], v161 offset:1024
	ds_read_b128 v[162:165], v161 offset:2048
	ds_read_b128 v[166:169], v161 offset:3072
	s_waitcnt vmcnt(8)
	s_waitcnt lgkmcnt(0)
	s_barrier
	s_setprio 1
	v_mfma_f32_16x16x32_bf16 v[140:143], v[40:43], v[198:201], v[140:143]
	v_mfma_f32_16x16x32_bf16 v[136:139], v[162:165], v[198:201], v[136:139]
	v_mfma_f32_16x16x32_bf16 v[124:127], v[40:43], v[206:209], v[124:127]
	v_mfma_f32_16x16x32_bf16 v[120:123], v[162:165], v[206:209], v[120:123]
	v_mfma_f32_16x16x32_bf16 v[108:111], v[40:43], v[214:217], v[108:111]
	v_mfma_f32_16x16x32_bf16 v[104:107], v[162:165], v[214:217], v[104:107]
	v_mfma_f32_16x16x32_bf16 v[92:95], v[40:43], v[222:225], v[92:95]
	v_mfma_f32_16x16x32_bf16 v[88:91], v[162:165], v[222:225], v[88:91]
	v_mfma_f32_16x16x32_bf16 v[140:143], v[48:51], v[202:205], v[140:143]
	v_mfma_f32_16x16x32_bf16 v[136:139], v[166:169], v[202:205], v[136:139]
	v_mfma_f32_16x16x32_bf16 v[124:127], v[48:51], v[210:213], v[124:127]
	v_mfma_f32_16x16x32_bf16 v[120:123], v[166:169], v[210:213], v[120:123]
	v_mfma_f32_16x16x32_bf16 v[108:111], v[48:51], v[218:221], v[108:111]
	v_mfma_f32_16x16x32_bf16 v[104:107], v[166:169], v[218:221], v[104:107]
	v_mfma_f32_16x16x32_bf16 v[92:95], v[48:51], v[226:229], v[92:95]
	v_mfma_f32_16x16x32_bf16 v[88:91], v[166:169], v[226:229], v[88:91]
	s_setprio 0
	s_barrier
	v_lshl_add_u64 v[178:179], s[14:15], 0, v[144:145]
	s_add_i32 m0, s1, 0x4000
	v_lshl_add_u64 v[230:231], s[14:15], 0, v[28:29]
	global_load_lds_dwordx4 v[178:179], off
	s_add_i32 m0, s1, 0x6000
	v_lshl_add_u64 v[232:233], s[2:3], 0, v[144:145]
	global_load_lds_dwordx4 v[230:231], off
	s_add_i32 m0, s1, 0x14000
	v_lshl_add_u64 v[234:235], s[2:3], 0, v[28:29]
	global_load_lds_dwordx4 v[232:233], off
	s_add_i32 m0, s1, 0x16000
	s_add_u32 s14, s14, 0x80
	s_addc_u32 s15, s15, 0
	global_load_lds_dwordx4 v[234:235], off
	s_add_u32 s2, s2, 0x80
	s_addc_u32 s3, s3, 0
	v_add_u32_e32 v161, 0x1c000, v38
	ds_read_b128 v[198:201], v39 offset:49152
	ds_read_b128 v[202:205], v39 offset:50176
	ds_read_b128 v[206:209], v39 offset:51200
	ds_read_b128 v[210:213], v39 offset:52224
	ds_read_b128 v[214:217], v39 offset:53248
	ds_read_b128 v[218:221], v39 offset:54272
	ds_read_b128 v[222:225], v39 offset:55296
	ds_read_b128 v[226:229], v39 offset:56320
	ds_read_b128 v[40:43], v161
	ds_read_b128 v[48:51], v161 offset:1024
	ds_read_b128 v[162:165], v161 offset:2048
	ds_read_b128 v[166:169], v161 offset:3072
	s_waitcnt vmcnt(8)
	s_waitcnt lgkmcnt(0)
	s_barrier
	s_setprio 1
	v_mfma_f32_16x16x32_bf16 v[140:143], v[40:43], v[198:201], v[140:143]
	v_mfma_f32_16x16x32_bf16 v[136:139], v[162:165], v[198:201], v[136:139]
	v_mfma_f32_16x16x32_bf16 v[124:127], v[40:43], v[206:209], v[124:127]
	v_mfma_f32_16x16x32_bf16 v[120:123], v[162:165], v[206:209], v[120:123]
	v_mfma_f32_16x16x32_bf16 v[108:111], v[40:43], v[214:217], v[108:111]
	v_mfma_f32_16x16x32_bf16 v[104:107], v[162:165], v[214:217], v[104:107]
	v_mfma_f32_16x16x32_bf16 v[92:95], v[40:43], v[222:225], v[92:95]
	v_mfma_f32_16x16x32_bf16 v[88:91], v[162:165], v[222:225], v[88:91]
	v_mfma_f32_16x16x32_bf16 v[140:143], v[48:51], v[202:205], v[140:143]
	v_mfma_f32_16x16x32_bf16 v[136:139], v[166:169], v[202:205], v[136:139]
	v_mfma_f32_16x16x32_bf16 v[124:127], v[48:51], v[210:213], v[124:127]
	v_mfma_f32_16x16x32_bf16 v[120:123], v[166:169], v[210:213], v[120:123]
	v_mfma_f32_16x16x32_bf16 v[108:111], v[48:51], v[218:221], v[108:111]
	v_mfma_f32_16x16x32_bf16 v[104:107], v[166:169], v[218:221], v[104:107]
	v_mfma_f32_16x16x32_bf16 v[92:95], v[48:51], v[226:229], v[92:95]
	v_mfma_f32_16x16x32_bf16 v[88:91], v[166:169], v[226:229], v[88:91]
	s_setprio 0
	s_barrier
	s_add_i32 s55, s55, 1
	s_cmp_lt_u32 s55, 7
	s_cbranch_scc1 .Lq_smp_0_k
	v_lshl_add_u64 v[178:179], s[14:15], 0, v[144:145]
	s_add_i32 m0, s1, 0xc000
	v_lshl_add_u64 v[230:231], s[14:15], 0, v[28:29]
	global_load_lds_dwordx4 v[178:179], off
	s_add_i32 m0, s1, 0xe000
	v_lshl_add_u64 v[232:233], s[2:3], 0, v[144:145]
	global_load_lds_dwordx4 v[230:231], off
	s_add_i32 m0, s1, 0x1c000
	v_lshl_add_u64 v[234:235], s[2:3], 0, v[28:29]
	global_load_lds_dwordx4 v[232:233], off
	s_add_i32 m0, s1, 0x1e000
	s_add_u32 s14, s14, 0x80
	s_addc_u32 s15, s15, 0
	global_load_lds_dwordx4 v[234:235], off
	s_add_u32 s2, s2, 0x80
	s_addc_u32 s3, s3, 0
	v_add_u32_e32 v161, 0x10000, v38
	ds_read_b128 v[198:201], v39 offset:0
	ds_read_b128 v[202:205], v39 offset:1024
	ds_read_b128 v[206:209], v39 offset:2048
	ds_read_b128 v[210:213], v39 offset:3072
	ds_read_b128 v[214:217], v39 offset:4096
	ds_read_b128 v[218:221], v39 offset:5120
	ds_read_b128 v[222:225], v39 offset:6144
	ds_read_b128 v[226:229], v39 offset:7168
	ds_read_b128 v[40:43], v161
	ds_read_b128 v[48:51], v161 offset:1024
	ds_read_b128 v[162:165], v161 offset:2048
	ds_read_b128 v[166:169], v161 offset:3072
	s_waitcnt vmcnt(8)
	s_waitcnt lgkmcnt(0)
	s_barrier
	s_setprio 1
	v_mfma_f32_16x16x32_bf16 v[140:143], v[40:43], v[198:201], v[140:143]
	v_mfma_f32_16x16x32_bf16 v[136:139], v[162:165], v[198:201], v[136:139]
	v_mfma_f32_16x16x32_bf16 v[124:127], v[40:43], v[206:209], v[124:127]
	v_mfma_f32_16x16x32_bf16 v[120:123], v[162:165], v[206:209], v[120:123]
	v_mfma_f32_16x16x32_bf16 v[108:111], v[40:43], v[214:217], v[108:111]
	v_mfma_f32_16x16x32_bf16 v[104:107], v[162:165], v[214:217], v[104:107]
	v_mfma_f32_16x16x32_bf16 v[92:95], v[40:43], v[222:225], v[92:95]
	v_mfma_f32_16x16x32_bf16 v[88:91], v[162:165], v[222:225], v[88:91]
	v_mfma_f32_16x16x32_bf16 v[140:143], v[48:51], v[202:205], v[140:143]
	v_mfma_f32_16x16x32_bf16 v[136:139], v[166:169], v[202:205], v[136:139]
	v_mfma_f32_16x16x32_bf16 v[124:127], v[48:51], v[210:213], v[124:127]
	v_mfma_f32_16x16x32_bf16 v[120:123], v[166:169], v[210:213], v[120:123]
	v_mfma_f32_16x16x32_bf16 v[108:111], v[48:51], v[218:221], v[108:111]
	v_mfma_f32_16x16x32_bf16 v[104:107], v[166:169], v[218:221], v[104:107]
	v_mfma_f32_16x16x32_bf16 v[92:95], v[48:51], v[226:229], v[92:95]
	v_mfma_f32_16x16x32_bf16 v[88:91], v[166:169], v[226:229], v[88:91]
	s_setprio 0
	s_barrier
	v_add_u32_e32 v161, 0x18000, v38
	ds_read_b128 v[198:201], v39 offset:32768
	ds_read_b128 v[202:205], v39 offset:33792
	ds_read_b128 v[206:209], v39 offset:34816
	ds_read_b128 v[210:213], v39 offset:35840
	ds_read_b128 v[214:217], v39 offset:36864
	ds_read_b128 v[218:221], v39 offset:37888
	ds_read_b128 v[222:225], v39 offset:38912
	ds_read_b128 v[226:229], v39 offset:39936
	ds_read_b128 v[40:43], v161
	ds_read_b128 v[48:51], v161 offset:1024
	ds_read_b128 v[162:165], v161 offset:2048
	ds_read_b128 v[166:169], v161 offset:3072
	s_waitcnt vmcnt(4)
	s_waitcnt lgkmcnt(0)
	s_barrier
	s_setprio 1
	v_mfma_f32_16x16x32_bf16 v[140:143], v[40:43], v[198:201], v[140:143]
	v_mfma_f32_16x16x32_bf16 v[136:139], v[162:165], v[198:201], v[136:139]
	v_mfma_f32_16x16x32_bf16 v[124:127], v[40:43], v[206:209], v[124:127]
	v_mfma_f32_16x16x32_bf16 v[120:123], v[162:165], v[206:209], v[120:123]
	v_mfma_f32_16x16x32_bf16 v[108:111], v[40:43], v[214:217], v[108:111]
	v_mfma_f32_16x16x32_bf16 v[104:107], v[162:165], v[214:217], v[104:107]
	v_mfma_f32_16x16x32_bf16 v[92:95], v[40:43], v[222:225], v[92:95]
	v_mfma_f32_16x16x32_bf16 v[88:91], v[162:165], v[222:225], v[88:91]
	v_mfma_f32_16x16x32_bf16 v[140:143], v[48:51], v[202:205], v[140:143]
	v_mfma_f32_16x16x32_bf16 v[136:139], v[166:169], v[202:205], v[136:139]
	v_mfma_f32_16x16x32_bf16 v[124:127], v[48:51], v[210:213], v[124:127]
	v_mfma_f32_16x16x32_bf16 v[120:123], v[166:169], v[210:213], v[120:123]
	v_mfma_f32_16x16x32_bf16 v[108:111], v[48:51], v[218:221], v[108:111]
	v_mfma_f32_16x16x32_bf16 v[104:107], v[166:169], v[218:221], v[104:107]
	v_mfma_f32_16x16x32_bf16 v[92:95], v[48:51], v[226:229], v[92:95]
	v_mfma_f32_16x16x32_bf16 v[88:91], v[166:169], v[226:229], v[88:91]
	s_setprio 0
	s_barrier
	v_add_u32_e32 v161, 0x14000, v38
	ds_read_b128 v[198:201], v39 offset:16384
	ds_read_b128 v[202:205], v39 offset:17408
	ds_read_b128 v[206:209], v39 offset:18432
	ds_read_b128 v[210:213], v39 offset:19456
	ds_read_b128 v[214:217], v39 offset:20480
	ds_read_b128 v[218:221], v39 offset:21504
	ds_read_b128 v[222:225], v39 offset:22528
	ds_read_b128 v[226:229], v39 offset:23552
	ds_read_b128 v[40:43], v161
	ds_read_b128 v[48:51], v161 offset:1024
	ds_read_b128 v[162:165], v161 offset:2048
	ds_read_b128 v[166:169], v161 offset:3072
	s_waitcnt vmcnt(0)
	s_waitcnt lgkmcnt(0)
	s_barrier
	s_setprio 1
	v_mfma_f32_16x16x32_bf16 v[140:143], v[40:43], v[198:201], v[140:143]
	v_mfma_f32_16x16x32_bf16 v[136:139], v[162:165], v[198:201], v[136:139]
	v_mfma_f32_16x16x32_bf16 v[124:127], v[40:43], v[206:209], v[124:127]
	v_mfma_f32_16x16x32_bf16 v[120:123], v[162:165], v[206:209], v[120:123]
	v_mfma_f32_16x16x32_bf16 v[108:111], v[40:43], v[214:217], v[108:111]
	v_mfma_f32_16x16x32_bf16 v[104:107], v[162:165], v[214:217], v[104:107]
	v_mfma_f32_16x16x32_bf16 v[92:95], v[40:43], v[222:225], v[92:95]
	v_mfma_f32_16x16x32_bf16 v[88:91], v[162:165], v[222:225], v[88:91]
	v_mfma_f32_16x16x32_bf16 v[140:143], v[48:51], v[202:205], v[140:143]
	v_mfma_f32_16x16x32_bf16 v[136:139], v[166:169], v[202:205], v[136:139]
	v_mfma_f32_16x16x32_bf16 v[124:127], v[48:51], v[210:213], v[124:127]
	v_mfma_f32_16x16x32_bf16 v[120:123], v[166:169], v[210:213], v[120:123]
	v_mfma_f32_16x16x32_bf16 v[108:111], v[48:51], v[218:221], v[108:111]
	v_mfma_f32_16x16x32_bf16 v[104:107], v[166:169], v[218:221], v[104:107]
	v_mfma_f32_16x16x32_bf16 v[92:95], v[48:51], v[226:229], v[92:95]
	v_mfma_f32_16x16x32_bf16 v[88:91], v[166:169], v[226:229], v[88:91]
	s_setprio 0
	s_barrier
	v_add_u32_e32 v161, 0x1c000, v38
	ds_read_b128 v[198:201], v39 offset:49152
	ds_read_b128 v[202:205], v39 offset:50176
	ds_read_b128 v[206:209], v39 offset:51200
	ds_read_b128 v[210:213], v39 offset:52224
	ds_read_b128 v[214:217], v39 offset:53248
	ds_read_b128 v[218:221], v39 offset:54272
	ds_read_b128 v[222:225], v39 offset:55296
	ds_read_b128 v[226:229], v39 offset:56320
	ds_read_b128 v[40:43], v161
	ds_read_b128 v[48:51], v161 offset:1024
	ds_read_b128 v[162:165], v161 offset:2048
	ds_read_b128 v[166:169], v161 offset:3072
	s_waitcnt lgkmcnt(0)
	s_barrier
	s_setprio 1
	v_mfma_f32_16x16x32_bf16 v[140:143], v[40:43], v[198:201], v[140:143]
	v_mfma_f32_16x16x32_bf16 v[136:139], v[162:165], v[198:201], v[136:139]
	v_mfma_f32_16x16x32_bf16 v[124:127], v[40:43], v[206:209], v[124:127]
	v_mfma_f32_16x16x32_bf16 v[120:123], v[162:165], v[206:209], v[120:123]
	v_mfma_f32_16x16x32_bf16 v[108:111], v[40:43], v[214:217], v[108:111]
	v_mfma_f32_16x16x32_bf16 v[104:107], v[162:165], v[214:217], v[104:107]
	v_mfma_f32_16x16x32_bf16 v[92:95], v[40:43], v[222:225], v[92:95]
	v_mfma_f32_16x16x32_bf16 v[88:91], v[162:165], v[222:225], v[88:91]
	v_mfma_f32_16x16x32_bf16 v[140:143], v[48:51], v[202:205], v[140:143]
	v_mfma_f32_16x16x32_bf16 v[136:139], v[166:169], v[202:205], v[136:139]
	v_mfma_f32_16x16x32_bf16 v[124:127], v[48:51], v[210:213], v[124:127]
	v_mfma_f32_16x16x32_bf16 v[120:123], v[166:169], v[210:213], v[120:123]
	v_mfma_f32_16x16x32_bf16 v[108:111], v[48:51], v[218:221], v[108:111]
	v_mfma_f32_16x16x32_bf16 v[104:107], v[166:169], v[218:221], v[104:107]
	v_mfma_f32_16x16x32_bf16 v[92:95], v[48:51], v[226:229], v[92:95]
	v_mfma_f32_16x16x32_bf16 v[88:91], v[166:169], v[226:229], v[88:91]
	s_setprio 0
	s_barrier
	s_branch .Lq_smp_exit
.Lq_smp_1_loop:
	s_add_u32 s14, s8, 0x100
	s_addc_u32 s15, s9, 0
	s_add_u32 s2, s4, 0x80100
	s_addc_u32 s3, s5, 0
	s_waitcnt vmcnt(0)
	s_barrier
	s_barrier
	v_lshl_add_u64 v[178:179], s[14:15], 0, v[144:145]
	s_add_i32 m0, s1, 0x4000
	v_lshl_add_u64 v[230:231], s[14:15], 0, v[28:29]
	global_load_lds_dwordx4 v[178:179], off
	s_add_i32 m0, s1, 0x6000
	v_lshl_add_u64 v[232:233], s[2:3], 0, v[144:145]
	global_load_lds_dwordx4 v[230:231], off
	s_add_i32 m0, s1, 0x10000
	v_lshl_add_u64 v[234:235], s[2:3], 0, v[28:29]
	global_load_lds_dwordx4 v[232:233], off
	s_add_i32 m0, s1, 0x12000
	s_add_u32 s14, s14, 0x80
	s_addc_u32 s15, s15, 0
	global_load_lds_dwordx4 v[234:235], off
	s_add_u32 s2, s2, 0x80
	s_addc_u32 s3, s3, 0
	s_mov_b32 s55, 0
.Lq_smp_1_k:
	v_lshl_add_u64 v[178:179], s[14:15], 0, v[144:145]
	s_add_i32 m0, s1, 0xc000
	v_lshl_add_u64 v[230:231], s[14:15], 0, v[28:29]
	global_load_lds_dwordx4 v[178:179], off
	s_add_i32 m0, s1, 0xe000
	v_lshl_add_u64 v[232:233], s[2:3], 0, v[144:145]
	global_load_lds_dwordx4 v[230:231], off
	s_add_i32 m0, s1, 0x18000
	v_lshl_add_u64 v[234:235], s[2:3], 0, v[28:29]
	global_load_lds_dwordx4 v[232:233], off
	s_add_i32 m0, s1, 0x1a000
	s_add_u32 s14, s14, 0x80
	s_addc_u32 s15, s15, 0
	global_load_lds_dwordx4 v[234:235], off
	s_add_u32 s2, s2, 0x80
	s_addc_u32 s3, s3, 0
	v_add_u32_e32 v161, 0x14000, v38
	ds_read_b128 v[198:201], v39 offset:0
	ds_read_b128 v[202:205], v39 offset:1024
	ds_read_b128 v[206:209], v39 offset:2048
	ds_read_b128 v[210:213], v39 offset:3072
	ds_read_b128 v[214:217], v39 offset:4096
	ds_read_b128 v[218:221], v39 offset:5120
	ds_read_b128 v[222:225], v39 offset:6144
	ds_read_b128 v[226:229], v39 offset:7168
	ds_read_b128 v[170:173], v161
	ds_read_b128 v[174:177], v161 offset:1024
	ds_read_b128 v[190:193], v161 offset:2048
	ds_read_b128 v[194:197], v161 offset:3072
	s_waitcnt vmcnt(8)
	s_waitcnt lgkmcnt(0)
	s_barrier
	s_setprio 1
	v_mfma_f32_16x16x32_bf16 v[132:135], v[170:173], v[198:201], v[132:135]
	v_mfma_f32_16x16x32_bf16 v[128:131], v[190:193], v[198:201], v[128:131]
	v_mfma_f32_16x16x32_bf16 v[116:119], v[170:173], v[206:209], v[116:119]
	v_mfma_f32_16x16x32_bf16 v[112:115], v[190:193], v[206:209], v[112:115]
	v_mfma_f32_16x16x32_bf16 v[100:103], v[170:173], v[214:217], v[100:103]
	v_mfma_f32_16x16x32_bf16 v[96:99], v[190:193], v[214:217], v[96:99]
	v_mfma_f32_16x16x32_bf16 v[84:87], v[170:173], v[222:225], v[84:87]
	v_mfma_f32_16x16x32_bf16 v[80:83], v[190:193], v[222:225], v[80:83]
	v_mfma_f32_16x16x32_bf16 v[132:135], v[174:177], v[202:205], v[132:135]
	v_mfma_f32_16x16x32_bf16 v[128:131], v[194:197], v[202:205], v[128:131]
	v_mfma_f32_16x16x32_bf16 v[116:119], v[174:177], v[210:213], v[116:119]
	v_mfma_f32_16x16x32_bf16 v[112:115], v[194:197], v[210:213], v[112:115]
	v_mfma_f32_16x16x32_bf16 v[100:103], v[174:177], v[218:221], v[100:103]
	v_mfma_f32_16x16x32_bf16 v[96:99], v[194:197], v[218:221], v[96:99]
	v_mfma_f32_16x16x32_bf16 v[84:87], v[174:177], v[226:229], v[84:87]
	v_mfma_f32_16x16x32_bf16 v[80:83], v[194:197], v[226:229], v[80:83]
	s_setprio 0
	s_barrier
	v_lshl_add_u64 v[178:179], s[14:15], 0, v[144:145]
	s_add_i32 m0, s1, 0x0
	v_lshl_add_u64 v[230:231], s[14:15], 0, v[28:29]
	global_load_lds_dwordx4 v[178:179], off
	s_add_i32 m0, s1, 0x2000
	v_lshl_add_u64 v[232:233], s[2:3], 0, v[144:145]
	global_load_lds_dwordx4 v[230:231], off
	s_add_i32 m0, s1, 0x14000
	v_lshl_add_u64 v[234:235], s[2:3], 0, v[28:29]
	global_load_lds_dwordx4 v[232:233], off
	s_add_i32 m0, s1, 0x16000
	s_add_u32 s14, s14, 0x80
	s_addc_u32 s15, s15, 0
	global_load_lds_dwordx4 v[234:235], off
	s_add_u32 s2, s2, 0x80
	s_addc_u32 s3, s3, 0
	v_add_u32_e32 v161, 0x1c000, v38
	ds_read_b128 v[198:201], v39 offset:32768
	ds_read_b128 v[202:205], v39 offset:33792
	ds_read_b128 v[206:209], v39 offset:34816
	ds_read_b128 v[210:213], v39 offset:35840
	ds_read_b128 v[214:217], v39 offset:36864
	ds_read_b128 v[218:221], v39 offset:37888
	ds_read_b128 v[222:225], v39 offset:38912
	ds_read_b128 v[226:229], v39 offset:39936
	ds_read_b128 v[170:173], v161
	ds_read_b128 v[174:177], v161 offset:1024
	ds_read_b128 v[190:193], v161 offset:2048
	ds_read_b128 v[194:197], v161 offset:3072
	s_waitcnt vmcnt(8)
	s_waitcnt lgkmcnt(0)
	s_barrier
	s_setprio 1
	v_mfma_f32_16x16x32_bf16 v[132:135], v[170:173], v[198:201], v[132:135]
	v_mfma_f32_16x16x32_bf16 v[128:131], v[190:193], v[198:201], v[128:131]
	v_mfma_f32_16x16x32_bf16 v[116:119], v[170:173], v[206:209], v[116:119]
	v_mfma_f32_16x16x32_bf16 v[112:115], v[190:193], v[206:209], v[112:115]
	v_mfma_f32_16x16x32_bf16 v[100:103], v[170:173], v[214:217], v[100:103]
	v_mfma_f32_16x16x32_bf16 v[96:99], v[190:193], v[214:217], v[96:99]
	v_mfma_f32_16x16x32_bf16 v[84:87], v[170:173], v[222:225], v[84:87]
	v_mfma_f32_16x16x32_bf16 v[80:83], v[190:193], v[222:225], v[80:83]
	v_mfma_f32_16x16x32_bf16 v[132:135], v[174:177], v[202:205], v[132:135]
	v_mfma_f32_16x16x32_bf16 v[128:131], v[194:197], v[202:205], v[128:131]
	v_mfma_f32_16x16x32_bf16 v[116:119], v[174:177], v[210:213], v[116:119]
	v_mfma_f32_16x16x32_bf16 v[112:115], v[194:197], v[210:213], v[112:115]
	v_mfma_f32_16x16x32_bf16 v[100:103], v[174:177], v[218:221], v[100:103]
	v_mfma_f32_16x16x32_bf16 v[96:99], v[194:197], v[218:221], v[96:99]
	v_mfma_f32_16x16x32_bf16 v[84:87], v[174:177], v[226:229], v[84:87]
	v_mfma_f32_16x16x32_bf16 v[80:83], v[194:197], v[226:229], v[80:83]
	s_setprio 0
	s_barrier
	v_lshl_add_u64 v[178:179], s[14:15], 0, v[144:145]
	s_add_i32 m0, s1, 0x8000
	v_lshl_add_u64 v[230:231], s[14:15], 0, v[28:29]
	global_load_lds_dwordx4 v[178:179], off
	s_add_i32 m0, s1, 0xa000
	v_lshl_add_u64 v[232:233], s[2:3], 0, v[144:145]
	global_load_lds_dwordx4 v[230:231], off
	s_add_i32 m0, s1, 0x1c000
	v_lshl_add_u64 v[234:235], s[2:3], 0, v[28:29]
	global_load_lds_dwordx4 v[232:233], off
	s_add_i32 m0, s1, 0x1e000
	s_add_u32 s14, s14, 0x80
	s_addc_u32 s15, s15, 0
	global_load_lds_dwordx4 v[234:235], off
	s_add_u32 s2, s2, 0x80
	s_addc_u32 s3, s3, 0
	v_add_u32_e32 v161, 0x10000, v38
	ds_read_b128 v[198:201], v39 offset:16384
	ds_read_b128 v[202:205], v39 offset:17408
	ds_read_b128 v[206:209], v39 offset:18432
	ds_read_b128 v[210:213], v39 offset:19456
	ds_read_b128 v[214:217], v39 offset:20480
	ds_read_b128 v[218:221], v39 offset:21504
	ds_read_b128 v[222:225], v39 offset:22528
	ds_read_b128 v[226:229], v39 offset:23552
	ds_read_b128 v[170:173], v161
	ds_read_b128 v[174:177], v161 offset:1024
	ds_read_b128 v[190:193], v161 offset:2048
	ds_read_b128 v[194:197], v161 offset:3072
	s_waitcnt vmcnt(8)
	s_waitcnt lgkmcnt(0)
	s_barrier
	s_setprio 1
	v_mfma_f32_16x16x32_bf16 v[132:135], v[170:173], v[198:201], v[132:135]
	v_mfma_f32_16x16x32_bf16 v[128:131], v[190:193], v[198:201], v[128:131]
	v_mfma_f32_16x16x32_bf16 v[116:119], v[170:173], v[206:209], v[116:119]
	v_mfma_f32_16x16x32_bf16 v[112:115], v[190:193], v[206:209], v[112:115]
	v_mfma_f32_16x16x32_bf16 v[100:103], v[170:173], v[214:217], v[100:103]
	v_mfma_f32_16x16x32_bf16 v[96:99], v[190:193], v[214:217], v[96:99]
	v_mfma_f32_16x16x32_bf16 v[84:87], v[170:173], v[222:225], v[84:87]
	v_mfma_f32_16x16x32_bf16 v[80:83], v[190:193], v[222:225], v[80:83]
	v_mfma_f32_16x16x32_bf16 v[132:135], v[174:177], v[202:205], v[132:135]
	v_mfma_f32_16x16x32_bf16 v[128:131], v[194:197], v[202:205], v[128:131]
	v_mfma_f32_16x16x32_bf16 v[116:119], v[174:177], v[210:213], v[116:119]
	v_mfma_f32_16x16x32_bf16 v[112:115], v[194:197], v[210:213], v[112:115]
	v_mfma_f32_16x16x32_bf16 v[100:103], v[174:177], v[218:221], v[100:103]
	v_mfma_f32_16x16x32_bf16 v[96:99], v[194:197], v[218:221], v[96:99]
	v_mfma_f32_16x16x32_bf16 v[84:87], v[174:177], v[226:229], v[84:87]
	v_mfma_f32_16x16x32_bf16 v[80:83], v[194:197], v[226:229], v[80:83]
	s_setprio 0
	s_barrier
	v_lshl_add_u64 v[178:179], s[14:15], 0, v[144:145]
	s_add_i32 m0, s1, 0x4000
	v_lshl_add_u64 v[230:231], s[14:15], 0, v[28:29]
	global_load_lds_dwordx4 v[178:179], off
	s_add_i32 m0, s1, 0x6000
	v_lshl_add_u64 v[232:233], s[2:3], 0, v[144:145]
	global_load_lds_dwordx4 v[230:231], off
	s_add_i32 m0, s1, 0x10000
	v_lshl_add_u64 v[234:235], s[2:3], 0, v[28:29]
	global_load_lds_dwordx4 v[232:233], off
	s_add_i32 m0, s1, 0x12000
	s_add_u32 s14, s14, 0x80
	s_addc_u32 s15, s15, 0
	global_load_lds_dwordx4 v[234:235], off
	s_add_u32 s2, s2, 0x80
	s_addc_u32 s3, s3, 0
	v_add_u32_e32 v161, 0x18000, v38
	ds_read_b128 v[198:201], v39 offset:49152
	ds_read_b128 v[202:205], v39 offset:50176
	ds_read_b128 v[206:209], v39 offset:51200
	ds_read_b128 v[210:213], v39 offset:52224
	ds_read_b128 v[214:217], v39 offset:53248
	ds_read_b128 v[218:221], v39 offset:54272
	ds_read_b128 v[222:225], v39 offset:55296
	ds_read_b128 v[226:229], v39 offset:56320
	ds_read_b128 v[170:173], v161
	ds_read_b128 v[174:177], v161 offset:1024
	ds_read_b128 v[190:193], v161 offset:2048
	ds_read_b128 v[194:197], v161 offset:3072
	s_waitcnt vmcnt(8)
	s_waitcnt lgkmcnt(0)
	s_barrier
	s_setprio 1
	v_mfma_f32_16x16x32_bf16 v[132:135], v[170:173], v[198:201], v[132:135]
	v_mfma_f32_16x16x32_bf16 v[128:131], v[190:193], v[198:201], v[128:131]
	v_mfma_f32_16x16x32_bf16 v[116:119], v[170:173], v[206:209], v[116:119]
	v_mfma_f32_16x16x32_bf16 v[112:115], v[190:193], v[206:209], v[112:115]
	v_mfma_f32_16x16x32_bf16 v[100:103], v[170:173], v[214:217], v[100:103]
	v_mfma_f32_16x16x32_bf16 v[96:99], v[190:193], v[214:217], v[96:99]
	v_mfma_f32_16x16x32_bf16 v[84:87], v[170:173], v[222:225], v[84:87]
	v_mfma_f32_16x16x32_bf16 v[80:83], v[190:193], v[222:225], v[80:83]
	v_mfma_f32_16x16x32_bf16 v[132:135], v[174:177], v[202:205], v[132:135]
	v_mfma_f32_16x16x32_bf16 v[128:131], v[194:197], v[202:205], v[128:131]
	v_mfma_f32_16x16x32_bf16 v[116:119], v[174:177], v[210:213], v[116:119]
	v_mfma_f32_16x16x32_bf16 v[112:115], v[194:197], v[210:213], v[112:115]
	v_mfma_f32_16x16x32_bf16 v[100:103], v[174:177], v[218:221], v[100:103]
	v_mfma_f32_16x16x32_bf16 v[96:99], v[194:197], v[218:221], v[96:99]
	v_mfma_f32_16x16x32_bf16 v[84:87], v[174:177], v[226:229], v[84:87]
	v_mfma_f32_16x16x32_bf16 v[80:83], v[194:197], v[226:229], v[80:83]
	s_setprio 0
	s_barrier
	s_add_i32 s55, s55, 1
	s_cmp_lt_u32 s55, 7
	s_cbranch_scc1 .Lq_smp_1_k
	v_lshl_add_u64 v[178:179], s[14:15], 0, v[144:145]
	s_add_i32 m0, s1, 0xc000
	v_lshl_add_u64 v[230:231], s[14:15], 0, v[28:29]
	global_load_lds_dwordx4 v[178:179], off
	s_add_i32 m0, s1, 0xe000
	v_lshl_add_u64 v[232:233], s[2:3], 0, v[144:145]
	global_load_lds_dwordx4 v[230:231], off
	s_add_i32 m0, s1, 0x18000
	v_lshl_add_u64 v[234:235], s[2:3], 0, v[28:29]
	global_load_lds_dwordx4 v[232:233], off
	s_add_i32 m0, s1, 0x1a000
	s_add_u32 s14, s14, 0x80
	s_addc_u32 s15, s15, 0
	global_load_lds_dwordx4 v[234:235], off
	s_add_u32 s2, s2, 0x80
	s_addc_u32 s3, s3, 0
	v_add_u32_e32 v161, 0x14000, v38
	ds_read_b128 v[198:201], v39 offset:0
	ds_read_b128 v[202:205], v39 offset:1024
	ds_read_b128 v[206:209], v39 offset:2048
	ds_read_b128 v[210:213], v39 offset:3072
	ds_read_b128 v[214:217], v39 offset:4096
	ds_read_b128 v[218:221], v39 offset:5120
	ds_read_b128 v[222:225], v39 offset:6144
	ds_read_b128 v[226:229], v39 offset:7168
	ds_read_b128 v[170:173], v161
	ds_read_b128 v[174:177], v161 offset:1024
	ds_read_b128 v[190:193], v161 offset:2048
	ds_read_b128 v[194:197], v161 offset:3072
	s_waitcnt vmcnt(8)
	s_waitcnt lgkmcnt(0)
	s_barrier
	s_setprio 1
	v_mfma_f32_16x16x32_bf16 v[132:135], v[170:173], v[198:201], v[132:135]
	v_mfma_f32_16x16x32_bf16 v[128:131], v[190:193], v[198:201], v[128:131]
	v_mfma_f32_16x16x32_bf16 v[116:119], v[170:173], v[206:209], v[116:119]
	v_mfma_f32_16x16x32_bf16 v[112:115], v[190:193], v[206:209], v[112:115]
	v_mfma_f32_16x16x32_bf16 v[100:103], v[170:173], v[214:217], v[100:103]
	v_mfma_f32_16x16x32_bf16 v[96:99], v[190:193], v[214:217], v[96:99]
	v_mfma_f32_16x16x32_bf16 v[84:87], v[170:173], v[222:225], v[84:87]
	v_mfma_f32_16x16x32_bf16 v[80:83], v[190:193], v[222:225], v[80:83]
	v_mfma_f32_16x16x32_bf16 v[132:135], v[174:177], v[202:205], v[132:135]
	v_mfma_f32_16x16x32_bf16 v[128:131], v[194:197], v[202:205], v[128:131]
	v_mfma_f32_16x16x32_bf16 v[116:119], v[174:177], v[210:213], v[116:119]
	v_mfma_f32_16x16x32_bf16 v[112:115], v[194:197], v[210:213], v[112:115]
	v_mfma_f32_16x16x32_bf16 v[100:103], v[174:177], v[218:221], v[100:103]
	v_mfma_f32_16x16x32_bf16 v[96:99], v[194:197], v[218:221], v[96:99]
	v_mfma_f32_16x16x32_bf16 v[84:87], v[174:177], v[226:229], v[84:87]
	v_mfma_f32_16x16x32_bf16 v[80:83], v[194:197], v[226:229], v[80:83]
	s_setprio 0
	s_barrier
	v_add_u32_e32 v161, 0x1c000, v38
	ds_read_b128 v[198:201], v39 offset:32768
	ds_read_b128 v[202:205], v39 offset:33792
	ds_read_b128 v[206:209], v39 offset:34816
	ds_read_b128 v[210:213], v39 offset:35840
	ds_read_b128 v[214:217], v39 offset:36864
	ds_read_b128 v[218:221], v39 offset:37888
	ds_read_b128 v[222:225], v39 offset:38912
	ds_read_b128 v[226:229], v39 offset:39936
	ds_read_b128 v[170:173], v161
	ds_read_b128 v[174:177], v161 offset:1024
	ds_read_b128 v[190:193], v161 offset:2048
	ds_read_b128 v[194:197], v161 offset:3072
	s_waitcnt vmcnt(4)
	s_waitcnt lgkmcnt(0)
	s_barrier
	s_setprio 1
	v_mfma_f32_16x16x32_bf16 v[132:135], v[170:173], v[198:201], v[132:135]
	v_mfma_f32_16x16x32_bf16 v[128:131], v[190:193], v[198:201], v[128:131]
	v_mfma_f32_16x16x32_bf16 v[116:119], v[170:173], v[206:209], v[116:119]
	v_mfma_f32_16x16x32_bf16 v[112:115], v[190:193], v[206:209], v[112:115]
	v_mfma_f32_16x16x32_bf16 v[100:103], v[170:173], v[214:217], v[100:103]
	v_mfma_f32_16x16x32_bf16 v[96:99], v[190:193], v[214:217], v[96:99]
	v_mfma_f32_16x16x32_bf16 v[84:87], v[170:173], v[222:225], v[84:87]
	v_mfma_f32_16x16x32_bf16 v[80:83], v[190:193], v[222:225], v[80:83]
	v_mfma_f32_16x16x32_bf16 v[132:135], v[174:177], v[202:205], v[132:135]
	v_mfma_f32_16x16x32_bf16 v[128:131], v[194:197], v[202:205], v[128:131]
	v_mfma_f32_16x16x32_bf16 v[116:119], v[174:177], v[210:213], v[116:119]
	v_mfma_f32_16x16x32_bf16 v[112:115], v[194:197], v[210:213], v[112:115]
	v_mfma_f32_16x16x32_bf16 v[100:103], v[174:177], v[218:221], v[100:103]
	v_mfma_f32_16x16x32_bf16 v[96:99], v[194:197], v[218:221], v[96:99]
	v_mfma_f32_16x16x32_bf16 v[84:87], v[174:177], v[226:229], v[84:87]
	v_mfma_f32_16x16x32_bf16 v[80:83], v[194:197], v[226:229], v[80:83]
	s_setprio 0
	s_barrier
	v_add_u32_e32 v161, 0x10000, v38
	ds_read_b128 v[198:201], v39 offset:16384
	ds_read_b128 v[202:205], v39 offset:17408
	ds_read_b128 v[206:209], v39 offset:18432
	ds_read_b128 v[210:213], v39 offset:19456
	ds_read_b128 v[214:217], v39 offset:20480
	ds_read_b128 v[218:221], v39 offset:21504
	ds_read_b128 v[222:225], v39 offset:22528
	ds_read_b128 v[226:229], v39 offset:23552
	ds_read_b128 v[170:173], v161
	ds_read_b128 v[174:177], v161 offset:1024
	ds_read_b128 v[190:193], v161 offset:2048
	ds_read_b128 v[194:197], v161 offset:3072
	s_waitcnt vmcnt(0)
	s_waitcnt lgkmcnt(0)
	s_barrier
	s_setprio 1
	v_mfma_f32_16x16x32_bf16 v[132:135], v[170:173], v[198:201], v[132:135]
	v_mfma_f32_16x16x32_bf16 v[128:131], v[190:193], v[198:201], v[128:131]
	v_mfma_f32_16x16x32_bf16 v[116:119], v[170:173], v[206:209], v[116:119]
	v_mfma_f32_16x16x32_bf16 v[112:115], v[190:193], v[206:209], v[112:115]
	v_mfma_f32_16x16x32_bf16 v[100:103], v[170:173], v[214:217], v[100:103]
	v_mfma_f32_16x16x32_bf16 v[96:99], v[190:193], v[214:217], v[96:99]
	v_mfma_f32_16x16x32_bf16 v[84:87], v[170:173], v[222:225], v[84:87]
	v_mfma_f32_16x16x32_bf16 v[80:83], v[190:193], v[222:225], v[80:83]
	v_mfma_f32_16x16x32_bf16 v[132:135], v[174:177], v[202:205], v[132:135]
	v_mfma_f32_16x16x32_bf16 v[128:131], v[194:197], v[202:205], v[128:131]
	v_mfma_f32_16x16x32_bf16 v[116:119], v[174:177], v[210:213], v[116:119]
	v_mfma_f32_16x16x32_bf16 v[112:115], v[194:197], v[210:213], v[112:115]
	v_mfma_f32_16x16x32_bf16 v[100:103], v[174:177], v[218:221], v[100:103]
	v_mfma_f32_16x16x32_bf16 v[96:99], v[194:197], v[218:221], v[96:99]
	v_mfma_f32_16x16x32_bf16 v[84:87], v[174:177], v[226:229], v[84:87]
	v_mfma_f32_16x16x32_bf16 v[80:83], v[194:197], v[226:229], v[80:83]
	s_setprio 0
	s_barrier
	v_add_u32_e32 v161, 0x18000, v38
	ds_read_b128 v[198:201], v39 offset:49152
	ds_read_b128 v[202:205], v39 offset:50176
	ds_read_b128 v[206:209], v39 offset:51200
	ds_read_b128 v[210:213], v39 offset:52224
	ds_read_b128 v[214:217], v39 offset:53248
	ds_read_b128 v[218:221], v39 offset:54272
	ds_read_b128 v[222:225], v39 offset:55296
	ds_read_b128 v[226:229], v39 offset:56320
	ds_read_b128 v[170:173], v161
	ds_read_b128 v[174:177], v161 offset:1024
	ds_read_b128 v[190:193], v161 offset:2048
	ds_read_b128 v[194:197], v161 offset:3072
	s_waitcnt lgkmcnt(0)
	s_barrier
	s_setprio 1
	v_mfma_f32_16x16x32_bf16 v[132:135], v[170:173], v[198:201], v[132:135]
	v_mfma_f32_16x16x32_bf16 v[128:131], v[190:193], v[198:201], v[128:131]
	v_mfma_f32_16x16x32_bf16 v[116:119], v[170:173], v[206:209], v[116:119]
	v_mfma_f32_16x16x32_bf16 v[112:115], v[190:193], v[206:209], v[112:115]
	v_mfma_f32_16x16x32_bf16 v[100:103], v[170:173], v[214:217], v[100:103]
	v_mfma_f32_16x16x32_bf16 v[96:99], v[190:193], v[214:217], v[96:99]
	v_mfma_f32_16x16x32_bf16 v[84:87], v[170:173], v[222:225], v[84:87]
	v_mfma_f32_16x16x32_bf16 v[80:83], v[190:193], v[222:225], v[80:83]
	v_mfma_f32_16x16x32_bf16 v[132:135], v[174:177], v[202:205], v[132:135]
	v_mfma_f32_16x16x32_bf16 v[128:131], v[194:197], v[202:205], v[128:131]
	v_mfma_f32_16x16x32_bf16 v[116:119], v[174:177], v[210:213], v[116:119]
	v_mfma_f32_16x16x32_bf16 v[112:115], v[194:197], v[210:213], v[112:115]
	v_mfma_f32_16x16x32_bf16 v[100:103], v[174:177], v[218:221], v[100:103]
	v_mfma_f32_16x16x32_bf16 v[96:99], v[194:197], v[218:221], v[96:99]
	v_mfma_f32_16x16x32_bf16 v[84:87], v[174:177], v[226:229], v[84:87]
	v_mfma_f32_16x16x32_bf16 v[80:83], v[194:197], v[226:229], v[80:83]
	s_setprio 0
	s_barrier
	s_branch .Lq_smp_exit
.Lq_smp_2_loop:
	s_add_u32 s14, s8, 0x80080
	s_addc_u32 s15, s9, 0
	s_add_u32 s2, s4, 0x100
	s_addc_u32 s3, s5, 0
	s_waitcnt vmcnt(0)
	s_barrier
	s_barrier
	v_lshl_add_u64 v[178:179], s[14:15], 0, v[144:145]
	s_add_i32 m0, s1, 0xc000
	v_lshl_add_u64 v[230:231], s[14:15], 0, v[28:29]
	global_load_lds_dwordx4 v[178:179], off
	s_add_i32 m0, s1, 0xe000
	s_add_u32 s14, s14, 0x80
	s_addc_u32 s15, s15, 0
	global_load_lds_dwordx4 v[230:231], off
	v_lshl_add_u64 v[178:179], s[14:15], 0, v[144:145]
	s_add_i32 m0, s1, 0x0
	v_lshl_add_u64 v[230:231], s[14:15], 0, v[28:29]
	global_load_lds_dwordx4 v[178:179], off
	s_add_i32 m0, s1, 0x2000
	v_lshl_add_u64 v[232:233], s[2:3], 0, v[144:145]
	global_load_lds_dwordx4 v[230:231], off
	s_add_i32 m0, s1, 0x14000
	v_lshl_add_u64 v[234:235], s[2:3], 0, v[28:29]
	global_load_lds_dwordx4 v[232:233], off
	s_add_i32 m0, s1, 0x16000
	s_add_u32 s14, s14, 0x80
	s_addc_u32 s15, s15, 0
	global_load_lds_dwordx4 v[234:235], off
	s_add_u32 s2, s2, 0x80
	s_addc_u32 s3, s3, 0
	s_mov_b32 s55, 0
.Lq_smp_2_k:
	v_lshl_add_u64 v[178:179], s[14:15], 0, v[144:145]
	s_add_i32 m0, s1, 0x8000
	v_lshl_add_u64 v[230:231], s[14:15], 0, v[28:29]
	global_load_lds_dwordx4 v[178:179], off
	s_add_i32 m0, s1, 0xa000
	v_lshl_add_u64 v[232:233], s[2:3], 0, v[144:145]
	global_load_lds_dwordx4 v[230:231], off
	s_add_i32 m0, s1, 0x1c000
	v_lshl_add_u64 v[234:235], s[2:3], 0, v[28:29]
	global_load_lds_dwordx4 v[232:233], off
	s_add_i32 m0, s1, 0x1e000
	s_add_u32 s14, s14, 0x80
	s_addc_u32 s15, s15, 0
	global_load_lds_dwordx4 v[234:235], off
	s_add_u32 s2, s2, 0x80
	s_addc_u32 s3, s3, 0
	v_add_u32_e32 v161, 0x10000, v38
	ds_read_b128 v[198:201], v39 offset:16384
	ds_read_b128 v[202:205], v39 offset:17408
	ds_read_b128 v[206:209], v39 offset:18432
	ds_read_b128 v[210:213], v39 offset:19456
	ds_read_b128 v[214:217], v39 offset:20480
	ds_read_b128 v[218:221], v39 offset:21504
	ds_read_b128 v[222:225], v39 offset:22528
	ds_read_b128 v[226:229], v39 offset:23552
	ds_read_b128 v[40:43], v161
	ds_read_b128 v[48:51], v161 offset:1024
	ds_read_b128 v[162:165], v161 offset:2048
	ds_read_b128 v[166:169], v161 offset:3072
	s_waitcnt vmcnt(8)
	s_waitcnt lgkmcnt(0)
	s_barrier
	s_setprio 1
	v_mfma_f32_16x16x32_bf16 v[76:79], v[40:43], v[198:201], v[76:79]
	v_mfma_f32_16x16x32_bf16 v[72:75], v[162:165], v[198:201], v[72:75]
	v_mfma_f32_16x16x32_bf16 v[60:63], v[40:43], v[206:209], v[60:63]
	v_mfma_f32_16x16x32_bf16 v[56:59], v[162:165], v[206:209], v[56:59]
	v_mfma_f32_16x16x32_bf16 v[32:35], v[40:43], v[214:217], v[32:35]
	v_mfma_f32_16x16x32_bf16 v[24:27], v[162:165], v[214:217], v[24:27]
	v_mfma_f32_16x16x32_bf16 v[12:15], v[40:43], v[222:225], v[12:15]
	v_mfma_f32_16x16x32_bf16 v[8:11], v[162:165], v[222:225], v[8:11]
	v_mfma_f32_16x16x32_bf16 v[76:79], v[48:51], v[202:205], v[76:79]
	v_mfma_f32_16x16x32_bf16 v[72:75], v[166:169], v[202:205], v[72:75]
	v_mfma_f32_16x16x32_bf16 v[60:63], v[48:51], v[210:213], v[60:63]
	v_mfma_f32_16x16x32_bf16 v[56:59], v[166:169], v[210:213], v[56:59]
	v_mfma_f32_16x16x32_bf16 v[32:35], v[48:51], v[218:221], v[32:35]
	v_mfma_f32_16x16x32_bf16 v[24:27], v[166:169], v[218:221], v[24:27]
	v_mfma_f32_16x16x32_bf16 v[12:15], v[48:51], v[226:229], v[12:15]
	v_mfma_f32_16x16x32_bf16 v[8:11], v[166:169], v[226:229], v[8:11]
	s_setprio 0
	s_barrier
	v_lshl_add_u64 v[178:179], s[14:15], 0, v[144:145]
	s_add_i32 m0, s1, 0x4000
	v_lshl_add_u64 v[230:231], s[14:15], 0, v[28:29]
	global_load_lds_dwordx4 v[178:179], off
	s_add_i32 m0, s1, 0x6000
	v_lshl_add_u64 v[232:233], s[2:3], 0, v[144:145]
	global_load_lds_dwordx4 v[230:231], off
	s_add_i32 m0, s1, 0x10000
	v_lshl_add_u64 v[234:235], s[2:3], 0, v[28:29]
	global_load_lds_dwordx4 v[232:233], off
	s_add_i32 m0, s1, 0x12000
	s_add_u32 s14, s14, 0x80
	s_addc_u32 s15, s15, 0
	global_load_lds_dwordx4 v[234:235], off
	s_add_u32 s2, s2, 0x80
	s_addc_u32 s3, s3, 0
	v_add_u32_e32 v161, 0x18000, v38
	ds_read_b128 v[198:201], v39 offset:49152
	ds_read_b128 v[202:205], v39 offset:50176
	ds_read_b128 v[206:209], v39 offset:51200
	ds_read_b128 v[210:213], v39 offset:52224
	ds_read_b128 v[214:217], v39 offset:53248
	ds_read_b128 v[218:221], v39 offset:54272
	ds_read_b128 v[222:225], v39 offset:55296
	ds_read_b128 v[226:229], v39 offset:56320
	ds_read_b128 v[40:43], v161
	ds_read_b128 v[48:51], v161 offset:1024
	ds_read_b128 v[162:165], v161 offset:2048
	ds_read_b128 v[166:169], v161 offset:3072
	s_waitcnt vmcnt(8)
	s_waitcnt lgkmcnt(0)
	s_barrier
	s_setprio 1
	v_mfma_f32_16x16x32_bf16 v[76:79], v[40:43], v[198:201], v[76:79]
	v_mfma_f32_16x16x32_bf16 v[72:75], v[162:165], v[198:201], v[72:75]
	v_mfma_f32_16x16x32_bf16 v[60:63], v[40:43], v[206:209], v[60:63]
	v_mfma_f32_16x16x32_bf16 v[56:59], v[162:165], v[206:209], v[56:59]
	v_mfma_f32_16x16x32_bf16 v[32:35], v[40:43], v[214:217], v[32:35]
	v_mfma_f32_16x16x32_bf16 v[24:27], v[162:165], v[214:217], v[24:27]
	v_mfma_f32_16x16x32_bf16 v[12:15], v[40:43], v[222:225], v[12:15]
	v_mfma_f32_16x16x32_bf16 v[8:11], v[162:165], v[222:225], v[8:11]
	v_mfma_f32_16x16x32_bf16 v[76:79], v[48:51], v[202:205], v[76:79]
	v_mfma_f32_16x16x32_bf16 v[72:75], v[166:169], v[202:205], v[72:75]
	v_mfma_f32_16x16x32_bf16 v[60:63], v[48:51], v[210:213], v[60:63]
	v_mfma_f32_16x16x32_bf16 v[56:59], v[166:169], v[210:213], v[56:59]
	v_mfma_f32_16x16x32_bf16 v[32:35], v[48:51], v[218:221], v[32:35]
	v_mfma_f32_16x16x32_bf16 v[24:27], v[166:169], v[218:221], v[24:27]
	v_mfma_f32_16x16x32_bf16 v[12:15], v[48:51], v[226:229], v[12:15]
	v_mfma_f32_16x16x32_bf16 v[8:11], v[166:169], v[226:229], v[8:11]
	s_setprio 0
	s_barrier
	v_lshl_add_u64 v[178:179], s[14:15], 0, v[144:145]
	s_add_i32 m0, s1, 0xc000
	v_lshl_add_u64 v[230:231], s[14:15], 0, v[28:29]
	global_load_lds_dwordx4 v[178:179], off
	s_add_i32 m0, s1, 0xe000
	v_lshl_add_u64 v[232:233], s[2:3], 0, v[144:145]
	global_load_lds_dwordx4 v[230:231], off
	s_add_i32 m0, s1, 0x18000
	v_lshl_add_u64 v[234:235], s[2:3], 0, v[28:29]
	global_load_lds_dwordx4 v[232:233], off
	s_add_i32 m0, s1, 0x1a000
	s_add_u32 s14, s14, 0x80
	s_addc_u32 s15, s15, 0
	global_load_lds_dwordx4 v[234:235], off
	s_add_u32 s2, s2, 0x80
	s_addc_u32 s3, s3, 0
	v_add_u32_e32 v161, 0x14000, v38
	ds_read_b128 v[198:201], v39 offset:0
	ds_read_b128 v[202:205], v39 offset:1024
	ds_read_b128 v[206:209], v39 offset:2048
	ds_read_b128 v[210:213], v39 offset:3072
	ds_read_b128 v[214:217], v39 offset:4096
	ds_read_b128 v[218:221], v39 offset:5120
	ds_read_b128 v[222:225], v39 offset:6144
	ds_read_b128 v[226:229], v39 offset:7168
	ds_read_b128 v[40:43], v161
	ds_read_b128 v[48:51], v161 offset:1024
	ds_read_b128 v[162:165], v161 offset:2048
	ds_read_b128 v[166:169], v161 offset:3072
	s_waitcnt vmcnt(8)
	s_waitcnt lgkmcnt(0)
	s_barrier
	s_setprio 1
	v_mfma_f32_16x16x32_bf16 v[76:79], v[40:43], v[198:201], v[76:79]
	v_mfma_f32_16x16x32_bf16 v[72:75], v[162:165], v[198:201], v[72:75]
	v_mfma_f32_16x16x32_bf16 v[60:63], v[40:43], v[206:209], v[60:63]
	v_mfma_f32_16x16x32_bf16 v[56:59], v[162:165], v[206:209], v[56:59]
	v_mfma_f32_16x16x32_bf16 v[32:35], v[40:43], v[214:217], v[32:35]
	v_mfma_f32_16x16x32_bf16 v[24:27], v[162:165], v[214:217], v[24:27]
	v_mfma_f32_16x16x32_bf16 v[12:15], v[40:43], v[222:225], v[12:15]
	v_mfma_f32_16x16x32_bf16 v[8:11], v[162:165], v[222:225], v[8:11]
	v_mfma_f32_16x16x32_bf16 v[76:79], v[48:51], v[202:205], v[76:79]
	v_mfma_f32_16x16x32_bf16 v[72:75], v[166:169], v[202:205], v[72:75]
	v_mfma_f32_16x16x32_bf16 v[60:63], v[48:51], v[210:213], v[60:63]
	v_mfma_f32_16x16x32_bf16 v[56:59], v[166:169], v[210:213], v[56:59]
	v_mfma_f32_16x16x32_bf16 v[32:35], v[48:51], v[218:221], v[32:35]
	v_mfma_f32_16x16x32_bf16 v[24:27], v[166:169], v[218:221], v[24:27]
	v_mfma_f32_16x16x32_bf16 v[12:15], v[48:51], v[226:229], v[12:15]
	v_mfma_f32_16x16x32_bf16 v[8:11], v[166:169], v[226:229], v[8:11]
	s_setprio 0
	s_barrier
	v_lshl_add_u64 v[178:179], s[14:15], 0, v[144:145]
	s_add_i32 m0, s1, 0x0
	v_lshl_add_u64 v[230:231], s[14:15], 0, v[28:29]
	global_load_lds_dwordx4 v[178:179], off
	s_add_i32 m0, s1, 0x2000
	v_lshl_add_u64 v[232:233], s[2:3], 0, v[144:145]
	global_load_lds_dwordx4 v[230:231], off
	s_add_i32 m0, s1, 0x14000
	v_lshl_add_u64 v[234:235], s[2:3], 0, v[28:29]
	global_load_lds_dwordx4 v[232:233], off
	s_add_i32 m0, s1, 0x16000
	s_add_u32 s14, s14, 0x80
	s_addc_u32 s15, s15, 0
	global_load_lds_dwordx4 v[234:235], off
	s_add_u32 s2, s2, 0x80
	s_addc_u32 s3, s3, 0
	v_add_u32_e32 v161, 0x1c000, v38
	ds_read_b128 v[198:201], v39 offset:32768
	ds_read_b128 v[202:205], v39 offset:33792
	ds_read_b128 v[206:209], v39 offset:34816
	ds_read_b128 v[210:213], v39 offset:35840
	ds_read_b128 v[214:217], v39 offset:36864
	ds_read_b128 v[218:221], v39 offset:37888
	ds_read_b128 v[222:225], v39 offset:38912
	ds_read_b128 v[226:229], v39 offset:39936
	ds_read_b128 v[40:43], v161
	ds_read_b128 v[48:51], v161 offset:1024
	ds_read_b128 v[162:165], v161 offset:2048
	ds_read_b128 v[166:169], v161 offset:3072
	s_waitcnt vmcnt(8)
	s_waitcnt lgkmcnt(0)
	s_barrier
	s_setprio 1
	v_mfma_f32_16x16x32_bf16 v[76:79], v[40:43], v[198:201], v[76:79]
	v_mfma_f32_16x16x32_bf16 v[72:75], v[162:165], v[198:201], v[72:75]
	v_mfma_f32_16x16x32_bf16 v[60:63], v[40:43], v[206:209], v[60:63]
	v_mfma_f32_16x16x32_bf16 v[56:59], v[162:165], v[206:209], v[56:59]
	v_mfma_f32_16x16x32_bf16 v[32:35], v[40:43], v[214:217], v[32:35]
	v_mfma_f32_16x16x32_bf16 v[24:27], v[162:165], v[214:217], v[24:27]
	v_mfma_f32_16x16x32_bf16 v[12:15], v[40:43], v[222:225], v[12:15]
	v_mfma_f32_16x16x32_bf16 v[8:11], v[162:165], v[222:225], v[8:11]
	v_mfma_f32_16x16x32_bf16 v[76:79], v[48:51], v[202:205], v[76:79]
	v_mfma_f32_16x16x32_bf16 v[72:75], v[166:169], v[202:205], v[72:75]
	v_mfma_f32_16x16x32_bf16 v[60:63], v[48:51], v[210:213], v[60:63]
	v_mfma_f32_16x16x32_bf16 v[56:59], v[166:169], v[210:213], v[56:59]
	v_mfma_f32_16x16x32_bf16 v[32:35], v[48:51], v[218:221], v[32:35]
	v_mfma_f32_16x16x32_bf16 v[24:27], v[166:169], v[218:221], v[24:27]
	v_mfma_f32_16x16x32_bf16 v[12:15], v[48:51], v[226:229], v[12:15]
	v_mfma_f32_16x16x32_bf16 v[8:11], v[166:169], v[226:229], v[8:11]
	s_setprio 0
	s_barrier
	s_add_i32 s55, s55, 1
	s_cmp_lt_u32 s55, 7
	s_cbranch_scc1 .Lq_smp_2_k
	v_lshl_add_u64 v[178:179], s[14:15], 0, v[144:145]
	s_add_i32 m0, s1, 0x8000
	v_lshl_add_u64 v[230:231], s[14:15], 0, v[28:29]
	global_load_lds_dwordx4 v[178:179], off
	s_add_i32 m0, s1, 0xa000
	v_lshl_add_u64 v[232:233], s[2:3], 0, v[144:145]
	global_load_lds_dwordx4 v[230:231], off
	s_add_i32 m0, s1, 0x1c000
	v_lshl_add_u64 v[234:235], s[2:3], 0, v[28:29]
	global_load_lds_dwordx4 v[232:233], off
	s_add_i32 m0, s1, 0x1e000
	s_add_u32 s14, s14, 0x80
	s_addc_u32 s15, s15, 0
	global_load_lds_dwordx4 v[234:235], off
	s_add_u32 s2, s2, 0x80
	s_addc_u32 s3, s3, 0
	v_add_u32_e32 v161, 0x10000, v38
	ds_read_b128 v[198:201], v39 offset:16384
	ds_read_b128 v[202:205], v39 offset:17408
	ds_read_b128 v[206:209], v39 offset:18432
	ds_read_b128 v[210:213], v39 offset:19456
	ds_read_b128 v[214:217], v39 offset:20480
	ds_read_b128 v[218:221], v39 offset:21504
	ds_read_b128 v[222:225], v39 offset:22528
	ds_read_b128 v[226:229], v39 offset:23552
	ds_read_b128 v[40:43], v161
	ds_read_b128 v[48:51], v161 offset:1024
	ds_read_b128 v[162:165], v161 offset:2048
	ds_read_b128 v[166:169], v161 offset:3072
	s_waitcnt vmcnt(8)
	s_waitcnt lgkmcnt(0)
	s_barrier
	s_setprio 1
	v_mfma_f32_16x16x32_bf16 v[76:79], v[40:43], v[198:201], v[76:79]
	v_mfma_f32_16x16x32_bf16 v[72:75], v[162:165], v[198:201], v[72:75]
	v_mfma_f32_16x16x32_bf16 v[60:63], v[40:43], v[206:209], v[60:63]
	v_mfma_f32_16x16x32_bf16 v[56:59], v[162:165], v[206:209], v[56:59]
	v_mfma_f32_16x16x32_bf16 v[32:35], v[40:43], v[214:217], v[32:35]
	v_mfma_f32_16x16x32_bf16 v[24:27], v[162:165], v[214:217], v[24:27]
	v_mfma_f32_16x16x32_bf16 v[12:15], v[40:43], v[222:225], v[12:15]
	v_mfma_f32_16x16x32_bf16 v[8:11], v[162:165], v[222:225], v[8:11]
	v_mfma_f32_16x16x32_bf16 v[76:79], v[48:51], v[202:205], v[76:79]
	v_mfma_f32_16x16x32_bf16 v[72:75], v[166:169], v[202:205], v[72:75]
	v_mfma_f32_16x16x32_bf16 v[60:63], v[48:51], v[210:213], v[60:63]
	v_mfma_f32_16x16x32_bf16 v[56:59], v[166:169], v[210:213], v[56:59]
	v_mfma_f32_16x16x32_bf16 v[32:35], v[48:51], v[218:221], v[32:35]
	v_mfma_f32_16x16x32_bf16 v[24:27], v[166:169], v[218:221], v[24:27]
	v_mfma_f32_16x16x32_bf16 v[12:15], v[48:51], v[226:229], v[12:15]
	v_mfma_f32_16x16x32_bf16 v[8:11], v[166:169], v[226:229], v[8:11]
	s_setprio 0
	s_barrier
	v_add_u32_e32 v161, 0x18000, v38
	ds_read_b128 v[198:201], v39 offset:49152
	ds_read_b128 v[202:205], v39 offset:50176
	ds_read_b128 v[206:209], v39 offset:51200
	ds_read_b128 v[210:213], v39 offset:52224
	ds_read_b128 v[214:217], v39 offset:53248
	ds_read_b128 v[218:221], v39 offset:54272
	ds_read_b128 v[222:225], v39 offset:55296
	ds_read_b128 v[226:229], v39 offset:56320
	ds_read_b128 v[40:43], v161
	ds_read_b128 v[48:51], v161 offset:1024
	ds_read_b128 v[162:165], v161 offset:2048
	ds_read_b128 v[166:169], v161 offset:3072
	s_waitcnt vmcnt(4)
	s_waitcnt lgkmcnt(0)
	s_barrier
	s_setprio 1
	v_mfma_f32_16x16x32_bf16 v[76:79], v[40:43], v[198:201], v[76:79]
	v_mfma_f32_16x16x32_bf16 v[72:75], v[162:165], v[198:201], v[72:75]
	v_mfma_f32_16x16x32_bf16 v[60:63], v[40:43], v[206:209], v[60:63]
	v_mfma_f32_16x16x32_bf16 v[56:59], v[162:165], v[206:209], v[56:59]
	v_mfma_f32_16x16x32_bf16 v[32:35], v[40:43], v[214:217], v[32:35]
	v_mfma_f32_16x16x32_bf16 v[24:27], v[162:165], v[214:217], v[24:27]
	v_mfma_f32_16x16x32_bf16 v[12:15], v[40:43], v[222:225], v[12:15]
	v_mfma_f32_16x16x32_bf16 v[8:11], v[162:165], v[222:225], v[8:11]
	v_mfma_f32_16x16x32_bf16 v[76:79], v[48:51], v[202:205], v[76:79]
	v_mfma_f32_16x16x32_bf16 v[72:75], v[166:169], v[202:205], v[72:75]
	v_mfma_f32_16x16x32_bf16 v[60:63], v[48:51], v[210:213], v[60:63]
	v_mfma_f32_16x16x32_bf16 v[56:59], v[166:169], v[210:213], v[56:59]
	v_mfma_f32_16x16x32_bf16 v[32:35], v[48:51], v[218:221], v[32:35]
	v_mfma_f32_16x16x32_bf16 v[24:27], v[166:169], v[218:221], v[24:27]
	v_mfma_f32_16x16x32_bf16 v[12:15], v[48:51], v[226:229], v[12:15]
	v_mfma_f32_16x16x32_bf16 v[8:11], v[166:169], v[226:229], v[8:11]
	s_setprio 0
	s_barrier
	v_add_u32_e32 v161, 0x14000, v38
	ds_read_b128 v[198:201], v39 offset:0
	ds_read_b128 v[202:205], v39 offset:1024
	ds_read_b128 v[206:209], v39 offset:2048
	ds_read_b128 v[210:213], v39 offset:3072
	ds_read_b128 v[214:217], v39 offset:4096
	ds_read_b128 v[218:221], v39 offset:5120
	ds_read_b128 v[222:225], v39 offset:6144
	ds_read_b128 v[226:229], v39 offset:7168
	ds_read_b128 v[40:43], v161
	ds_read_b128 v[48:51], v161 offset:1024
	ds_read_b128 v[162:165], v161 offset:2048
	ds_read_b128 v[166:169], v161 offset:3072
	s_waitcnt vmcnt(0)
	s_waitcnt lgkmcnt(0)
	s_barrier
	s_setprio 1
	v_mfma_f32_16x16x32_bf16 v[76:79], v[40:43], v[198:201], v[76:79]
	v_mfma_f32_16x16x32_bf16 v[72:75], v[162:165], v[198:201], v[72:75]
	v_mfma_f32_16x16x32_bf16 v[60:63], v[40:43], v[206:209], v[60:63]
	v_mfma_f32_16x16x32_bf16 v[56:59], v[162:165], v[206:209], v[56:59]
	v_mfma_f32_16x16x32_bf16 v[32:35], v[40:43], v[214:217], v[32:35]
	v_mfma_f32_16x16x32_bf16 v[24:27], v[162:165], v[214:217], v[24:27]
	v_mfma_f32_16x16x32_bf16 v[12:15], v[40:43], v[222:225], v[12:15]
	v_mfma_f32_16x16x32_bf16 v[8:11], v[162:165], v[222:225], v[8:11]
	v_mfma_f32_16x16x32_bf16 v[76:79], v[48:51], v[202:205], v[76:79]
	v_mfma_f32_16x16x32_bf16 v[72:75], v[166:169], v[202:205], v[72:75]
	v_mfma_f32_16x16x32_bf16 v[60:63], v[48:51], v[210:213], v[60:63]
	v_mfma_f32_16x16x32_bf16 v[56:59], v[166:169], v[210:213], v[56:59]
	v_mfma_f32_16x16x32_bf16 v[32:35], v[48:51], v[218:221], v[32:35]
	v_mfma_f32_16x16x32_bf16 v[24:27], v[166:169], v[218:221], v[24:27]
	v_mfma_f32_16x16x32_bf16 v[12:15], v[48:51], v[226:229], v[12:15]
	v_mfma_f32_16x16x32_bf16 v[8:11], v[166:169], v[226:229], v[8:11]
	s_setprio 0
	s_barrier
	v_add_u32_e32 v161, 0x1c000, v38
	ds_read_b128 v[198:201], v39 offset:32768
	ds_read_b128 v[202:205], v39 offset:33792
	ds_read_b128 v[206:209], v39 offset:34816
	ds_read_b128 v[210:213], v39 offset:35840
	ds_read_b128 v[214:217], v39 offset:36864
	ds_read_b128 v[218:221], v39 offset:37888
	ds_read_b128 v[222:225], v39 offset:38912
	ds_read_b128 v[226:229], v39 offset:39936
	ds_read_b128 v[40:43], v161
	ds_read_b128 v[48:51], v161 offset:1024
	ds_read_b128 v[162:165], v161 offset:2048
	ds_read_b128 v[166:169], v161 offset:3072
	s_waitcnt lgkmcnt(0)
	s_barrier
	s_setprio 1
	v_mfma_f32_16x16x32_bf16 v[76:79], v[40:43], v[198:201], v[76:79]
	v_mfma_f32_16x16x32_bf16 v[72:75], v[162:165], v[198:201], v[72:75]
	v_mfma_f32_16x16x32_bf16 v[60:63], v[40:43], v[206:209], v[60:63]
	v_mfma_f32_16x16x32_bf16 v[56:59], v[162:165], v[206:209], v[56:59]
	v_mfma_f32_16x16x32_bf16 v[32:35], v[40:43], v[214:217], v[32:35]
	v_mfma_f32_16x16x32_bf16 v[24:27], v[162:165], v[214:217], v[24:27]
	v_mfma_f32_16x16x32_bf16 v[12:15], v[40:43], v[222:225], v[12:15]
	v_mfma_f32_16x16x32_bf16 v[8:11], v[162:165], v[222:225], v[8:11]
	v_mfma_f32_16x16x32_bf16 v[76:79], v[48:51], v[202:205], v[76:79]
	v_mfma_f32_16x16x32_bf16 v[72:75], v[166:169], v[202:205], v[72:75]
	v_mfma_f32_16x16x32_bf16 v[60:63], v[48:51], v[210:213], v[60:63]
	v_mfma_f32_16x16x32_bf16 v[56:59], v[166:169], v[210:213], v[56:59]
	v_mfma_f32_16x16x32_bf16 v[32:35], v[48:51], v[218:221], v[32:35]
	v_mfma_f32_16x16x32_bf16 v[24:27], v[166:169], v[218:221], v[24:27]
	v_mfma_f32_16x16x32_bf16 v[12:15], v[48:51], v[226:229], v[12:15]
	v_mfma_f32_16x16x32_bf16 v[8:11], v[166:169], v[226:229], v[8:11]
	s_setprio 0
	s_barrier
	s_branch .Lq_smp_exit
.Lq_smp_3_loop:
	s_add_u32 s14, s8, 0x80080
	s_addc_u32 s15, s9, 0
	s_add_u32 s2, s4, 0x80100
	s_addc_u32 s3, s5, 0
	s_waitcnt vmcnt(0)
	s_barrier
	s_barrier
	v_lshl_add_u64 v[178:179], s[14:15], 0, v[144:145]
	s_add_i32 m0, s1, 0xc000
	v_lshl_add_u64 v[230:231], s[14:15], 0, v[28:29]
	global_load_lds_dwordx4 v[178:179], off
	s_add_i32 m0, s1, 0xe000
	s_add_u32 s14, s14, 0x80
	s_addc_u32 s15, s15, 0
	global_load_lds_dwordx4 v[230:231], off
	v_lshl_add_u64 v[178:179], s[14:15], 0, v[144:145]
	s_add_i32 m0, s1, 0x0
	v_lshl_add_u64 v[230:231], s[14:15], 0, v[28:29]
	global_load_lds_dwordx4 v[178:179], off
	s_add_i32 m0, s1, 0x2000
	v_lshl_add_u64 v[232:233], s[2:3], 0, v[144:145]
	global_load_lds_dwordx4 v[230:231], off
	s_add_i32 m0, s1, 0x10000
	v_lshl_add_u64 v[234:235], s[2:3], 0, v[28:29]
	global_load_lds_dwordx4 v[232:233], off
	s_add_i32 m0, s1, 0x12000
	s_add_u32 s14, s14, 0x80
	s_addc_u32 s15, s15, 0
	global_load_lds_dwordx4 v[234:235], off
	s_add_u32 s2, s2, 0x80
	s_addc_u32 s3, s3, 0
	s_mov_b32 s55, 0
.Lq_smp_3_k:
	v_lshl_add_u64 v[178:179], s[14:15], 0, v[144:145]
	s_add_i32 m0, s1, 0x8000
	v_lshl_add_u64 v[230:231], s[14:15], 0, v[28:29]
	global_load_lds_dwordx4 v[178:179], off
	s_add_i32 m0, s1, 0xa000
	v_lshl_add_u64 v[232:233], s[2:3], 0, v[144:145]
	global_load_lds_dwordx4 v[230:231], off
	s_add_i32 m0, s1, 0x18000
	v_lshl_add_u64 v[234:235], s[2:3], 0, v[28:29]
	global_load_lds_dwordx4 v[232:233], off
	s_add_i32 m0, s1, 0x1a000
	s_add_u32 s14, s14, 0x80
	s_addc_u32 s15, s15, 0
	global_load_lds_dwordx4 v[234:235], off
	s_add_u32 s2, s2, 0x80
	s_addc_u32 s3, s3, 0
	v_add_u32_e32 v161, 0x14000, v38
	ds_read_b128 v[198:201], v39 offset:16384
	ds_read_b128 v[202:205], v39 offset:17408
	ds_read_b128 v[206:209], v39 offset:18432
	ds_read_b128 v[210:213], v39 offset:19456
	ds_read_b128 v[214:217], v39 offset:20480
	ds_read_b128 v[218:221], v39 offset:21504
	ds_read_b128 v[222:225], v39 offset:22528
	ds_read_b128 v[226:229], v39 offset:23552
	ds_read_b128 v[170:173], v161
	ds_read_b128 v[174:177], v161 offset:1024
	ds_read_b128 v[190:193], v161 offset:2048
	ds_read_b128 v[194:197], v161 offset:3072
	s_waitcnt vmcnt(8)
	s_waitcnt lgkmcnt(0)
	s_barrier
	s_setprio 1
	v_mfma_f32_16x16x32_bf16 v[52:55], v[170:173], v[206:209], v[52:55]
	v_mfma_f32_16x16x32_bf16 v[44:47], v[190:193], v[206:209], v[44:47]
	v_mfma_f32_16x16x32_bf16 v[20:23], v[170:173], v[214:217], v[20:23]
	v_mfma_f32_16x16x32_bf16 v[16:19], v[190:193], v[214:217], v[16:19]
	v_mfma_f32_16x16x32_bf16 v[4:7], v[170:173], v[222:225], v[4:7]
	v_mfma_f32_16x16x32_bf16 v[0:3], v[190:193], v[222:225], v[0:3]
	v_mfma_f32_16x16x32_bf16 v[68:71], v[170:173], v[198:201], v[68:71]
	v_mfma_f32_16x16x32_bf16 v[64:67], v[190:193], v[198:201], v[64:67]
	v_mfma_f32_16x16x32_bf16 v[52:55], v[174:177], v[210:213], v[52:55]
	v_mfma_f32_16x16x32_bf16 v[44:47], v[194:197], v[210:213], v[44:47]
	v_mfma_f32_16x16x32_bf16 v[20:23], v[174:177], v[218:221], v[20:23]
	v_mfma_f32_16x16x32_bf16 v[16:19], v[194:197], v[218:221], v[16:19]
	v_mfma_f32_16x16x32_bf16 v[4:7], v[174:177], v[226:229], v[4:7]
	v_mfma_f32_16x16x32_bf16 v[0:3], v[194:197], v[226:229], v[0:3]
	v_mfma_f32_16x16x32_bf16 v[68:71], v[174:177], v[202:205], v[68:71]
	v_mfma_f32_16x16x32_bf16 v[64:67], v[194:197], v[202:205], v[64:67]
	s_setprio 0
	s_barrier
	v_lshl_add_u64 v[178:179], s[14:15], 0, v[144:145]
	s_add_i32 m0, s1, 0x4000
	v_lshl_add_u64 v[230:231], s[14:15], 0, v[28:29]
	global_load_lds_dwordx4 v[178:179], off
	s_add_i32 m0, s1, 0x6000
	v_lshl_add_u64 v[232:233], s[2:3], 0, v[144:145]
	global_load_lds_dwordx4 v[230:231], off
	s_add_i32 m0, s1, 0x14000
	v_lshl_add_u64 v[234:235], s[2:3], 0, v[28:29]
	global_load_lds_dwordx4 v[232:233], off
	s_add_i32 m0, s1, 0x16000
	s_add_u32 s14, s14, 0x80
	s_addc_u32 s15, s15, 0
	global_load_lds_dwordx4 v[234:235], off
	s_add_u32 s2, s2, 0x80
	s_addc_u32 s3, s3, 0
	v_add_u32_e32 v161, 0x1c000, v38
	ds_read_b128 v[198:201], v39 offset:49152
	ds_read_b128 v[202:205], v39 offset:50176
	ds_read_b128 v[206:209], v39 offset:51200
	ds_read_b128 v[210:213], v39 offset:52224
	ds_read_b128 v[214:217], v39 offset:53248
	ds_read_b128 v[218:221], v39 offset:54272
	ds_read_b128 v[222:225], v39 offset:55296
	ds_read_b128 v[226:229], v39 offset:56320
	ds_read_b128 v[170:173], v161
	ds_read_b128 v[174:177], v161 offset:1024
	ds_read_b128 v[190:193], v161 offset:2048
	ds_read_b128 v[194:197], v161 offset:3072
	s_waitcnt vmcnt(8)
	s_waitcnt lgkmcnt(0)
	s_barrier
	s_setprio 1
	v_mfma_f32_16x16x32_bf16 v[52:55], v[170:173], v[206:209], v[52:55]
	v_mfma_f32_16x16x32_bf16 v[44:47], v[190:193], v[206:209], v[44:47]
	v_mfma_f32_16x16x32_bf16 v[20:23], v[170:173], v[214:217], v[20:23]
	v_mfma_f32_16x16x32_bf16 v[16:19], v[190:193], v[214:217], v[16:19]
	v_mfma_f32_16x16x32_bf16 v[4:7], v[170:173], v[222:225], v[4:7]
	v_mfma_f32_16x16x32_bf16 v[0:3], v[190:193], v[222:225], v[0:3]
	v_mfma_f32_16x16x32_bf16 v[68:71], v[170:173], v[198:201], v[68:71]
	v_mfma_f32_16x16x32_bf16 v[64:67], v[190:193], v[198:201], v[64:67]
	v_mfma_f32_16x16x32_bf16 v[52:55], v[174:177], v[210:213], v[52:55]
	v_mfma_f32_16x16x32_bf16 v[44:47], v[194:197], v[210:213], v[44:47]
	v_mfma_f32_16x16x32_bf16 v[20:23], v[174:177], v[218:221], v[20:23]
	v_mfma_f32_16x16x32_bf16 v[16:19], v[194:197], v[218:221], v[16:19]
	v_mfma_f32_16x16x32_bf16 v[4:7], v[174:177], v[226:229], v[4:7]
	v_mfma_f32_16x16x32_bf16 v[0:3], v[194:197], v[226:229], v[0:3]
	v_mfma_f32_16x16x32_bf16 v[68:71], v[174:177], v[202:205], v[68:71]
	v_mfma_f32_16x16x32_bf16 v[64:67], v[194:197], v[202:205], v[64:67]
	s_setprio 0
	s_barrier
	v_lshl_add_u64 v[178:179], s[14:15], 0, v[144:145]
	s_add_i32 m0, s1, 0xc000
	v_lshl_add_u64 v[230:231], s[14:15], 0, v[28:29]
	global_load_lds_dwordx4 v[178:179], off
	s_add_i32 m0, s1, 0xe000
	v_lshl_add_u64 v[232:233], s[2:3], 0, v[144:145]
	global_load_lds_dwordx4 v[230:231], off
	s_add_i32 m0, s1, 0x1c000
	v_lshl_add_u64 v[234:235], s[2:3], 0, v[28:29]
	global_load_lds_dwordx4 v[232:233], off
	s_add_i32 m0, s1, 0x1e000
	s_add_u32 s14, s14, 0x80
	s_addc_u32 s15, s15, 0
	global_load_lds_dwordx4 v[234:235], off
	s_add_u32 s2, s2, 0x80
	s_addc_u32 s3, s3, 0
	v_add_u32_e32 v161, 0x10000, v38
	ds_read_b128 v[198:201], v39 offset:0
	ds_read_b128 v[202:205], v39 offset:1024
	ds_read_b128 v[206:209], v39 offset:2048
	ds_read_b128 v[210:213], v39 offset:3072
	ds_read_b128 v[214:217], v39 offset:4096
	ds_read_b128 v[218:221], v39 offset:5120
	ds_read_b128 v[222:225], v39 offset:6144
	ds_read_b128 v[226:229], v39 offset:7168
	ds_read_b128 v[170:173], v161
	ds_read_b128 v[174:177], v161 offset:1024
	ds_read_b128 v[190:193], v161 offset:2048
	ds_read_b128 v[194:197], v161 offset:3072
	s_waitcnt vmcnt(8)
	s_waitcnt lgkmcnt(0)
	s_barrier
	s_setprio 1
	v_mfma_f32_16x16x32_bf16 v[52:55], v[170:173], v[206:209], v[52:55]
	v_mfma_f32_16x16x32_bf16 v[44:47], v[190:193], v[206:209], v[44:47]
	v_mfma_f32_16x16x32_bf16 v[20:23], v[170:173], v[214:217], v[20:23]
	v_mfma_f32_16x16x32_bf16 v[16:19], v[190:193], v[214:217], v[16:19]
	v_mfma_f32_16x16x32_bf16 v[4:7], v[170:173], v[222:225], v[4:7]
	v_mfma_f32_16x16x32_bf16 v[0:3], v[190:193], v[222:225], v[0:3]
	v_mfma_f32_16x16x32_bf16 v[68:71], v[170:173], v[198:201], v[68:71]
	v_mfma_f32_16x16x32_bf16 v[64:67], v[190:193], v[198:201], v[64:67]
	v_mfma_f32_16x16x32_bf16 v[52:55], v[174:177], v[210:213], v[52:55]
	v_mfma_f32_16x16x32_bf16 v[44:47], v[194:197], v[210:213], v[44:47]
	v_mfma_f32_16x16x32_bf16 v[20:23], v[174:177], v[218:221], v[20:23]
	v_mfma_f32_16x16x32_bf16 v[16:19], v[194:197], v[218:221], v[16:19]
	v_mfma_f32_16x16x32_bf16 v[4:7], v[174:177], v[226:229], v[4:7]
	v_mfma_f32_16x16x32_bf16 v[0:3], v[194:197], v[226:229], v[0:3]
	v_mfma_f32_16x16x32_bf16 v[68:71], v[174:177], v[202:205], v[68:71]
	v_mfma_f32_16x16x32_bf16 v[64:67], v[194:197], v[202:205], v[64:67]
	s_setprio 0
	s_barrier
	v_lshl_add_u64 v[178:179], s[14:15], 0, v[144:145]
	s_add_i32 m0, s1, 0x0
	v_lshl_add_u64 v[230:231], s[14:15], 0, v[28:29]
	global_load_lds_dwordx4 v[178:179], off
	s_add_i32 m0, s1, 0x2000
	v_lshl_add_u64 v[232:233], s[2:3], 0, v[144:145]
	global_load_lds_dwordx4 v[230:231], off
	s_add_i32 m0, s1, 0x10000
	v_lshl_add_u64 v[234:235], s[2:3], 0, v[28:29]
	global_load_lds_dwordx4 v[232:233], off
	s_add_i32 m0, s1, 0x12000
	s_add_u32 s14, s14, 0x80
	s_addc_u32 s15, s15, 0
	global_load_lds_dwordx4 v[234:235], off
	s_add_u32 s2, s2, 0x80
	s_addc_u32 s3, s3, 0
	v_add_u32_e32 v161, 0x18000, v38
	ds_read_b128 v[198:201], v39 offset:32768
	ds_read_b128 v[202:205], v39 offset:33792
	ds_read_b128 v[206:209], v39 offset:34816
	ds_read_b128 v[210:213], v39 offset:35840
	ds_read_b128 v[214:217], v39 offset:36864
	ds_read_b128 v[218:221], v39 offset:37888
	ds_read_b128 v[222:225], v39 offset:38912
	ds_read_b128 v[226:229], v39 offset:39936
	ds_read_b128 v[170:173], v161
	ds_read_b128 v[174:177], v161 offset:1024
	ds_read_b128 v[190:193], v161 offset:2048
	ds_read_b128 v[194:197], v161 offset:3072
	s_waitcnt vmcnt(8)
	s_waitcnt lgkmcnt(0)
	s_barrier
	s_setprio 1
	v_mfma_f32_16x16x32_bf16 v[52:55], v[170:173], v[206:209], v[52:55]
	v_mfma_f32_16x16x32_bf16 v[44:47], v[190:193], v[206:209], v[44:47]
	v_mfma_f32_16x16x32_bf16 v[20:23], v[170:173], v[214:217], v[20:23]
	v_mfma_f32_16x16x32_bf16 v[16:19], v[190:193], v[214:217], v[16:19]
	v_mfma_f32_16x16x32_bf16 v[4:7], v[170:173], v[222:225], v[4:7]
	v_mfma_f32_16x16x32_bf16 v[0:3], v[190:193], v[222:225], v[0:3]
	v_mfma_f32_16x16x32_bf16 v[68:71], v[170:173], v[198:201], v[68:71]
	v_mfma_f32_16x16x32_bf16 v[64:67], v[190:193], v[198:201], v[64:67]
	v_mfma_f32_16x16x32_bf16 v[52:55], v[174:177], v[210:213], v[52:55]
	v_mfma_f32_16x16x32_bf16 v[44:47], v[194:197], v[210:213], v[44:47]
	v_mfma_f32_16x16x32_bf16 v[20:23], v[174:177], v[218:221], v[20:23]
	v_mfma_f32_16x16x32_bf16 v[16:19], v[194:197], v[218:221], v[16:19]
	v_mfma_f32_16x16x32_bf16 v[4:7], v[174:177], v[226:229], v[4:7]
	v_mfma_f32_16x16x32_bf16 v[0:3], v[194:197], v[226:229], v[0:3]
	v_mfma_f32_16x16x32_bf16 v[68:71], v[174:177], v[202:205], v[68:71]
	v_mfma_f32_16x16x32_bf16 v[64:67], v[194:197], v[202:205], v[64:67]
	s_setprio 0
	s_barrier
	s_add_i32 s55, s55, 1
	s_cmp_lt_u32 s55, 7
	s_cbranch_scc1 .Lq_smp_3_k
	v_lshl_add_u64 v[178:179], s[14:15], 0, v[144:145]
	s_add_i32 m0, s1, 0x8000
	v_lshl_add_u64 v[230:231], s[14:15], 0, v[28:29]
	global_load_lds_dwordx4 v[178:179], off
	s_add_i32 m0, s1, 0xa000
	v_lshl_add_u64 v[232:233], s[2:3], 0, v[144:145]
	global_load_lds_dwordx4 v[230:231], off
	s_add_i32 m0, s1, 0x18000
	v_lshl_add_u64 v[234:235], s[2:3], 0, v[28:29]
	global_load_lds_dwordx4 v[232:233], off
	s_add_i32 m0, s1, 0x1a000
	s_add_u32 s14, s14, 0x80
	s_addc_u32 s15, s15, 0
	global_load_lds_dwordx4 v[234:235], off
	s_add_u32 s2, s2, 0x80
	s_addc_u32 s3, s3, 0
	v_add_u32_e32 v161, 0x14000, v38
	ds_read_b128 v[198:201], v39 offset:16384
	ds_read_b128 v[202:205], v39 offset:17408
	ds_read_b128 v[206:209], v39 offset:18432
	ds_read_b128 v[210:213], v39 offset:19456
	ds_read_b128 v[214:217], v39 offset:20480
	ds_read_b128 v[218:221], v39 offset:21504
	ds_read_b128 v[222:225], v39 offset:22528
	ds_read_b128 v[226:229], v39 offset:23552
	ds_read_b128 v[170:173], v161
	ds_read_b128 v[174:177], v161 offset:1024
	ds_read_b128 v[190:193], v161 offset:2048
	ds_read_b128 v[194:197], v161 offset:3072
	s_waitcnt vmcnt(8)
	s_waitcnt lgkmcnt(0)
	s_barrier
	s_setprio 1
	v_mfma_f32_16x16x32_bf16 v[52:55], v[170:173], v[206:209], v[52:55]
	v_mfma_f32_16x16x32_bf16 v[44:47], v[190:193], v[206:209], v[44:47]
	v_mfma_f32_16x16x32_bf16 v[20:23], v[170:173], v[214:217], v[20:23]
	v_mfma_f32_16x16x32_bf16 v[16:19], v[190:193], v[214:217], v[16:19]
	v_mfma_f32_16x16x32_bf16 v[4:7], v[170:173], v[222:225], v[4:7]
	v_mfma_f32_16x16x32_bf16 v[0:3], v[190:193], v[222:225], v[0:3]
	v_mfma_f32_16x16x32_bf16 v[68:71], v[170:173], v[198:201], v[68:71]
	v_mfma_f32_16x16x32_bf16 v[64:67], v[190:193], v[198:201], v[64:67]
	v_mfma_f32_16x16x32_bf16 v[52:55], v[174:177], v[210:213], v[52:55]
	v_mfma_f32_16x16x32_bf16 v[44:47], v[194:197], v[210:213], v[44:47]
	v_mfma_f32_16x16x32_bf16 v[20:23], v[174:177], v[218:221], v[20:23]
	v_mfma_f32_16x16x32_bf16 v[16:19], v[194:197], v[218:221], v[16:19]
	v_mfma_f32_16x16x32_bf16 v[4:7], v[174:177], v[226:229], v[4:7]
	v_mfma_f32_16x16x32_bf16 v[0:3], v[194:197], v[226:229], v[0:3]
	v_mfma_f32_16x16x32_bf16 v[68:71], v[174:177], v[202:205], v[68:71]
	v_mfma_f32_16x16x32_bf16 v[64:67], v[194:197], v[202:205], v[64:67]
	s_setprio 0
	s_barrier
	v_add_u32_e32 v161, 0x1c000, v38
	ds_read_b128 v[198:201], v39 offset:49152
	ds_read_b128 v[202:205], v39 offset:50176
	ds_read_b128 v[206:209], v39 offset:51200
	ds_read_b128 v[210:213], v39 offset:52224
	ds_read_b128 v[214:217], v39 offset:53248
	ds_read_b128 v[218:221], v39 offset:54272
	ds_read_b128 v[222:225], v39 offset:55296
	ds_read_b128 v[226:229], v39 offset:56320
	ds_read_b128 v[170:173], v161
	ds_read_b128 v[174:177], v161 offset:1024
	ds_read_b128 v[190:193], v161 offset:2048
	ds_read_b128 v[194:197], v161 offset:3072
	s_waitcnt vmcnt(4)
	s_waitcnt lgkmcnt(0)
	s_barrier
	s_setprio 1
	v_mfma_f32_16x16x32_bf16 v[52:55], v[170:173], v[206:209], v[52:55]
	v_mfma_f32_16x16x32_bf16 v[44:47], v[190:193], v[206:209], v[44:47]
	v_mfma_f32_16x16x32_bf16 v[20:23], v[170:173], v[214:217], v[20:23]
	v_mfma_f32_16x16x32_bf16 v[16:19], v[190:193], v[214:217], v[16:19]
	v_mfma_f32_16x16x32_bf16 v[4:7], v[170:173], v[222:225], v[4:7]
	v_mfma_f32_16x16x32_bf16 v[0:3], v[190:193], v[222:225], v[0:3]
	v_mfma_f32_16x16x32_bf16 v[68:71], v[170:173], v[198:201], v[68:71]
	v_mfma_f32_16x16x32_bf16 v[64:67], v[190:193], v[198:201], v[64:67]
	v_mfma_f32_16x16x32_bf16 v[52:55], v[174:177], v[210:213], v[52:55]
	v_mfma_f32_16x16x32_bf16 v[44:47], v[194:197], v[210:213], v[44:47]
	v_mfma_f32_16x16x32_bf16 v[20:23], v[174:177], v[218:221], v[20:23]
	v_mfma_f32_16x16x32_bf16 v[16:19], v[194:197], v[218:221], v[16:19]
	v_mfma_f32_16x16x32_bf16 v[4:7], v[174:177], v[226:229], v[4:7]
	v_mfma_f32_16x16x32_bf16 v[0:3], v[194:197], v[226:229], v[0:3]
	v_mfma_f32_16x16x32_bf16 v[68:71], v[174:177], v[202:205], v[68:71]
	v_mfma_f32_16x16x32_bf16 v[64:67], v[194:197], v[202:205], v[64:67]
	s_setprio 0
	s_barrier
	v_add_u32_e32 v161, 0x10000, v38
	ds_read_b128 v[198:201], v39 offset:0
	ds_read_b128 v[202:205], v39 offset:1024
	ds_read_b128 v[206:209], v39 offset:2048
	ds_read_b128 v[210:213], v39 offset:3072
	ds_read_b128 v[214:217], v39 offset:4096
	ds_read_b128 v[218:221], v39 offset:5120
	ds_read_b128 v[222:225], v39 offset:6144
	ds_read_b128 v[226:229], v39 offset:7168
	ds_read_b128 v[170:173], v161
	ds_read_b128 v[174:177], v161 offset:1024
	ds_read_b128 v[190:193], v161 offset:2048
	ds_read_b128 v[194:197], v161 offset:3072
	s_waitcnt vmcnt(0)
	s_waitcnt lgkmcnt(0)
	s_barrier
	s_setprio 1
	v_mfma_f32_16x16x32_bf16 v[52:55], v[170:173], v[206:209], v[52:55]
	v_mfma_f32_16x16x32_bf16 v[44:47], v[190:193], v[206:209], v[44:47]
	v_mfma_f32_16x16x32_bf16 v[20:23], v[170:173], v[214:217], v[20:23]
	v_mfma_f32_16x16x32_bf16 v[16:19], v[190:193], v[214:217], v[16:19]
	v_mfma_f32_16x16x32_bf16 v[4:7], v[170:173], v[222:225], v[4:7]
	v_mfma_f32_16x16x32_bf16 v[0:3], v[190:193], v[222:225], v[0:3]
	v_mfma_f32_16x16x32_bf16 v[68:71], v[170:173], v[198:201], v[68:71]
	v_mfma_f32_16x16x32_bf16 v[64:67], v[190:193], v[198:201], v[64:67]
	v_mfma_f32_16x16x32_bf16 v[52:55], v[174:177], v[210:213], v[52:55]
	v_mfma_f32_16x16x32_bf16 v[44:47], v[194:197], v[210:213], v[44:47]
	v_mfma_f32_16x16x32_bf16 v[20:23], v[174:177], v[218:221], v[20:23]
	v_mfma_f32_16x16x32_bf16 v[16:19], v[194:197], v[218:221], v[16:19]
	v_mfma_f32_16x16x32_bf16 v[4:7], v[174:177], v[226:229], v[4:7]
	v_mfma_f32_16x16x32_bf16 v[0:3], v[194:197], v[226:229], v[0:3]
	v_mfma_f32_16x16x32_bf16 v[68:71], v[174:177], v[202:205], v[68:71]
	v_mfma_f32_16x16x32_bf16 v[64:67], v[194:197], v[202:205], v[64:67]
	s_setprio 0
	s_barrier
	v_add_u32_e32 v161, 0x18000, v38
	ds_read_b128 v[198:201], v39 offset:32768
	ds_read_b128 v[202:205], v39 offset:33792
	ds_read_b128 v[206:209], v39 offset:34816
	ds_read_b128 v[210:213], v39 offset:35840
	ds_read_b128 v[214:217], v39 offset:36864
	ds_read_b128 v[218:221], v39 offset:37888
	ds_read_b128 v[222:225], v39 offset:38912
	ds_read_b128 v[226:229], v39 offset:39936
	ds_read_b128 v[170:173], v161
	ds_read_b128 v[174:177], v161 offset:1024
	ds_read_b128 v[190:193], v161 offset:2048
	ds_read_b128 v[194:197], v161 offset:3072
	s_waitcnt lgkmcnt(0)
	s_barrier
	s_setprio 1
	v_mfma_f32_16x16x32_bf16 v[52:55], v[170:173], v[206:209], v[52:55]
	v_mfma_f32_16x16x32_bf16 v[44:47], v[190:193], v[206:209], v[44:47]
	v_mfma_f32_16x16x32_bf16 v[20:23], v[170:173], v[214:217], v[20:23]
	v_mfma_f32_16x16x32_bf16 v[16:19], v[190:193], v[214:217], v[16:19]
	v_mfma_f32_16x16x32_bf16 v[4:7], v[170:173], v[222:225], v[4:7]
	v_mfma_f32_16x16x32_bf16 v[0:3], v[190:193], v[222:225], v[0:3]
	v_mfma_f32_16x16x32_bf16 v[68:71], v[170:173], v[198:201], v[68:71]
	v_mfma_f32_16x16x32_bf16 v[64:67], v[190:193], v[198:201], v[64:67]
	v_mfma_f32_16x16x32_bf16 v[52:55], v[174:177], v[210:213], v[52:55]
	v_mfma_f32_16x16x32_bf16 v[44:47], v[194:197], v[210:213], v[44:47]
	v_mfma_f32_16x16x32_bf16 v[20:23], v[174:177], v[218:221], v[20:23]
	v_mfma_f32_16x16x32_bf16 v[16:19], v[194:197], v[218:221], v[16:19]
	v_mfma_f32_16x16x32_bf16 v[4:7], v[174:177], v[226:229], v[4:7]
	v_mfma_f32_16x16x32_bf16 v[0:3], v[194:197], v[226:229], v[0:3]
	v_mfma_f32_16x16x32_bf16 v[68:71], v[174:177], v[202:205], v[68:71]
	v_mfma_f32_16x16x32_bf16 v[64:67], v[194:197], v[202:205], v[64:67]
	s_setprio 0
	s_barrier
	s_branch .Lq_smp_exit
.Lq_smp_exit:
	s_cmpk_lt_u32 s7, 0x100
	s_cbranch_scc0 .LBB0_1156
	s_barrier
.LBB0_1156:
	s_add_u32 s1, s26, 0xbd00000
	v_readlane_b32 s2, v244, 13
	s_addc_u32 s4, s27, 0
	v_readlane_b32 s3, v244, 14
	s_and_b64 s[2:3], s[2:3], exec
	s_cselect_b32 s17, s17, s4
	s_cselect_b32 s16, s16, s1
	s_lshl_b64 s[2:3], s[66:67], 2
	s_add_u32 s2, s18, s2
	s_addc_u32 s3, s19, s3
	s_add_u32 s14, s26, 0x7d00000
	s_addc_u32 s15, s27, 0
	s_lshl_b32 s1, s6, 8
	v_lshl_or_b32 v28, v146, 2, s1
	v_or_b32_e32 v168, s28, v28
	v_lshlrev_b32_e32 v144, 2, v168
	v_lshl_add_u64 v[28:29], s[2:3], 0, v[144:145]
	global_load_dwordx4 v[48:51], v[28:29], off
	global_load_dwordx4 v[40:43], v[28:29], off offset:64
	global_load_dwordx4 v[36:39], v[28:29], off offset:512
	s_nop 0
	global_load_dwordx4 v[28:31], v[28:29], off offset:576
	v_lshl_add_u32 v160, s0, 8, v160
	v_cmp_lt_i32_e32 vcc, s70, v160
	s_and_saveexec_b64 s[0:1], vcc
	s_xor_b64 s[0:1], exec, s[0:1]
	v_add_u32_e32 v162, 0xffffe000, v160
	v_mov_b32_e32 v163, v145
	v_lshlrev_b64 v[162:163], 13, v[162:163]
	v_mov_b32_e32 v161, v145
	v_lshl_add_u64 v[162:163], s[16:17], 0, v[162:163]
	v_lshlrev_b64 v[166:167], 11, v[160:161]
	s_andn2_saveexec_b64 s[0:1], s[0:1]
	v_ashrrev_i32_e32 v161, 31, v160
	v_lshlrev_b64 v[162:163], 13, v[160:161]
	v_lshlrev_b64 v[166:167], 11, v[160:161]
	v_lshl_add_u64 v[162:163], s[14:15], 0, v[162:163]
	s_or_b64 exec, exec, s[0:1]
	v_lshl_add_u64 v[164:165], v[162:163], 0, v[144:145]
	v_readlane_b32 s0, v244, 17
	v_readlane_b32 s1, v244, 18
	s_lshl_b64 s[0:1], s[0:1], 2
	s_add_u32 s0, s26, s0
	s_addc_u32 s1, s27, s1
	v_lshl_add_u64 v[162:163], v[166:167], 2, s[14:15]
	v_cmp_eq_u32_e32 vcc, 0, v146
	s_add_u32 s8, s0, 0x10000
	v_lshl_add_u64 v[162:163], v[162:163], 0, v[144:145]
	s_addc_u32 s9, s1, 0
	s_add_u32 s12, s26, 0xc500000
	s_addc_u32 s13, s27, 0
	s_waitcnt vmcnt(0) lgkmcnt(0)
	v_mul_f32_e32 v166, v143, v143
	v_mul_f32_e32 v146, v141, v141
	s_bitcmp1_b32 s51, 0
	s_cbranch_scc0 .Lqs_smp_0
	global_store_dwordx4 v[162:163], v[140:143], off
.Lqs_smp_0:
	v_fmac_f32_e32 v146, v140, v140
	v_fmac_f32_e32 v166, v142, v142
	v_mul_f32_e32 v140, v48, v140
	v_mul_f32_e32 v141, v49, v141
	v_add_f32_e32 v146, v146, v166
	v_cvt_pk_bf16_f32 v166, v140, v141
	v_mul_f32_e32 v140, v50, v142
	v_mul_f32_e32 v141, v51, v143
	v_cvt_pk_bf16_f32 v167, v140, v141
	v_lshlrev_b64 v[140:141], 12, v[160:161]
	v_lshl_add_u64 v[142:143], s[12:13], 0, v[140:141]
	v_lshlrev_b32_e32 v140, 1, v168
	v_mov_b32_e32 v141, v145
	v_lshl_add_u64 v[142:143], v[142:143], 0, v[140:141]
	s_bitcmp1_b32 s51, 0
	s_cbranch_scc0 .Lqs_smp_1
	global_store_dwordx2 v[142:143], v[166:167], off
.Lqs_smp_1:
	s_waitcnt lgkmcnt(0)
	v_mul_f32_e32 v141, v137, v137
	s_bitcmp1_b32 s51, 0
	s_cbranch_scc0 .Lqs_smp_2
	global_store_dwordx4 v[162:163], v[136:139], off offset:64
.Lqs_smp_2:
	v_fmac_f32_e32 v141, v136, v136
	v_mul_f32_e32 v166, v139, v139
	v_mul_f32_e32 v136, v40, v136
	v_mul_f32_e32 v137, v41, v137
	v_cvt_pk_bf16_f32 v136, v136, v137
	v_mul_f32_e32 v137, v42, v138
	v_fmac_f32_e32 v166, v138, v138
	v_mul_f32_e32 v138, v43, v139
	v_cvt_pk_bf16_f32 v137, v137, v138
	s_bitcmp1_b32 s51, 0
	s_cbranch_scc0 .Lqs_smp_3
	global_store_dwordx2 v[142:143], v[136:137], off offset:32
.Lqs_smp_3:
	v_add_f32_e32 v141, v141, v166
	v_add_f32_e32 v141, v146, v141
	s_waitcnt lgkmcnt(0)
	v_mul_f32_e32 v136, v133, v133
	s_bitcmp1_b32 s51, 1
	s_cbranch_scc0 .Lqs_smp_4
	global_store_dwordx4 v[162:163], v[132:135], off offset:512
.Lqs_smp_4:
	v_fmac_f32_e32 v136, v132, v132
	v_mul_f32_e32 v137, v135, v135
	v_mul_f32_e32 v132, v36, v132
	v_mul_f32_e32 v133, v37, v133
	v_cvt_pk_bf16_f32 v132, v132, v133
	v_mul_f32_e32 v133, v38, v134
	v_fmac_f32_e32 v137, v134, v134
	v_mul_f32_e32 v134, v39, v135
	v_cvt_pk_bf16_f32 v133, v133, v134
	s_bitcmp1_b32 s51, 1
	s_cbranch_scc0 .Lqs_smp_5
	global_store_dwordx2 v[142:143], v[132:133], off offset:256
.Lqs_smp_5:
	v_add_f32_e32 v136, v136, v137
	v_add_f32_e32 v136, v141, v136
	s_waitcnt lgkmcnt(0)
	s_bitcmp1_b32 s51, 1
	s_cbranch_scc0 .Lqs_smp_6
	global_store_dwordx4 v[162:163], v[128:131], off offset:576
.Lqs_smp_6:
	v_mul_f32_e32 v133, v29, v129
	v_mul_f32_e32 v132, v28, v128
	v_mul_f32_e32 v129, v129, v129
	v_fmac_f32_e32 v129, v128, v128
	v_mul_f32_e32 v128, v131, v131
	v_cvt_pk_bf16_f32 v132, v132, v133
	v_mul_f32_e32 v133, v30, v130
	v_fmac_f32_e32 v128, v130, v130
	v_and_b32_e32 v130, 64, v182
	v_add_f32_e32 v128, v129, v128
	v_xor_b32_e32 v129, 16, v182
	v_add_u32_e32 v130, 64, v130
	v_cmp_lt_i32_e64 s[0:1], v129, v130
	v_add_f32_e32 v128, v136, v128
	v_mul_f32_e32 v134, v31, v131
	v_cndmask_b32_e64 v129, v182, v129, s[0:1]
	v_lshlrev_b32_e32 v136, 2, v129
	ds_bpermute_b32 v129, v136, v128
	v_cvt_pk_bf16_f32 v133, v133, v134
	s_bitcmp1_b32 s51, 1
	s_cbranch_scc0 .Lqs_smp_7
	global_store_dwordx2 v[142:143], v[132:133], off offset:288
.Lqs_smp_7:
	s_waitcnt lgkmcnt(0)
	v_add_f32_e32 v128, v128, v129
	v_xor_b32_e32 v129, 32, v182
	v_cmp_lt_i32_e64 s[0:1], v129, v130
	s_nop 1
	v_cndmask_b32_e64 v129, v182, v129, s[0:1]
	v_lshlrev_b32_e32 v137, 2, v129
	ds_bpermute_b32 v129, v137, v128
	s_and_saveexec_b64 s[0:1], vcc
	s_cbranch_execz .LBB0_1162
	v_lshl_add_u64 v[130:131], v[160:161], 2, s[8:9]
	s_waitcnt lgkmcnt(0)
	v_add_f32_e32 v128, v128, v129
	global_atomic_add_f32 v[130:131], v128, off
.LBB0_1162:
	s_or_b64 exec, exec, s[0:1]
	s_waitcnt lgkmcnt(0)
	v_or_b32_e32 v128, 16, v160
	v_cmp_lt_i32_e64 s[0:1], s70, v128
	s_and_saveexec_b64 s[2:3], s[0:1]
	s_xor_b64 s[0:1], exec, s[2:3]
	v_add_u32_e32 v130, 0xffffe010, v160
	v_mov_b32_e32 v131, v145
	v_lshlrev_b64 v[130:131], 13, v[130:131]
	v_mov_b32_e32 v129, v145
	v_lshl_add_u64 v[130:131], s[16:17], 0, v[130:131]
	v_lshlrev_b64 v[134:135], 11, v[128:129]
	s_andn2_saveexec_b64 s[0:1], s[0:1]
	v_ashrrev_i32_e32 v129, 31, v128
	v_lshlrev_b64 v[130:131], 13, v[128:129]
	v_lshlrev_b64 v[134:135], 11, v[128:129]
	v_lshl_add_u64 v[130:131], s[14:15], 0, v[130:131]
	s_or_b64 exec, exec, s[0:1]
	v_lshl_add_u64 v[132:133], v[130:131], 0, v[144:145]
	v_lshl_add_u64 v[130:131], v[134:135], 2, s[14:15]
	v_lshl_add_u64 v[130:131], v[130:131], 0, v[144:145]
	v_mov_b32_e32 v141, v145
	s_waitcnt lgkmcnt(0)
	v_mul_f32_e32 v134, v125, v125
	s_bitcmp1_b32 s51, 0
	s_cbranch_scc0 .Lqs_smp_8
	global_store_dwordx4 v[130:131], v[124:127], off
.Lqs_smp_8:
	v_fmac_f32_e32 v134, v124, v124
	v_mul_f32_e32 v135, v127, v127
	v_mul_f32_e32 v124, v48, v124
	v_mul_f32_e32 v125, v49, v125
	v_fmac_f32_e32 v135, v126, v126
	v_cvt_pk_bf16_f32 v124, v124, v125
	v_mul_f32_e32 v125, v50, v126
	v_mul_f32_e32 v126, v51, v127
	v_cvt_pk_bf16_f32 v125, v125, v126
	v_lshlrev_b64 v[126:127], 12, v[128:129]
	v_lshl_add_u64 v[126:127], s[12:13], 0, v[126:127]
	v_add_f32_e32 v138, v134, v135
	v_lshl_add_u64 v[134:135], v[126:127], 0, v[140:141]
	s_bitcmp1_b32 s51, 0
	s_cbranch_scc0 .Lqs_smp_9
	global_store_dwordx2 v[134:135], v[124:125], off
.Lqs_smp_9:
	s_waitcnt lgkmcnt(0)
	v_mul_f32_e32 v124, v121, v121
	s_bitcmp1_b32 s51, 0
	s_cbranch_scc0 .Lqs_smp_10
	global_store_dwordx4 v[130:131], v[120:123], off offset:64
.Lqs_smp_10:
	v_fmac_f32_e32 v124, v120, v120
	v_mul_f32_e32 v125, v123, v123
	v_mul_f32_e32 v120, v40, v120
	v_mul_f32_e32 v121, v41, v121
	v_cvt_pk_bf16_f32 v120, v120, v121
	v_mul_f32_e32 v121, v42, v122
	v_fmac_f32_e32 v125, v122, v122
	v_mul_f32_e32 v122, v43, v123
	v_cvt_pk_bf16_f32 v121, v121, v122
	s_bitcmp1_b32 s51, 0
	s_cbranch_scc0 .Lqs_smp_11
	global_store_dwordx2 v[134:135], v[120:121], off offset:32
.Lqs_smp_11:
	v_add_f32_e32 v124, v124, v125
	v_add_f32_e32 v124, v138, v124
	s_waitcnt lgkmcnt(0)
	v_mul_f32_e32 v120, v117, v117
	s_bitcmp1_b32 s51, 1
	s_cbranch_scc0 .Lqs_smp_12
	global_store_dwordx4 v[130:131], v[116:119], off offset:512
.Lqs_smp_12:
	v_fmac_f32_e32 v120, v116, v116
	v_mul_f32_e32 v121, v119, v119
	v_mul_f32_e32 v116, v36, v116
	v_mul_f32_e32 v117, v37, v117
	v_cvt_pk_bf16_f32 v116, v116, v117
	v_mul_f32_e32 v117, v38, v118
	v_fmac_f32_e32 v121, v118, v118
	v_mul_f32_e32 v118, v39, v119
	v_cvt_pk_bf16_f32 v117, v117, v118
	s_bitcmp1_b32 s51, 1
	s_cbranch_scc0 .Lqs_smp_13
	global_store_dwordx2 v[134:135], v[116:117], off offset:256
.Lqs_smp_13:
	v_add_f32_e32 v120, v120, v121
	v_add_f32_e32 v120, v124, v120
	s_waitcnt lgkmcnt(0)
	s_bitcmp1_b32 s51, 1
	s_cbranch_scc0 .Lqs_smp_14
	global_store_dwordx4 v[130:131], v[112:115], off offset:576
.Lqs_smp_14:
	v_mul_f32_e32 v117, v29, v113
	v_mul_f32_e32 v116, v28, v112
	v_mul_f32_e32 v113, v113, v113
	v_fmac_f32_e32 v113, v112, v112
	v_mul_f32_e32 v112, v115, v115
	v_fmac_f32_e32 v112, v114, v114
	v_add_f32_e32 v112, v113, v112
	v_add_f32_e32 v112, v120, v112
	ds_bpermute_b32 v113, v136, v112
	v_cvt_pk_bf16_f32 v116, v116, v117
	v_mul_f32_e32 v117, v30, v114
	v_mul_f32_e32 v118, v31, v115
	v_cvt_pk_bf16_f32 v117, v117, v118
	s_waitcnt lgkmcnt(0)
	v_add_f32_e32 v112, v112, v113
	ds_bpermute_b32 v113, v137, v112
	s_bitcmp1_b32 s51, 1
	s_cbranch_scc0 .Lqs_smp_15
	global_store_dwordx2 v[134:135], v[116:117], off offset:288
.Lqs_smp_15:
	s_and_saveexec_b64 s[0:1], vcc
	s_cbranch_execz .LBB0_1168
	v_lshl_add_u64 v[114:115], v[128:129], 2, s[8:9]
	s_waitcnt lgkmcnt(0)
	v_add_f32_e32 v112, v112, v113
	global_atomic_add_f32 v[114:115], v112, off
.LBB0_1168:
	s_or_b64 exec, exec, s[0:1]
	s_waitcnt lgkmcnt(0)
	v_or_b32_e32 v112, 32, v160
	v_cmp_lt_i32_e64 s[0:1], s70, v112
	s_and_saveexec_b64 s[2:3], s[0:1]
	s_xor_b64 s[0:1], exec, s[2:3]
	v_add_u32_e32 v114, 0xffffe020, v160
	v_mov_b32_e32 v115, v145
	v_lshlrev_b64 v[114:115], 13, v[114:115]
	v_mov_b32_e32 v113, v145
	v_lshl_add_u64 v[114:115], s[16:17], 0, v[114:115]
	v_lshlrev_b64 v[118:119], 11, v[112:113]
	s_andn2_saveexec_b64 s[0:1], s[0:1]
	v_ashrrev_i32_e32 v113, 31, v112
	v_lshlrev_b64 v[114:115], 13, v[112:113]
	v_lshlrev_b64 v[118:119], 11, v[112:113]
	v_lshl_add_u64 v[114:115], s[14:15], 0, v[114:115]
	s_or_b64 exec, exec, s[0:1]
	v_lshl_add_u64 v[116:117], v[114:115], 0, v[144:145]
	v_lshl_add_u64 v[114:115], v[118:119], 2, s[14:15]
	v_lshl_add_u64 v[114:115], v[114:115], 0, v[144:145]
	v_mov_b32_e32 v141, v145
	s_waitcnt lgkmcnt(0)
	v_mul_f32_e32 v118, v109, v109
	s_bitcmp1_b32 s51, 0
	s_cbranch_scc0 .Lqs_smp_16
	global_store_dwordx4 v[114:115], v[108:111], off
.Lqs_smp_16:
	v_fmac_f32_e32 v118, v108, v108
	v_mul_f32_e32 v119, v111, v111
	v_mul_f32_e32 v108, v48, v108
	v_mul_f32_e32 v109, v49, v109
	v_fmac_f32_e32 v119, v110, v110
	v_cvt_pk_bf16_f32 v108, v108, v109
	v_mul_f32_e32 v109, v50, v110
	v_mul_f32_e32 v110, v51, v111
	v_cvt_pk_bf16_f32 v109, v109, v110
	v_lshlrev_b64 v[110:111], 12, v[112:113]
	v_lshl_add_u64 v[110:111], s[12:13], 0, v[110:111]
	v_add_f32_e32 v120, v118, v119
	v_lshl_add_u64 v[118:119], v[110:111], 0, v[140:141]
	s_bitcmp1_b32 s51, 0
	s_cbranch_scc0 .Lqs_smp_17
	global_store_dwordx2 v[118:119], v[108:109], off
.Lqs_smp_17:
	s_waitcnt lgkmcnt(0)
	v_mul_f32_e32 v108, v105, v105
	s_bitcmp1_b32 s51, 0
	s_cbranch_scc0 .Lqs_smp_18
	global_store_dwordx4 v[114:115], v[104:107], off offset:64
.Lqs_smp_18:
	v_fmac_f32_e32 v108, v104, v104
	v_mul_f32_e32 v109, v107, v107
	v_mul_f32_e32 v104, v40, v104
	v_mul_f32_e32 v105, v41, v105
	v_cvt_pk_bf16_f32 v104, v104, v105
	v_mul_f32_e32 v105, v42, v106
	v_fmac_f32_e32 v109, v106, v106
	v_mul_f32_e32 v106, v43, v107
	v_cvt_pk_bf16_f32 v105, v105, v106
	s_bitcmp1_b32 s51, 0
	s_cbranch_scc0 .Lqs_smp_19
	global_store_dwordx2 v[118:119], v[104:105], off offset:32
.Lqs_smp_19:
	v_add_f32_e32 v108, v108, v109
	v_add_f32_e32 v108, v120, v108
	s_waitcnt lgkmcnt(0)
	v_mul_f32_e32 v104, v101, v101
	s_bitcmp1_b32 s51, 1
	s_cbranch_scc0 .Lqs_smp_20
	global_store_dwordx4 v[114:115], v[100:103], off offset:512
.Lqs_smp_20:
	v_fmac_f32_e32 v104, v100, v100
	v_mul_f32_e32 v105, v103, v103
	v_mul_f32_e32 v100, v36, v100
	v_mul_f32_e32 v101, v37, v101
	v_cvt_pk_bf16_f32 v100, v100, v101
	v_mul_f32_e32 v101, v38, v102
	v_fmac_f32_e32 v105, v102, v102
	v_mul_f32_e32 v102, v39, v103
	v_cvt_pk_bf16_f32 v101, v101, v102
	s_bitcmp1_b32 s51, 1
	s_cbranch_scc0 .Lqs_smp_21
	global_store_dwordx2 v[118:119], v[100:101], off offset:256
.Lqs_smp_21:
	v_add_f32_e32 v104, v104, v105
	v_add_f32_e32 v104, v108, v104
	s_waitcnt lgkmcnt(0)
	s_bitcmp1_b32 s51, 1
	s_cbranch_scc0 .Lqs_smp_22
	global_store_dwordx4 v[114:115], v[96:99], off offset:576
.Lqs_smp_22:
	v_mul_f32_e32 v101, v29, v97
	v_mul_f32_e32 v100, v28, v96
	v_mul_f32_e32 v97, v97, v97
	v_fmac_f32_e32 v97, v96, v96
	v_mul_f32_e32 v96, v99, v99
	v_fmac_f32_e32 v96, v98, v98
	v_add_f32_e32 v96, v97, v96
	v_add_f32_e32 v96, v104, v96
	ds_bpermute_b32 v97, v136, v96
	v_cvt_pk_bf16_f32 v100, v100, v101
	v_mul_f32_e32 v101, v30, v98
	v_mul_f32_e32 v102, v31, v99
	v_cvt_pk_bf16_f32 v101, v101, v102
	s_waitcnt lgkmcnt(0)
	v_add_f32_e32 v96, v96, v97
	ds_bpermute_b32 v97, v137, v96
	s_bitcmp1_b32 s51, 1
	s_cbranch_scc0 .Lqs_smp_23
	global_store_dwordx2 v[118:119], v[100:101], off offset:288
.Lqs_smp_23:
	s_and_saveexec_b64 s[0:1], vcc
	s_cbranch_execz .LBB0_1174
	v_lshl_add_u64 v[98:99], v[112:113], 2, s[8:9]
	s_waitcnt lgkmcnt(0)
	v_add_f32_e32 v96, v96, v97
	global_atomic_add_f32 v[98:99], v96, off
.LBB0_1174:
	s_or_b64 exec, exec, s[0:1]
	s_waitcnt lgkmcnt(0)
	v_or_b32_e32 v96, 48, v160
	v_cmp_lt_i32_e64 s[0:1], s70, v96
	s_and_saveexec_b64 s[2:3], s[0:1]
	s_xor_b64 s[0:1], exec, s[2:3]
	v_add_u32_e32 v98, 0xffffe030, v160
	v_mov_b32_e32 v99, v145
	v_lshlrev_b64 v[98:99], 13, v[98:99]
	v_mov_b32_e32 v97, v145
	v_lshl_add_u64 v[98:99], s[16:17], 0, v[98:99]
	v_lshlrev_b64 v[102:103], 11, v[96:97]
	s_andn2_saveexec_b64 s[0:1], s[0:1]
	v_ashrrev_i32_e32 v97, 31, v96
	v_lshlrev_b64 v[98:99], 13, v[96:97]
	v_lshlrev_b64 v[102:103], 11, v[96:97]
	v_lshl_add_u64 v[98:99], s[14:15], 0, v[98:99]
	s_or_b64 exec, exec, s[0:1]
	v_lshl_add_u64 v[100:101], v[98:99], 0, v[144:145]
	v_lshl_add_u64 v[98:99], v[102:103], 2, s[14:15]
	v_lshl_add_u64 v[98:99], v[98:99], 0, v[144:145]
	v_mov_b32_e32 v141, v145
	s_waitcnt lgkmcnt(0)
	v_mul_f32_e32 v102, v93, v93
	s_bitcmp1_b32 s51, 0
	s_cbranch_scc0 .Lqs_smp_24
	global_store_dwordx4 v[98:99], v[92:95], off
.Lqs_smp_24:
	v_fmac_f32_e32 v102, v92, v92
	v_mul_f32_e32 v103, v95, v95
	v_mul_f32_e32 v92, v48, v92
	v_mul_f32_e32 v93, v49, v93
	v_fmac_f32_e32 v103, v94, v94
	v_cvt_pk_bf16_f32 v92, v92, v93
	v_mul_f32_e32 v93, v50, v94
	v_mul_f32_e32 v94, v51, v95
	v_cvt_pk_bf16_f32 v93, v93, v94
	v_lshlrev_b64 v[94:95], 12, v[96:97]
	v_lshl_add_u64 v[94:95], s[12:13], 0, v[94:95]
	v_add_f32_e32 v104, v102, v103
	v_lshl_add_u64 v[102:103], v[94:95], 0, v[140:141]
	s_bitcmp1_b32 s51, 0
	s_cbranch_scc0 .Lqs_smp_25
	global_store_dwordx2 v[102:103], v[92:93], off
.Lqs_smp_25:
	s_waitcnt lgkmcnt(0)
	v_mul_f32_e32 v92, v89, v89
	s_bitcmp1_b32 s51, 0
	s_cbranch_scc0 .Lqs_smp_26
	global_store_dwordx4 v[98:99], v[88:91], off offset:64
.Lqs_smp_26:
	v_fmac_f32_e32 v92, v88, v88
	v_mul_f32_e32 v93, v91, v91
	v_mul_f32_e32 v88, v40, v88
	v_mul_f32_e32 v89, v41, v89
	v_cvt_pk_bf16_f32 v88, v88, v89
	v_mul_f32_e32 v89, v42, v90
	v_fmac_f32_e32 v93, v90, v90
	v_mul_f32_e32 v90, v43, v91
	v_cvt_pk_bf16_f32 v89, v89, v90
	s_bitcmp1_b32 s51, 0
	s_cbranch_scc0 .Lqs_smp_27
	global_store_dwordx2 v[102:103], v[88:89], off offset:32
.Lqs_smp_27:
	v_add_f32_e32 v92, v92, v93
	v_add_f32_e32 v92, v104, v92
	s_waitcnt lgkmcnt(0)
	v_mul_f32_e32 v88, v85, v85
	s_bitcmp1_b32 s51, 1
	s_cbranch_scc0 .Lqs_smp_28
	global_store_dwordx4 v[98:99], v[84:87], off offset:512
.Lqs_smp_28:
	v_fmac_f32_e32 v88, v84, v84
	v_mul_f32_e32 v89, v87, v87
	v_mul_f32_e32 v84, v36, v84
	v_mul_f32_e32 v85, v37, v85
	v_cvt_pk_bf16_f32 v84, v84, v85
	v_mul_f32_e32 v85, v38, v86
	v_fmac_f32_e32 v89, v86, v86
	v_mul_f32_e32 v86, v39, v87
	v_cvt_pk_bf16_f32 v85, v85, v86
	s_bitcmp1_b32 s51, 1
	s_cbranch_scc0 .Lqs_smp_29
	global_store_dwordx2 v[102:103], v[84:85], off offset:256
.Lqs_smp_29:
	v_add_f32_e32 v88, v88, v89
	v_add_f32_e32 v88, v92, v88
	s_waitcnt lgkmcnt(0)
	s_bitcmp1_b32 s51, 1
	s_cbranch_scc0 .Lqs_smp_30
	global_store_dwordx4 v[98:99], v[80:83], off offset:576
.Lqs_smp_30:
	v_mul_f32_e32 v85, v29, v81
	v_mul_f32_e32 v84, v28, v80
	v_mul_f32_e32 v81, v81, v81
	v_fmac_f32_e32 v81, v80, v80
	v_mul_f32_e32 v80, v83, v83
	v_fmac_f32_e32 v80, v82, v82
	v_add_f32_e32 v80, v81, v80
	v_add_f32_e32 v80, v88, v80
	ds_bpermute_b32 v81, v136, v80
	v_cvt_pk_bf16_f32 v84, v84, v85
	v_mul_f32_e32 v85, v30, v82
	v_mul_f32_e32 v86, v31, v83
	v_cvt_pk_bf16_f32 v85, v85, v86
	s_waitcnt lgkmcnt(0)
	v_add_f32_e32 v80, v80, v81
	ds_bpermute_b32 v81, v137, v80
	s_bitcmp1_b32 s51, 1
	s_cbranch_scc0 .Lqs_smp_31
	global_store_dwordx2 v[102:103], v[84:85], off offset:288
.Lqs_smp_31:
	s_and_saveexec_b64 s[0:1], vcc
	s_cbranch_execz .LBB0_1180
	v_lshl_add_u64 v[82:83], v[96:97], 2, s[8:9]
	s_waitcnt lgkmcnt(0)
	v_add_f32_e32 v80, v80, v81
	global_atomic_add_f32 v[82:83], v80, off
.LBB0_1180:
	s_or_b64 exec, exec, s[0:1]
	s_movk_i32 s0, 0x1f7f
	s_waitcnt lgkmcnt(0)
	v_add_u32_e32 v80, 0x80, v160
	v_cmp_lt_i32_e64 s[0:1], s0, v160
	s_and_saveexec_b64 s[2:3], s[0:1]
	s_xor_b64 s[0:1], exec, s[2:3]
	v_add_u32_e32 v82, 0xffffe080, v160
	v_mov_b32_e32 v83, v145
	v_lshlrev_b64 v[82:83], 13, v[82:83]
	v_mov_b32_e32 v81, v145
	v_lshl_add_u64 v[82:83], s[16:17], 0, v[82:83]
	v_lshlrev_b64 v[86:87], 11, v[80:81]
	s_andn2_saveexec_b64 s[0:1], s[0:1]
	v_ashrrev_i32_e32 v81, 31, v80
	v_lshlrev_b64 v[82:83], 13, v[80:81]
	v_lshlrev_b64 v[86:87], 11, v[80:81]
	v_lshl_add_u64 v[82:83], s[14:15], 0, v[82:83]
	s_or_b64 exec, exec, s[0:1]
	v_lshl_add_u64 v[84:85], v[82:83], 0, v[144:145]
	v_lshl_add_u64 v[82:83], v[86:87], 2, s[14:15]
	v_lshl_add_u64 v[82:83], v[82:83], 0, v[144:145]
	v_mov_b32_e32 v141, v145
	s_waitcnt lgkmcnt(0)
	v_mul_f32_e32 v86, v77, v77
	s_bitcmp1_b32 s51, 2
	s_cbranch_scc0 .Lqs_smp_32
	global_store_dwordx4 v[82:83], v[76:79], off
.Lqs_smp_32:
	v_fmac_f32_e32 v86, v76, v76
	v_mul_f32_e32 v87, v79, v79
	v_mul_f32_e32 v76, v48, v76
	v_mul_f32_e32 v77, v49, v77
	v_fmac_f32_e32 v87, v78, v78
	v_cvt_pk_bf16_f32 v76, v76, v77
	v_mul_f32_e32 v77, v50, v78
	v_mul_f32_e32 v78, v51, v79
	v_cvt_pk_bf16_f32 v77, v77, v78
	v_lshlrev_b64 v[78:79], 12, v[80:81]
	v_lshl_add_u64 v[78:79], s[12:13], 0, v[78:79]
	v_add_f32_e32 v88, v86, v87
	v_lshl_add_u64 v[86:87], v[78:79], 0, v[140:141]
	s_bitcmp1_b32 s51, 2
	s_cbranch_scc0 .Lqs_smp_33
	global_store_dwordx2 v[86:87], v[76:77], off
.Lqs_smp_33:
	s_waitcnt lgkmcnt(0)
	v_mul_f32_e32 v76, v73, v73
	s_bitcmp1_b32 s51, 2
	s_cbranch_scc0 .Lqs_smp_34
	global_store_dwordx4 v[82:83], v[72:75], off offset:64
.Lqs_smp_34:
	v_fmac_f32_e32 v76, v72, v72
	v_mul_f32_e32 v77, v75, v75
	v_mul_f32_e32 v72, v40, v72
	v_mul_f32_e32 v73, v41, v73
	v_cvt_pk_bf16_f32 v72, v72, v73
	v_mul_f32_e32 v73, v42, v74
	v_fmac_f32_e32 v77, v74, v74
	v_mul_f32_e32 v74, v43, v75
	v_cvt_pk_bf16_f32 v73, v73, v74
	s_bitcmp1_b32 s51, 2
	s_cbranch_scc0 .Lqs_smp_35
	global_store_dwordx2 v[86:87], v[72:73], off offset:32
.Lqs_smp_35:
	v_add_f32_e32 v76, v76, v77
	v_add_f32_e32 v76, v88, v76
	s_waitcnt lgkmcnt(0)
	v_mul_f32_e32 v72, v69, v69
	s_bitcmp1_b32 s51, 3
	s_cbranch_scc0 .Lqs_smp_36
	global_store_dwordx4 v[82:83], v[68:71], off offset:512
.Lqs_smp_36:
	v_fmac_f32_e32 v72, v68, v68
	v_mul_f32_e32 v73, v71, v71
	v_mul_f32_e32 v68, v36, v68
	v_mul_f32_e32 v69, v37, v69
	v_cvt_pk_bf16_f32 v68, v68, v69
	v_mul_f32_e32 v69, v38, v70
	v_fmac_f32_e32 v73, v70, v70
	v_mul_f32_e32 v70, v39, v71
	v_cvt_pk_bf16_f32 v69, v69, v70
	s_bitcmp1_b32 s51, 3
	s_cbranch_scc0 .Lqs_smp_37
	global_store_dwordx2 v[86:87], v[68:69], off offset:256
.Lqs_smp_37:
	v_add_f32_e32 v72, v72, v73
	v_add_f32_e32 v72, v76, v72
	s_waitcnt lgkmcnt(0)
	s_bitcmp1_b32 s51, 3
	s_cbranch_scc0 .Lqs_smp_38
	global_store_dwordx4 v[82:83], v[64:67], off offset:576
.Lqs_smp_38:
	v_mul_f32_e32 v69, v29, v65
	v_mul_f32_e32 v68, v28, v64
	v_mul_f32_e32 v65, v65, v65
	v_fmac_f32_e32 v65, v64, v64
	v_mul_f32_e32 v64, v67, v67
	v_fmac_f32_e32 v64, v66, v66
	v_add_f32_e32 v64, v65, v64
	v_add_f32_e32 v64, v72, v64
	ds_bpermute_b32 v65, v136, v64
	v_cvt_pk_bf16_f32 v68, v68, v69
	v_mul_f32_e32 v69, v30, v66
	v_mul_f32_e32 v70, v31, v67
	v_cvt_pk_bf16_f32 v69, v69, v70
	s_waitcnt lgkmcnt(0)
	v_add_f32_e32 v64, v64, v65
	ds_bpermute_b32 v65, v137, v64
	s_bitcmp1_b32 s51, 3
	s_cbranch_scc0 .Lqs_smp_39
	global_store_dwordx2 v[86:87], v[68:69], off offset:288
.Lqs_smp_39:
	s_and_saveexec_b64 s[0:1], vcc
	s_cbranch_execz .LBB0_1186
	v_lshl_add_u64 v[66:67], v[80:81], 2, s[8:9]
	s_waitcnt lgkmcnt(0)
	v_add_f32_e32 v64, v64, v65
	global_atomic_add_f32 v[66:67], v64, off
.LBB0_1186:
	s_or_b64 exec, exec, s[0:1]
	s_movk_i32 s0, 0x1f6f
	s_waitcnt lgkmcnt(0)
	v_add_u32_e32 v64, 0x90, v160
	v_cmp_lt_i32_e64 s[0:1], s0, v160
	s_and_saveexec_b64 s[2:3], s[0:1]
	s_xor_b64 s[0:1], exec, s[2:3]
	v_add_u32_e32 v66, 0xffffe090, v160
	v_mov_b32_e32 v67, v145
	v_lshlrev_b64 v[66:67], 13, v[66:67]
	v_mov_b32_e32 v65, v145
	v_lshl_add_u64 v[66:67], s[16:17], 0, v[66:67]
	v_lshlrev_b64 v[70:71], 11, v[64:65]
	s_andn2_saveexec_b64 s[0:1], s[0:1]
	v_ashrrev_i32_e32 v65, 31, v64
	v_lshlrev_b64 v[66:67], 13, v[64:65]
	v_lshlrev_b64 v[70:71], 11, v[64:65]
	v_lshl_add_u64 v[66:67], s[14:15], 0, v[66:67]
	s_or_b64 exec, exec, s[0:1]
	v_lshl_add_u64 v[68:69], v[66:67], 0, v[144:145]
	v_lshl_add_u64 v[66:67], v[70:71], 2, s[14:15]
	v_lshl_add_u64 v[66:67], v[66:67], 0, v[144:145]
	v_mov_b32_e32 v141, v145
	s_waitcnt lgkmcnt(0)
	v_mul_f32_e32 v70, v61, v61
	s_bitcmp1_b32 s51, 2
	s_cbranch_scc0 .Lqs_smp_40
	global_store_dwordx4 v[66:67], v[60:63], off
.Lqs_smp_40:
	v_fmac_f32_e32 v70, v60, v60
	v_mul_f32_e32 v71, v63, v63
	v_mul_f32_e32 v60, v48, v60
	v_mul_f32_e32 v61, v49, v61
	v_fmac_f32_e32 v71, v62, v62
	v_cvt_pk_bf16_f32 v60, v60, v61
	v_mul_f32_e32 v61, v50, v62
	v_mul_f32_e32 v62, v51, v63
	v_cvt_pk_bf16_f32 v61, v61, v62
	v_lshlrev_b64 v[62:63], 12, v[64:65]
	v_lshl_add_u64 v[62:63], s[12:13], 0, v[62:63]
	v_add_f32_e32 v72, v70, v71
	v_lshl_add_u64 v[70:71], v[62:63], 0, v[140:141]
	s_bitcmp1_b32 s51, 2
	s_cbranch_scc0 .Lqs_smp_41
	global_store_dwordx2 v[70:71], v[60:61], off
.Lqs_smp_41:
	s_waitcnt lgkmcnt(0)
	v_mul_f32_e32 v60, v57, v57
	s_bitcmp1_b32 s51, 2
	s_cbranch_scc0 .Lqs_smp_42
	global_store_dwordx4 v[66:67], v[56:59], off offset:64
.Lqs_smp_42:
	v_fmac_f32_e32 v60, v56, v56
	v_mul_f32_e32 v61, v59, v59
	v_mul_f32_e32 v56, v40, v56
	v_mul_f32_e32 v57, v41, v57
	v_cvt_pk_bf16_f32 v56, v56, v57
	v_mul_f32_e32 v57, v42, v58
	v_fmac_f32_e32 v61, v58, v58
	v_mul_f32_e32 v58, v43, v59
	v_cvt_pk_bf16_f32 v57, v57, v58
	s_bitcmp1_b32 s51, 2
	s_cbranch_scc0 .Lqs_smp_43
	global_store_dwordx2 v[70:71], v[56:57], off offset:32
.Lqs_smp_43:
	v_add_f32_e32 v60, v60, v61
	v_add_f32_e32 v60, v72, v60
	s_waitcnt lgkmcnt(0)
	v_mul_f32_e32 v56, v53, v53
	s_bitcmp1_b32 s51, 3
	s_cbranch_scc0 .Lqs_smp_44
	global_store_dwordx4 v[66:67], v[52:55], off offset:512
.Lqs_smp_44:
	v_fmac_f32_e32 v56, v52, v52
	v_mul_f32_e32 v57, v55, v55
	v_mul_f32_e32 v52, v36, v52
	v_mul_f32_e32 v53, v37, v53
	v_cvt_pk_bf16_f32 v52, v52, v53
	v_mul_f32_e32 v53, v38, v54
	v_fmac_f32_e32 v57, v54, v54
	v_mul_f32_e32 v54, v39, v55
	v_cvt_pk_bf16_f32 v53, v53, v54
	s_bitcmp1_b32 s51, 3
	s_cbranch_scc0 .Lqs_smp_45
	global_store_dwordx2 v[70:71], v[52:53], off offset:256
.Lqs_smp_45:
	v_add_f32_e32 v56, v56, v57
	v_add_f32_e32 v56, v60, v56
	s_waitcnt lgkmcnt(0)
	s_bitcmp1_b32 s51, 3
	s_cbranch_scc0 .Lqs_smp_46
	global_store_dwordx4 v[66:67], v[44:47], off offset:576
.Lqs_smp_46:
	v_mul_f32_e32 v53, v29, v45
	v_mul_f32_e32 v52, v28, v44
	v_mul_f32_e32 v45, v45, v45
	v_fmac_f32_e32 v45, v44, v44
	v_mul_f32_e32 v44, v47, v47
	v_fmac_f32_e32 v44, v46, v46
	v_add_f32_e32 v44, v45, v44
	v_add_f32_e32 v44, v56, v44
	ds_bpermute_b32 v45, v136, v44
	v_cvt_pk_bf16_f32 v52, v52, v53
	v_mul_f32_e32 v53, v30, v46
	v_mul_f32_e32 v54, v31, v47
	v_cvt_pk_bf16_f32 v53, v53, v54
	s_waitcnt lgkmcnt(0)
	v_add_f32_e32 v44, v44, v45
	ds_bpermute_b32 v45, v137, v44
	s_bitcmp1_b32 s51, 3
	s_cbranch_scc0 .Lqs_smp_47
	global_store_dwordx2 v[70:71], v[52:53], off offset:288
.Lqs_smp_47:
	s_and_saveexec_b64 s[0:1], vcc
	s_cbranch_execz .LBB0_1192
	v_lshl_add_u64 v[46:47], v[64:65], 2, s[8:9]
	s_waitcnt lgkmcnt(0)
	v_add_f32_e32 v44, v44, v45
	global_atomic_add_f32 v[46:47], v44, off
.LBB0_1192:
	s_or_b64 exec, exec, s[0:1]
	s_movk_i32 s0, 0x1f5f
	s_waitcnt lgkmcnt(0)
	v_add_u32_e32 v44, 0xa0, v160
	v_cmp_lt_i32_e64 s[0:1], s0, v160
	s_and_saveexec_b64 s[2:3], s[0:1]
	s_xor_b64 s[0:1], exec, s[2:3]
	v_add_u32_e32 v46, 0xffffe0a0, v160
	v_mov_b32_e32 v47, v145
	v_lshlrev_b64 v[46:47], 13, v[46:47]
	v_mov_b32_e32 v45, v145
	v_lshl_add_u64 v[46:47], s[16:17], 0, v[46:47]
	v_lshlrev_b64 v[54:55], 11, v[44:45]
	s_andn2_saveexec_b64 s[0:1], s[0:1]
	v_ashrrev_i32_e32 v45, 31, v44
	v_lshlrev_b64 v[46:47], 13, v[44:45]
	v_lshlrev_b64 v[54:55], 11, v[44:45]
	v_lshl_add_u64 v[46:47], s[14:15], 0, v[46:47]
	s_or_b64 exec, exec, s[0:1]
	v_lshl_add_u64 v[52:53], v[46:47], 0, v[144:145]
	v_lshl_add_u64 v[46:47], v[54:55], 2, s[14:15]
	v_lshl_add_u64 v[46:47], v[46:47], 0, v[144:145]
	v_mov_b32_e32 v141, v145
	s_waitcnt lgkmcnt(0)
	v_mul_f32_e32 v54, v33, v33
	s_bitcmp1_b32 s51, 2
	s_cbranch_scc0 .Lqs_smp_48
	global_store_dwordx4 v[46:47], v[32:35], off
.Lqs_smp_48:
	v_fmac_f32_e32 v54, v32, v32
	v_mul_f32_e32 v55, v35, v35
	v_mul_f32_e32 v32, v48, v32
	v_mul_f32_e32 v33, v49, v33
	v_fmac_f32_e32 v55, v34, v34
	v_cvt_pk_bf16_f32 v32, v32, v33
	v_mul_f32_e32 v33, v50, v34
	v_mul_f32_e32 v34, v51, v35
	v_cvt_pk_bf16_f32 v33, v33, v34
	v_lshlrev_b64 v[34:35], 12, v[44:45]
	v_lshl_add_u64 v[34:35], s[12:13], 0, v[34:35]
	v_add_f32_e32 v56, v54, v55
	v_lshl_add_u64 v[54:55], v[34:35], 0, v[140:141]
	s_bitcmp1_b32 s51, 2
	s_cbranch_scc0 .Lqs_smp_49
	global_store_dwordx2 v[54:55], v[32:33], off
.Lqs_smp_49:
	s_waitcnt lgkmcnt(0)
	v_mul_f32_e32 v32, v25, v25
	s_bitcmp1_b32 s51, 2
	s_cbranch_scc0 .Lqs_smp_50
	global_store_dwordx4 v[46:47], v[24:27], off offset:64
.Lqs_smp_50:
	v_fmac_f32_e32 v32, v24, v24
	v_mul_f32_e32 v33, v27, v27
	v_mul_f32_e32 v24, v40, v24
	v_mul_f32_e32 v25, v41, v25
	v_cvt_pk_bf16_f32 v24, v24, v25
	v_mul_f32_e32 v25, v42, v26
	v_fmac_f32_e32 v33, v26, v26
	v_mul_f32_e32 v26, v43, v27
	v_cvt_pk_bf16_f32 v25, v25, v26
	s_bitcmp1_b32 s51, 2
	s_cbranch_scc0 .Lqs_smp_51
	global_store_dwordx2 v[54:55], v[24:25], off offset:32
.Lqs_smp_51:
	v_add_f32_e32 v32, v32, v33
	v_add_f32_e32 v32, v56, v32
	s_waitcnt lgkmcnt(0)
	v_mul_f32_e32 v24, v21, v21
	s_bitcmp1_b32 s51, 3
	s_cbranch_scc0 .Lqs_smp_52
	global_store_dwordx4 v[46:47], v[20:23], off offset:512
.Lqs_smp_52:
	v_fmac_f32_e32 v24, v20, v20
	v_mul_f32_e32 v25, v23, v23
	v_mul_f32_e32 v20, v36, v20
	v_mul_f32_e32 v21, v37, v21
	v_cvt_pk_bf16_f32 v20, v20, v21
	v_mul_f32_e32 v21, v38, v22
	v_fmac_f32_e32 v25, v22, v22
	v_mul_f32_e32 v22, v39, v23
	v_cvt_pk_bf16_f32 v21, v21, v22
	s_bitcmp1_b32 s51, 3
	s_cbranch_scc0 .Lqs_smp_53
	global_store_dwordx2 v[54:55], v[20:21], off offset:256
.Lqs_smp_53:
	v_add_f32_e32 v24, v24, v25
	v_add_f32_e32 v24, v32, v24
	s_waitcnt lgkmcnt(0)
	s_bitcmp1_b32 s51, 3
	s_cbranch_scc0 .Lqs_smp_54
	global_store_dwordx4 v[46:47], v[16:19], off offset:576
.Lqs_smp_54:
	v_mul_f32_e32 v21, v29, v17
	v_mul_f32_e32 v20, v28, v16
	v_mul_f32_e32 v17, v17, v17
	v_fmac_f32_e32 v17, v16, v16
	v_mul_f32_e32 v16, v19, v19
	v_fmac_f32_e32 v16, v18, v18
	v_add_f32_e32 v16, v17, v16
	v_add_f32_e32 v16, v24, v16
	ds_bpermute_b32 v17, v136, v16
	v_cvt_pk_bf16_f32 v20, v20, v21
	v_mul_f32_e32 v21, v30, v18
	v_mul_f32_e32 v22, v31, v19
	v_cvt_pk_bf16_f32 v21, v21, v22
	s_waitcnt lgkmcnt(0)
	v_add_f32_e32 v16, v16, v17
	ds_bpermute_b32 v17, v137, v16
	s_bitcmp1_b32 s51, 3
	s_cbranch_scc0 .Lqs_smp_55
	global_store_dwordx2 v[54:55], v[20:21], off offset:288
.Lqs_smp_55:
	s_and_saveexec_b64 s[0:1], vcc
	s_cbranch_execz .LBB0_1198
	v_lshl_add_u64 v[18:19], v[44:45], 2, s[8:9]
	s_waitcnt lgkmcnt(0)
	v_add_f32_e32 v16, v16, v17
	global_atomic_add_f32 v[18:19], v16, off
.LBB0_1198:
	s_or_b64 exec, exec, s[0:1]
	s_movk_i32 s0, 0x1f4f
	s_waitcnt lgkmcnt(0)
	v_add_u32_e32 v16, 0xb0, v160
	v_cmp_lt_i32_e64 s[0:1], s0, v160
	s_and_saveexec_b64 s[2:3], s[0:1]
	s_xor_b64 s[0:1], exec, s[2:3]
	v_add_u32_e32 v18, 0xffffe0b0, v160
	v_mov_b32_e32 v19, v145
	v_lshlrev_b64 v[18:19], 13, v[18:19]
	v_mov_b32_e32 v17, v145
	v_lshl_add_u64 v[18:19], s[16:17], 0, v[18:19]
	v_lshlrev_b64 v[22:23], 11, v[16:17]
	s_andn2_saveexec_b64 s[0:1], s[0:1]
	v_ashrrev_i32_e32 v17, 31, v16
	v_lshlrev_b64 v[18:19], 13, v[16:17]
	v_lshlrev_b64 v[22:23], 11, v[16:17]
	v_lshl_add_u64 v[18:19], s[14:15], 0, v[18:19]
	s_or_b64 exec, exec, s[0:1]
	v_lshl_add_u64 v[20:21], v[18:19], 0, v[144:145]
	v_lshl_add_u64 v[18:19], v[22:23], 2, s[14:15]
	v_lshl_add_u64 v[18:19], v[18:19], 0, v[144:145]
	v_mov_b32_e32 v141, v145
	s_waitcnt lgkmcnt(0)
	v_mul_f32_e32 v22, v13, v13
	s_bitcmp1_b32 s51, 2
	s_cbranch_scc0 .Lqs_smp_56
	global_store_dwordx4 v[18:19], v[12:15], off
.Lqs_smp_56:
	v_fmac_f32_e32 v22, v12, v12
	v_mul_f32_e32 v23, v15, v15
	v_mul_f32_e32 v12, v48, v12
	v_mul_f32_e32 v13, v49, v13
	v_fmac_f32_e32 v23, v14, v14
	v_cvt_pk_bf16_f32 v12, v12, v13
	v_mul_f32_e32 v13, v50, v14
	v_mul_f32_e32 v14, v51, v15
	v_cvt_pk_bf16_f32 v13, v13, v14
	v_lshlrev_b64 v[14:15], 12, v[16:17]
	v_lshl_add_u64 v[14:15], s[12:13], 0, v[14:15]
	v_add_f32_e32 v24, v22, v23
	v_lshl_add_u64 v[22:23], v[14:15], 0, v[140:141]
	s_bitcmp1_b32 s51, 2
	s_cbranch_scc0 .Lqs_smp_57
	global_store_dwordx2 v[22:23], v[12:13], off
.Lqs_smp_57:
	s_waitcnt lgkmcnt(0)
	v_mul_f32_e32 v12, v9, v9
	s_bitcmp1_b32 s51, 2
	s_cbranch_scc0 .Lqs_smp_58
	global_store_dwordx4 v[18:19], v[8:11], off offset:64
.Lqs_smp_58:
	v_fmac_f32_e32 v12, v8, v8
	v_mul_f32_e32 v13, v11, v11
	v_mul_f32_e32 v8, v40, v8
	v_mul_f32_e32 v9, v41, v9
	v_cvt_pk_bf16_f32 v8, v8, v9
	v_mul_f32_e32 v9, v42, v10
	v_fmac_f32_e32 v13, v10, v10
	v_mul_f32_e32 v10, v43, v11
	v_cvt_pk_bf16_f32 v9, v9, v10
	s_bitcmp1_b32 s51, 2
	s_cbranch_scc0 .Lqs_smp_59
	global_store_dwordx2 v[22:23], v[8:9], off offset:32
.Lqs_smp_59:
	v_add_f32_e32 v12, v12, v13
	v_add_f32_e32 v12, v24, v12
	s_waitcnt lgkmcnt(0)
	v_mul_f32_e32 v8, v5, v5
	s_bitcmp1_b32 s51, 3
	s_cbranch_scc0 .Lqs_smp_60
	global_store_dwordx4 v[18:19], v[4:7], off offset:512
.Lqs_smp_60:
	v_fmac_f32_e32 v8, v4, v4
	v_mul_f32_e32 v9, v7, v7
	v_mul_f32_e32 v4, v36, v4
	v_mul_f32_e32 v5, v37, v5
	v_cvt_pk_bf16_f32 v4, v4, v5
	v_mul_f32_e32 v5, v38, v6
	v_fmac_f32_e32 v9, v6, v6
	v_mul_f32_e32 v6, v39, v7
	v_cvt_pk_bf16_f32 v5, v5, v6
	s_bitcmp1_b32 s51, 3
	s_cbranch_scc0 .Lqs_smp_61
	global_store_dwordx2 v[22:23], v[4:5], off offset:256
.Lqs_smp_61:
	v_add_f32_e32 v8, v8, v9
	v_add_f32_e32 v8, v12, v8
	s_waitcnt lgkmcnt(0)
	s_bitcmp1_b32 s51, 3
	s_cbranch_scc0 .Lqs_smp_62
	global_store_dwordx4 v[18:19], v[0:3], off offset:576
.Lqs_smp_62:
	v_mul_f32_e32 v5, v29, v1
	v_mul_f32_e32 v4, v28, v0
	v_mul_f32_e32 v1, v1, v1
	v_fmac_f32_e32 v1, v0, v0
	v_mul_f32_e32 v0, v3, v3
	v_fmac_f32_e32 v0, v2, v2
	v_add_f32_e32 v0, v1, v0
	v_add_f32_e32 v0, v8, v0
	ds_bpermute_b32 v1, v136, v0
	v_cvt_pk_bf16_f32 v4, v4, v5
	v_mul_f32_e32 v5, v30, v2
	v_mul_f32_e32 v6, v31, v3
	v_cvt_pk_bf16_f32 v5, v5, v6
	s_waitcnt lgkmcnt(0)
	v_add_f32_e32 v0, v0, v1
	ds_bpermute_b32 v1, v137, v0
	s_bitcmp1_b32 s51, 3
	s_cbranch_scc0 .Lqs_smp_63
	flat_store_dwordx2 v[22:23], v[4:5] offset:288
.Lqs_smp_63:
	s_and_saveexec_b64 s[0:1], vcc
	s_cbranch_execz .LBB0_1204
	v_lshl_add_u64 v[2:3], v[16:17], 2, s[8:9]
	s_waitcnt lgkmcnt(0)
	v_add_f32_e32 v0, v0, v1
	flat_atomic_add_f32 v[2:3], v0
